# v051 + SGU output stores widened: v_permlane16_swap pairs, 16 dwordx4 stores per wave instead of 32 dwordx2
# speedup vs baseline: 1.0058x; 1.0058x over previous
; __device__ __forceinline__ unsigned cvt_pk_bf16(float lo, float hi) { unsigned r; asm volatile("v_cvt_pk_bf16_f32 %0, %1, %2" : "=v"(r) : "v"(lo), "v"(hi)); return r; }
; __device__ __forceinline__ float bf_lo(unsigned w) { return __uint_as_float(w << 16); }
; __device__ __forceinline__ float bf_hi(unsigned w) { return __uint_as_float(w & 0xffff0000u); }
; #define LAS __attribute__((address_space(3)))
; __device__ __forceinline__ void sgu_unit(LAS unsigned char* lds, bf16* U, const bf16* VS, const float* SGS, const float* lnw, const float* lnb, const v4u* WF, const float* bsl, int unit, int tid) {
;     ...
;         const int c8 = lane & 7, rp = lane >> 3, col = colbase + 8 * c8;
;         v4u sl[8][2];
; #pragma unroll
;         for (int i = 0; i < 8; ++i) { const int s0 = 2 * (rp + 8 * i); sl[i][0] = *(const v4u*)(VS + (size_t)(r0 + s0) * 1024 + col); sl[i][1] = *(const v4u*)(VS + (size_t)(r0 + s0 + 1) * 1024 + col); }
;         const f32x4 lw0 = *(const f32x4*)(lnw + col), lw1 = *(const f32x4*)(lnw + col + 4), lb0 = *(const f32x4*)(lnb + col), lb1 = *(const f32x4*)(lnb + col + 4);
;         const float lw[8] = {lw0.x, lw0.y, lw0.z, lw0.w, lw1.x, lw1.y, lw1.z, lw1.w}, lb[8] = {lb0.x, lb0.y, lb0.z, lb0.w, lb1.x, lb1.y, lb1.z, lb1.w};
;         __syncthreads();
;         LAS unsigned char* wbase = vt + c8 * SGU_VP + rp * 4;
; #pragma unroll
;         for (int i = 0; i < 8; ++i) {
;             const f32x4 st4 = *(const LAS f32x4*)(stat + 4 * (rp + 8 * i));
;             const v4u w0 = sl[i][0], w1 = sl[i][1];
;             const unsigned A0[4] = {w0.x, w0.y, w0.z, w0.w}, A1[4] = {w1.x, w1.y, w1.z, w1.w};
; #pragma unroll
;             for (int e = 0; e < 8; ++e) { typedef float f32x2p __attribute__((ext_vector_type(2)));
;                 f32x2p v; v.x = (e & 1) ? bf_hi(A0[e >> 1]) : bf_lo(A0[e >> 1]); v.y = (e & 1) ? bf_hi(A1[e >> 1]) : bf_lo(A1[e >> 1]);
;                 const f32x2p mn = {st4.x, st4.z}, rs = {st4.y, st4.w};
;                 const f32x2p o = ((v - mn) * rs) * lw[e] + lb[e];
;                 *(LAS unsigned*)(wbase + e * 8 * SGU_VP + i * 32) = cvt_pk_bf16(o.x, o.y); }
;         }
.LBB0_498:
	s_or_b64 exec, exec, s[14:15]
	v_mov_b32_e32 v122, v222
	v_mov_b32_e32 v123, v223
	v_mov_b32_e32 v124, v224
	v_mov_b32_e32 v125, v225
	v_mov_b32_e32 v126, v226
	v_mov_b32_e32 v127, v227
	v_mov_b32_e32 v128, v228
	v_mov_b32_e32 v129, v229
	v_mov_b32_e32 v114, v230
	v_mov_b32_e32 v115, v231
	v_mov_b32_e32 v116, v232
	v_mov_b32_e32 v117, v233
	v_mov_b32_e32 v118, v234
	v_mov_b32_e32 v119, v235
	v_mov_b32_e32 v120, v236
	v_mov_b32_e32 v121, v237
	v_mov_b32_e32 v106, v238
	v_mov_b32_e32 v107, v239
	v_mov_b32_e32 v108, v240
	v_mov_b32_e32 v109, v241
	v_mov_b32_e32 v110, v242
	v_mov_b32_e32 v111, v243
	v_mov_b32_e32 v112, v244
	v_mov_b32_e32 v113, v245
	v_or_b32_e32 v158, v82, v168
	v_or_b32_e32 v82, v158, v170
	v_lshl_or_b32 v84, s16, 11, v181
	v_mov_b32_e32 v85, v147
	v_ashrrev_i32_e32 v83, 31, v82
	v_lshl_add_u64 v[84:85], s[48:49], 0, v[84:85]
	v_lshl_add_u64 v[90:91], v[82:83], 1, v[84:85]
	v_lshlrev_b64 v[82:83], 2, v[82:83]
	s_waitcnt lgkmcnt(0)
	v_lshl_add_u64 v[84:85], s[30:31], 0, v[82:83]
	v_lshl_add_u64 v[86:87], s[50:51], 0, v[82:83]
	global_load_dwordx4 v[98:101], v[86:87], off
	global_load_dwordx4 v[102:105], v[84:85], off
	s_nop 0
	global_load_dwordx4 v[82:85], v[84:85], off offset:16
	s_nop 0
	global_load_dwordx4 v[86:89], v[86:87], off offset:16
	v_add_co_u32_e32 v92, vcc, 0x8000, v90
	s_mov_b64 s[14:15], 0
	s_nop 0
	v_addc_co_u32_e32 v93, vcc, 0, v91, vcc
	v_add_co_u32_e32 v94, vcc, 0x10000, v90
	s_waitcnt vmcnt(7)
	v_and_b32_e32 v228, 0xffff0000, v206
	v_addc_co_u32_e32 v95, vcc, 0, v91, vcc
	v_add_co_u32_e32 v92, vcc, 0x18000, v90
	s_waitcnt vmcnt(8)
	v_and_b32_e32 v229, 0xffff0000, v210
	v_addc_co_u32_e32 v93, vcc, 0, v91, vcc
	v_add_co_u32_e32 v94, vcc, 0x20000, v90
	v_addc_co_u32_e32 v95, vcc, 0, v91, vcc
	v_add_co_u32_e32 v92, vcc, 0x28000, v90
	v_addc_co_u32_e32 v93, vcc, 0, v91, vcc
	v_add_co_u32_e32 v94, vcc, 0x30000, v90
	v_addc_co_u32_e32 v95, vcc, 0, v91, vcc
	v_add_co_u32_e32 v96, vcc, 0x38000, v90
	v_addc_co_u32_e32 v97, vcc, 0, v91, vcc
	v_mov_b32_e32 v90, v248
	v_mov_b32_e32 v91, v249
	v_mov_b32_e32 v92, v250
	v_mov_b32_e32 v93, v251
	s_nop 0
	v_mov_b32_e32 v94, v252
	v_mov_b32_e32 v95, v253
	v_mov_b32_e32 v96, v254
	v_mov_b32_e32 v97, v255
	s_barrier
	ds_read_b128 v[222:225], v182
	v_lshlrev_b32_e32 v230, 16, v207
	v_lshlrev_b32_e32 v231, 16, v211
	s_waitcnt vmcnt(2)
	v_mov_b32_e32 v160, v105
	v_mov_b32_e32 v162, v101
	s_waitcnt lgkmcnt(0)
	v_mov_b32_e32 v226, v222
	v_mov_b32_e32 v227, v224
	v_mov_b32_e32 v224, v223
	v_lshlrev_b32_e32 v222, 16, v206
	v_lshlrev_b32_e32 v223, 16, v210
	v_pk_add_f32 v[222:223], v[222:223], v[226:227] neg_lo:[0,1] neg_hi:[0,1]
	v_and_b32_e32 v206, 0xffff0000, v207
	v_and_b32_e32 v207, 0xffff0000, v211
	v_pk_add_f32 v[228:229], v[228:229], v[226:227] neg_lo:[0,1] neg_hi:[0,1]
	v_pk_mul_f32 v[222:223], v[224:225], v[222:223]
	v_pk_add_f32 v[206:207], v[206:207], v[226:227] neg_lo:[0,1] neg_hi:[0,1]
	v_pk_add_f32 v[230:231], v[230:231], v[226:227] neg_lo:[0,1] neg_hi:[0,1]
	v_pk_mul_f32 v[228:229], v[224:225], v[228:229]
	v_pk_fma_f32 v[222:223], v[102:103], v[222:223], v[98:99] op_sel_hi:[0,1,0]
	v_cvt_pk_bf16_f32 v159, v222, v223
	v_pk_mul_f32 v[206:207], v[224:225], v[206:207]
	v_pk_mul_f32 v[230:231], v[224:225], v[230:231]
	v_pk_fma_f32 v[228:229], v[102:103], v[228:229], v[98:99] op_sel:[1,0,1]
	ds_write_b32 v178, v159 offset:1024
	v_cvt_pk_bf16_f32 v159, v228, v229
	v_pk_fma_f32 v[206:207], v[160:161], v[206:207], v[162:163] op_sel_hi:[0,1,0]
	v_pk_fma_f32 v[230:231], v[104:105], v[230:231], v[100:101] op_sel_hi:[0,1,0]
	ds_write_b32 v178, v159 offset:3200
	v_cvt_pk_bf16_f32 v159, v230, v231
	ds_write_b32 v178, v159 offset:5376
	v_cvt_pk_bf16_f32 v101, v206, v207
	v_lshlrev_b32_e32 v206, 16, v208
	v_lshlrev_b32_e32 v207, 16, v212
	v_pk_add_f32 v[206:207], v[206:207], v[226:227] neg_lo:[0,1] neg_hi:[0,1]
	ds_write_b32 v178, v101 offset:7552
	v_pk_mul_f32 v[206:207], v[224:225], v[206:207]
	s_waitcnt vmcnt(1)
	v_mov_b32_e32 v164, v85
	s_waitcnt vmcnt(0)
	v_pk_fma_f32 v[206:207], v[82:83], v[206:207], v[86:87] op_sel_hi:[0,1,0]
	v_cvt_pk_bf16_f32 v101, v206, v207
	v_and_b32_e32 v206, 0xffff0000, v208
	v_and_b32_e32 v207, 0xffff0000, v212
	v_pk_add_f32 v[206:207], v[206:207], v[226:227] neg_lo:[0,1] neg_hi:[0,1]
	ds_write_b32 v178, v101 offset:9728
	v_pk_mul_f32 v[206:207], v[224:225], v[206:207]
	v_mov_b32_e32 v166, v89
	v_pk_fma_f32 v[206:207], v[82:83], v[206:207], v[86:87] op_sel:[1,0,1]
	v_ashrrev_i32_e32 v159, 31, v158
	v_cvt_pk_bf16_f32 v101, v206, v207
	v_lshlrev_b32_e32 v206, 16, v209
	v_lshlrev_b32_e32 v207, 16, v213
	v_pk_add_f32 v[206:207], v[206:207], v[226:227] neg_lo:[0,1] neg_hi:[0,1]
	ds_write_b32 v178, v101 offset:11904
	v_pk_mul_f32 v[206:207], v[224:225], v[206:207]
	s_nop 0
	v_pk_fma_f32 v[206:207], v[84:85], v[206:207], v[88:89] op_sel_hi:[0,1,0]
	v_cvt_pk_bf16_f32 v101, v206, v207
	v_and_b32_e32 v206, 0xffff0000, v209
	v_and_b32_e32 v207, 0xffff0000, v213
	v_pk_add_f32 v[206:207], v[206:207], v[226:227] neg_lo:[0,1] neg_hi:[0,1]
	ds_write_b32 v178, v101 offset:14080
	v_pk_mul_f32 v[206:207], v[224:225], v[206:207]
	s_nop 0
	v_pk_fma_f32 v[206:207], v[164:165], v[206:207], v[166:167] op_sel_hi:[0,1,0]
	v_cvt_pk_bf16_f32 v85, v206, v207
	ds_write_b32 v178, v85 offset:16256
	ds_read_b128 v[206:209], v182 offset:128
	s_waitcnt lgkmcnt(0)
	v_mov_b32_e32 v210, v206
	v_mov_b32_e32 v211, v208
	v_mov_b32_e32 v208, v207
	s_waitcnt vmcnt(13)
	v_lshlrev_b32_e32 v206, 16, v214
	s_waitcnt vmcnt(12)
; __device__ __forceinline__ unsigned cvt_pk_bf16(float lo, float hi) { unsigned r; asm volatile("v_cvt_pk_bf16_f32 %0, %1, %2" : "=v"(r) : "v"(lo), "v"(hi)); return r; }
; __device__ __forceinline__ float bf_lo(unsigned w) { return __uint_as_float(w << 16); }
; __device__ __forceinline__ float bf_hi(unsigned w) { return __uint_as_float(w & 0xffff0000u); }
; #define LAS __attribute__((address_space(3)))
; __device__ __forceinline__ void sgu_unit(LAS unsigned char* lds, bf16* U, const bf16* VS, const float* SGS, const float* lnw, const float* lnb, const v4u* WF, const float* bsl, int unit, int tid) {
;     ...
;         for (int i = 0; i < 8; ++i) {
;             const f32x4 st4 = *(const LAS f32x4*)(stat + 4 * (rp + 8 * i));
;             const v4u w0 = sl[i][0], w1 = sl[i][1];
;             const unsigned A0[4] = {w0.x, w0.y, w0.z, w0.w}, A1[4] = {w1.x, w1.y, w1.z, w1.w};
; #pragma unroll
;             for (int e = 0; e < 8; ++e) { typedef float f32x2p __attribute__((ext_vector_type(2)));
;                 f32x2p v; v.x = (e & 1) ? bf_hi(A0[e >> 1]) : bf_lo(A0[e >> 1]); v.y = (e & 1) ? bf_hi(A1[e >> 1]) : bf_lo(A1[e >> 1]);
;                 const f32x2p mn = {st4.x, st4.z}, rs = {st4.y, st4.w};
;                 const f32x2p o = ((v - mn) * rs) * lw[e] + lb[e];
;                 *(LAS unsigned*)(wbase + e * 8 * SGU_VP + i * 32) = cvt_pk_bf16(o.x, o.y); }
;         }
	v_lshlrev_b32_e32 v207, 16, v218
	v_pk_add_f32 v[206:207], v[206:207], v[210:211] neg_lo:[0,1] neg_hi:[0,1]
	s_nop 0
	v_pk_mul_f32 v[206:207], v[208:209], v[206:207]
	s_nop 0
	v_pk_fma_f32 v[206:207], v[102:103], v[206:207], v[98:99] op_sel_hi:[0,1,0]
	v_cvt_pk_bf16_f32 v85, v206, v207
	v_and_b32_e32 v206, 0xffff0000, v214
	v_and_b32_e32 v207, 0xffff0000, v218
	v_pk_add_f32 v[206:207], v[206:207], v[210:211] neg_lo:[0,1] neg_hi:[0,1]
	ds_write_b32 v178, v85 offset:1056
	v_pk_mul_f32 v[206:207], v[208:209], v[206:207]
	s_nop 0
	v_pk_fma_f32 v[206:207], v[102:103], v[206:207], v[98:99] op_sel:[1,0,1]
	s_nop 0
	v_cvt_pk_bf16_f32 v85, v206, v207
	v_lshlrev_b32_e32 v206, 16, v215
	v_lshlrev_b32_e32 v207, 16, v219
	v_pk_add_f32 v[206:207], v[206:207], v[210:211] neg_lo:[0,1] neg_hi:[0,1]
	ds_write_b32 v178, v85 offset:3232
	v_pk_mul_f32 v[206:207], v[208:209], v[206:207]
	s_nop 0
	v_pk_fma_f32 v[206:207], v[104:105], v[206:207], v[100:101] op_sel_hi:[0,1,0]
	v_cvt_pk_bf16_f32 v85, v206, v207
	v_and_b32_e32 v206, 0xffff0000, v215
	v_and_b32_e32 v207, 0xffff0000, v219
	v_pk_add_f32 v[206:207], v[206:207], v[210:211] neg_lo:[0,1] neg_hi:[0,1]
	ds_write_b32 v178, v85 offset:5408
	v_pk_mul_f32 v[206:207], v[208:209], v[206:207]
	s_nop 0
	v_pk_fma_f32 v[206:207], v[160:161], v[206:207], v[162:163] op_sel_hi:[0,1,0]
	v_cvt_pk_bf16_f32 v85, v206, v207
	v_lshlrev_b32_e32 v206, 16, v216
	v_lshlrev_b32_e32 v207, 16, v220
	v_pk_add_f32 v[206:207], v[206:207], v[210:211] neg_lo:[0,1] neg_hi:[0,1]
	ds_write_b32 v178, v85 offset:7584
	v_pk_mul_f32 v[206:207], v[208:209], v[206:207]
	s_nop 0
	v_pk_fma_f32 v[206:207], v[82:83], v[206:207], v[86:87] op_sel_hi:[0,1,0]
	v_cvt_pk_bf16_f32 v85, v206, v207
	v_and_b32_e32 v206, 0xffff0000, v216
	v_and_b32_e32 v207, 0xffff0000, v220
	v_pk_add_f32 v[206:207], v[206:207], v[210:211] neg_lo:[0,1] neg_hi:[0,1]
	ds_write_b32 v178, v85 offset:9760
	v_pk_mul_f32 v[206:207], v[208:209], v[206:207]
	s_nop 0
	v_pk_fma_f32 v[206:207], v[82:83], v[206:207], v[86:87] op_sel:[1,0,1]
	s_nop 0
	v_cvt_pk_bf16_f32 v85, v206, v207
	v_lshlrev_b32_e32 v206, 16, v217
	v_lshlrev_b32_e32 v207, 16, v221
	v_pk_add_f32 v[206:207], v[206:207], v[210:211] neg_lo:[0,1] neg_hi:[0,1]
	ds_write_b32 v178, v85 offset:11936
	v_pk_mul_f32 v[206:207], v[208:209], v[206:207]
	s_nop 0
	v_pk_fma_f32 v[206:207], v[84:85], v[206:207], v[88:89] op_sel_hi:[0,1,0]
	v_cvt_pk_bf16_f32 v85, v206, v207
	v_and_b32_e32 v206, 0xffff0000, v217
	v_and_b32_e32 v207, 0xffff0000, v221
	v_pk_add_f32 v[206:207], v[206:207], v[210:211] neg_lo:[0,1] neg_hi:[0,1]
	ds_write_b32 v178, v85 offset:14112
	v_pk_mul_f32 v[206:207], v[208:209], v[206:207]
	s_nop 0
	v_pk_fma_f32 v[206:207], v[164:165], v[206:207], v[166:167] op_sel_hi:[0,1,0]
	v_cvt_pk_bf16_f32 v85, v206, v207
	ds_write_b32 v178, v85 offset:16288
	ds_read_b128 v[206:209], v182 offset:256
	s_waitcnt lgkmcnt(0)
	v_mov_b32_e32 v210, v206
	v_mov_b32_e32 v211, v208
	v_mov_b32_e32 v208, v207
	s_waitcnt vmcnt(11)
	v_lshlrev_b32_e32 v206, 16, v138
	s_waitcnt vmcnt(10)
	v_lshlrev_b32_e32 v207, 16, v142
	v_pk_add_f32 v[206:207], v[206:207], v[210:211] neg_lo:[0,1] neg_hi:[0,1]
	s_nop 0
	v_pk_mul_f32 v[206:207], v[208:209], v[206:207]
	s_nop 0
	v_pk_fma_f32 v[206:207], v[102:103], v[206:207], v[98:99] op_sel_hi:[0,1,0]
	v_cvt_pk_bf16_f32 v85, v206, v207
	v_and_b32_e32 v206, 0xffff0000, v138
	v_and_b32_e32 v207, 0xffff0000, v142
	v_pk_add_f32 v[206:207], v[206:207], v[210:211] neg_lo:[0,1] neg_hi:[0,1]
	ds_write_b32 v178, v85 offset:1088
	v_pk_mul_f32 v[206:207], v[208:209], v[206:207]
	v_and_b32_e32 v138, 0xffff0000, v139
	v_pk_fma_f32 v[206:207], v[102:103], v[206:207], v[98:99] op_sel:[1,0,1]
	s_nop 0
	v_cvt_pk_bf16_f32 v85, v206, v207
	v_lshlrev_b32_e32 v206, 16, v139
	v_lshlrev_b32_e32 v207, 16, v143
	v_and_b32_e32 v139, 0xffff0000, v143
	v_pk_add_f32 v[206:207], v[206:207], v[210:211] neg_lo:[0,1] neg_hi:[0,1]
	v_pk_add_f32 v[138:139], v[138:139], v[210:211] neg_lo:[0,1] neg_hi:[0,1]
	v_pk_mul_f32 v[206:207], v[208:209], v[206:207]
	v_pk_mul_f32 v[138:139], v[208:209], v[138:139]
	ds_write_b32 v178, v85 offset:3264
	v_pk_fma_f32 v[206:207], v[104:105], v[206:207], v[100:101] op_sel_hi:[0,1,0]
	v_cvt_pk_bf16_f32 v85, v206, v207
	v_pk_fma_f32 v[138:139], v[160:161], v[138:139], v[162:163] op_sel_hi:[0,1,0]
	ds_write_b32 v178, v85 offset:5440
	v_cvt_pk_bf16_f32 v85, v138, v139
	v_lshlrev_b32_e32 v138, 16, v140
	v_lshlrev_b32_e32 v139, 16, v144
	v_pk_add_f32 v[138:139], v[138:139], v[210:211] neg_lo:[0,1] neg_hi:[0,1]
	ds_write_b32 v178, v85 offset:7616
	v_pk_mul_f32 v[138:139], v[208:209], v[138:139]
	s_nop 0
	v_pk_fma_f32 v[138:139], v[82:83], v[138:139], v[86:87] op_sel_hi:[0,1,0]
	v_cvt_pk_bf16_f32 v85, v138, v139
	v_and_b32_e32 v138, 0xffff0000, v140
	v_and_b32_e32 v139, 0xffff0000, v144
	v_pk_add_f32 v[138:139], v[138:139], v[210:211] neg_lo:[0,1] neg_hi:[0,1]
	ds_write_b32 v178, v85 offset:9792
	v_pk_mul_f32 v[138:139], v[208:209], v[138:139]
	s_nop 0
	v_pk_fma_f32 v[138:139], v[82:83], v[138:139], v[86:87] op_sel:[1,0,1]
	s_nop 0
	v_cvt_pk_bf16_f32 v85, v138, v139
	v_lshlrev_b32_e32 v138, 16, v141
	v_lshlrev_b32_e32 v139, 16, v145
	v_pk_add_f32 v[138:139], v[138:139], v[210:211] neg_lo:[0,1] neg_hi:[0,1]
	ds_write_b32 v178, v85 offset:11968
	v_pk_mul_f32 v[138:139], v[208:209], v[138:139]
	s_nop 0
	v_pk_fma_f32 v[138:139], v[84:85], v[138:139], v[88:89] op_sel_hi:[0,1,0]
	v_cvt_pk_bf16_f32 v85, v138, v139
	v_and_b32_e32 v138, 0xffff0000, v141
	v_and_b32_e32 v139, 0xffff0000, v145
	v_pk_add_f32 v[138:139], v[138:139], v[210:211] neg_lo:[0,1] neg_hi:[0,1]
	ds_write_b32 v178, v85 offset:14144
	v_pk_mul_f32 v[138:139], v[208:209], v[138:139]
	s_nop 0
	v_pk_fma_f32 v[138:139], v[164:165], v[138:139], v[166:167] op_sel_hi:[0,1,0]
	v_cvt_pk_bf16_f32 v85, v138, v139
	ds_write_b32 v178, v85 offset:16320
	ds_read_b128 v[138:141], v182 offset:384
	s_waitcnt lgkmcnt(0)
; __device__ __forceinline__ unsigned cvt_pk_bf16(float lo, float hi) { unsigned r; asm volatile("v_cvt_pk_bf16_f32 %0, %1, %2" : "=v"(r) : "v"(lo), "v"(hi)); return r; }
; __device__ __forceinline__ float bf_lo(unsigned w) { return __uint_as_float(w << 16); }
; __device__ __forceinline__ float bf_hi(unsigned w) { return __uint_as_float(w & 0xffff0000u); }
; #define LAS __attribute__((address_space(3)))
; __device__ __forceinline__ void sgu_unit(LAS unsigned char* lds, bf16* U, const bf16* VS, const float* SGS, const float* lnw, const float* lnb, const v4u* WF, const float* bsl, int unit, int tid) {
;     ...
;         for (int i = 0; i < 8; ++i) {
;             const f32x4 st4 = *(const LAS f32x4*)(stat + 4 * (rp + 8 * i));
;             const v4u w0 = sl[i][0], w1 = sl[i][1];
;             const unsigned A0[4] = {w0.x, w0.y, w0.z, w0.w}, A1[4] = {w1.x, w1.y, w1.z, w1.w};
; #pragma unroll
;             for (int e = 0; e < 8; ++e) { typedef float f32x2p __attribute__((ext_vector_type(2)));
;                 f32x2p v; v.x = (e & 1) ? bf_hi(A0[e >> 1]) : bf_lo(A0[e >> 1]); v.y = (e & 1) ? bf_hi(A1[e >> 1]) : bf_lo(A1[e >> 1]);
;                 const f32x2p mn = {st4.x, st4.z}, rs = {st4.y, st4.w};
;                 const f32x2p o = ((v - mn) * rs) * lw[e] + lb[e];
;                 *(LAS unsigned*)(wbase + e * 8 * SGU_VP + i * 32) = cvt_pk_bf16(o.x, o.y); }
;         }
	v_mov_b32_e32 v142, v138
	v_mov_b32_e32 v143, v140
	v_mov_b32_e32 v140, v139
	s_waitcnt vmcnt(9)
	v_lshlrev_b32_e32 v138, 16, v130
	s_waitcnt vmcnt(8)
	v_lshlrev_b32_e32 v139, 16, v134
	v_pk_add_f32 v[138:139], v[138:139], v[142:143] neg_lo:[0,1] neg_hi:[0,1]
	s_nop 0
	v_pk_mul_f32 v[138:139], v[140:141], v[138:139]
	s_nop 0
	v_pk_fma_f32 v[138:139], v[102:103], v[138:139], v[98:99] op_sel_hi:[0,1,0]
	v_cvt_pk_bf16_f32 v85, v138, v139
	v_and_b32_e32 v138, 0xffff0000, v130
	v_and_b32_e32 v139, 0xffff0000, v134
	v_pk_add_f32 v[138:139], v[138:139], v[142:143] neg_lo:[0,1] neg_hi:[0,1]
	ds_write_b32 v178, v85 offset:1120
	v_pk_mul_f32 v[138:139], v[140:141], v[138:139]
	v_and_b32_e32 v130, 0xffff0000, v131
	v_pk_fma_f32 v[138:139], v[102:103], v[138:139], v[98:99] op_sel:[1,0,1]
	s_nop 0
	v_cvt_pk_bf16_f32 v85, v138, v139
	v_lshlrev_b32_e32 v138, 16, v131
	v_lshlrev_b32_e32 v139, 16, v135
	v_and_b32_e32 v131, 0xffff0000, v135
	v_pk_add_f32 v[138:139], v[138:139], v[142:143] neg_lo:[0,1] neg_hi:[0,1]
	v_pk_add_f32 v[130:131], v[130:131], v[142:143] neg_lo:[0,1] neg_hi:[0,1]
	v_pk_mul_f32 v[138:139], v[140:141], v[138:139]
	v_pk_mul_f32 v[130:131], v[140:141], v[130:131]
	ds_write_b32 v178, v85 offset:3296
	v_pk_fma_f32 v[138:139], v[104:105], v[138:139], v[100:101] op_sel_hi:[0,1,0]
	v_cvt_pk_bf16_f32 v85, v138, v139
	v_pk_fma_f32 v[130:131], v[160:161], v[130:131], v[162:163] op_sel_hi:[0,1,0]
	ds_write_b32 v178, v85 offset:5472
	v_cvt_pk_bf16_f32 v85, v130, v131
	v_lshlrev_b32_e32 v130, 16, v132
	v_lshlrev_b32_e32 v131, 16, v136
	v_pk_add_f32 v[130:131], v[130:131], v[142:143] neg_lo:[0,1] neg_hi:[0,1]
	ds_write_b32 v178, v85 offset:7648
	v_pk_mul_f32 v[130:131], v[140:141], v[130:131]
	s_nop 0
	v_pk_fma_f32 v[130:131], v[82:83], v[130:131], v[86:87] op_sel_hi:[0,1,0]
	v_cvt_pk_bf16_f32 v85, v130, v131
	v_and_b32_e32 v130, 0xffff0000, v132
	v_and_b32_e32 v131, 0xffff0000, v136
	v_pk_add_f32 v[130:131], v[130:131], v[142:143] neg_lo:[0,1] neg_hi:[0,1]
	ds_write_b32 v178, v85 offset:9824
	v_pk_mul_f32 v[130:131], v[140:141], v[130:131]
	s_nop 0
	v_pk_fma_f32 v[130:131], v[82:83], v[130:131], v[86:87] op_sel:[1,0,1]
	s_nop 0
	v_cvt_pk_bf16_f32 v85, v130, v131
	v_lshlrev_b32_e32 v130, 16, v133
	v_lshlrev_b32_e32 v131, 16, v137
	v_pk_add_f32 v[130:131], v[130:131], v[142:143] neg_lo:[0,1] neg_hi:[0,1]
	ds_write_b32 v178, v85 offset:12000
	v_pk_mul_f32 v[130:131], v[140:141], v[130:131]
	s_nop 0
	v_pk_fma_f32 v[130:131], v[84:85], v[130:131], v[88:89] op_sel_hi:[0,1,0]
	v_cvt_pk_bf16_f32 v85, v130, v131
	v_and_b32_e32 v130, 0xffff0000, v133
	v_and_b32_e32 v131, 0xffff0000, v137
	v_pk_add_f32 v[130:131], v[130:131], v[142:143] neg_lo:[0,1] neg_hi:[0,1]
	ds_write_b32 v178, v85 offset:14176
	v_pk_mul_f32 v[130:131], v[140:141], v[130:131]
	s_nop 0
	v_pk_fma_f32 v[130:131], v[164:165], v[130:131], v[166:167] op_sel_hi:[0,1,0]
	v_cvt_pk_bf16_f32 v85, v130, v131
	ds_write_b32 v178, v85 offset:16352
	ds_read_b128 v[130:133], v182 offset:512
	s_waitcnt lgkmcnt(0)
	v_mov_b32_e32 v134, v130
	v_mov_b32_e32 v135, v132
	v_mov_b32_e32 v132, v131
	s_waitcnt vmcnt(7)
	v_lshlrev_b32_e32 v130, 16, v122
	s_waitcnt vmcnt(6)
	v_lshlrev_b32_e32 v131, 16, v126
	v_pk_add_f32 v[130:131], v[130:131], v[134:135] neg_lo:[0,1] neg_hi:[0,1]
	s_nop 0
	v_pk_mul_f32 v[130:131], v[132:133], v[130:131]
	s_nop 0
	v_pk_fma_f32 v[130:131], v[102:103], v[130:131], v[98:99] op_sel_hi:[0,1,0]
	v_cvt_pk_bf16_f32 v85, v130, v131
	v_and_b32_e32 v130, 0xffff0000, v122
	v_and_b32_e32 v131, 0xffff0000, v126
	v_pk_add_f32 v[130:131], v[130:131], v[134:135] neg_lo:[0,1] neg_hi:[0,1]
	ds_write_b32 v178, v85 offset:1152
	v_pk_mul_f32 v[130:131], v[132:133], v[130:131]
	v_and_b32_e32 v122, 0xffff0000, v123
	v_pk_fma_f32 v[130:131], v[102:103], v[130:131], v[98:99] op_sel:[1,0,1]
	s_nop 0
	v_cvt_pk_bf16_f32 v85, v130, v131
	v_lshlrev_b32_e32 v130, 16, v123
	v_lshlrev_b32_e32 v131, 16, v127
	v_and_b32_e32 v123, 0xffff0000, v127
	v_pk_add_f32 v[130:131], v[130:131], v[134:135] neg_lo:[0,1] neg_hi:[0,1]
	v_pk_add_f32 v[122:123], v[122:123], v[134:135] neg_lo:[0,1] neg_hi:[0,1]
	v_pk_mul_f32 v[130:131], v[132:133], v[130:131]
	v_pk_mul_f32 v[122:123], v[132:133], v[122:123]
	ds_write_b32 v178, v85 offset:3328
	v_pk_fma_f32 v[130:131], v[104:105], v[130:131], v[100:101] op_sel_hi:[0,1,0]
	v_cvt_pk_bf16_f32 v85, v130, v131
	v_pk_fma_f32 v[122:123], v[160:161], v[122:123], v[162:163] op_sel_hi:[0,1,0]
	ds_write_b32 v178, v85 offset:5504
	v_cvt_pk_bf16_f32 v85, v122, v123
	v_lshlrev_b32_e32 v122, 16, v124
	v_lshlrev_b32_e32 v123, 16, v128
	v_pk_add_f32 v[122:123], v[122:123], v[134:135] neg_lo:[0,1] neg_hi:[0,1]
	ds_write_b32 v178, v85 offset:7680
	v_pk_mul_f32 v[122:123], v[132:133], v[122:123]
	s_nop 0
	v_pk_fma_f32 v[122:123], v[82:83], v[122:123], v[86:87] op_sel_hi:[0,1,0]
	v_cvt_pk_bf16_f32 v85, v122, v123
	v_and_b32_e32 v122, 0xffff0000, v124
	v_and_b32_e32 v123, 0xffff0000, v128
	v_pk_add_f32 v[122:123], v[122:123], v[134:135] neg_lo:[0,1] neg_hi:[0,1]
	ds_write_b32 v178, v85 offset:9856
	v_pk_mul_f32 v[122:123], v[132:133], v[122:123]
	s_nop 0
	v_pk_fma_f32 v[122:123], v[82:83], v[122:123], v[86:87] op_sel:[1,0,1]
	s_nop 0
	v_cvt_pk_bf16_f32 v85, v122, v123
	v_lshlrev_b32_e32 v122, 16, v125
	v_lshlrev_b32_e32 v123, 16, v129
	v_pk_add_f32 v[122:123], v[122:123], v[134:135] neg_lo:[0,1] neg_hi:[0,1]
	ds_write_b32 v178, v85 offset:12032
	v_pk_mul_f32 v[122:123], v[132:133], v[122:123]
	s_nop 0
	v_pk_fma_f32 v[122:123], v[84:85], v[122:123], v[88:89] op_sel_hi:[0,1,0]
	v_cvt_pk_bf16_f32 v85, v122, v123
	v_and_b32_e32 v122, 0xffff0000, v125
	v_and_b32_e32 v123, 0xffff0000, v129
	v_pk_add_f32 v[122:123], v[122:123], v[134:135] neg_lo:[0,1] neg_hi:[0,1]
	ds_write_b32 v178, v85 offset:14208
	v_pk_mul_f32 v[122:123], v[132:133], v[122:123]
	s_nop 0
	v_pk_fma_f32 v[122:123], v[164:165], v[122:123], v[166:167] op_sel_hi:[0,1,0]
	v_cvt_pk_bf16_f32 v85, v122, v123
	ds_write_b32 v178, v85 offset:16384
	ds_read_b128 v[122:125], v182 offset:640
	s_waitcnt lgkmcnt(0)
; __device__ __forceinline__ unsigned cvt_pk_bf16(float lo, float hi) { unsigned r; asm volatile("v_cvt_pk_bf16_f32 %0, %1, %2" : "=v"(r) : "v"(lo), "v"(hi)); return r; }
; __device__ __forceinline__ float bf_lo(unsigned w) { return __uint_as_float(w << 16); }
; __device__ __forceinline__ float bf_hi(unsigned w) { return __uint_as_float(w & 0xffff0000u); }
; #define LAS __attribute__((address_space(3)))
; __device__ __forceinline__ void sgu_unit(LAS unsigned char* lds, bf16* U, const bf16* VS, const float* SGS, const float* lnw, const float* lnb, const v4u* WF, const float* bsl, int unit, int tid) {
;     ...
;         for (int i = 0; i < 8; ++i) {
;             const f32x4 st4 = *(const LAS f32x4*)(stat + 4 * (rp + 8 * i));
;             const v4u w0 = sl[i][0], w1 = sl[i][1];
;             const unsigned A0[4] = {w0.x, w0.y, w0.z, w0.w}, A1[4] = {w1.x, w1.y, w1.z, w1.w};
; #pragma unroll
;             for (int e = 0; e < 8; ++e) { typedef float f32x2p __attribute__((ext_vector_type(2)));
;                 f32x2p v; v.x = (e & 1) ? bf_hi(A0[e >> 1]) : bf_lo(A0[e >> 1]); v.y = (e & 1) ? bf_hi(A1[e >> 1]) : bf_lo(A1[e >> 1]);
;                 const f32x2p mn = {st4.x, st4.z}, rs = {st4.y, st4.w};
;                 const f32x2p o = ((v - mn) * rs) * lw[e] + lb[e];
;                 *(LAS unsigned*)(wbase + e * 8 * SGU_VP + i * 32) = cvt_pk_bf16(o.x, o.y); }
;         }
	v_mov_b32_e32 v126, v122
	v_mov_b32_e32 v127, v124
	v_mov_b32_e32 v124, v123
	s_waitcnt vmcnt(5)
	v_lshlrev_b32_e32 v122, 16, v114
	s_waitcnt vmcnt(4)
	v_lshlrev_b32_e32 v123, 16, v118
	v_pk_add_f32 v[122:123], v[122:123], v[126:127] neg_lo:[0,1] neg_hi:[0,1]
	s_nop 0
	v_pk_mul_f32 v[122:123], v[124:125], v[122:123]
	s_nop 0
	v_pk_fma_f32 v[122:123], v[102:103], v[122:123], v[98:99] op_sel_hi:[0,1,0]
	v_cvt_pk_bf16_f32 v85, v122, v123
	v_and_b32_e32 v122, 0xffff0000, v114
	v_and_b32_e32 v123, 0xffff0000, v118
	v_pk_add_f32 v[122:123], v[122:123], v[126:127] neg_lo:[0,1] neg_hi:[0,1]
	ds_write_b32 v178, v85 offset:1184
	v_pk_mul_f32 v[122:123], v[124:125], v[122:123]
	v_and_b32_e32 v114, 0xffff0000, v115
	v_pk_fma_f32 v[122:123], v[102:103], v[122:123], v[98:99] op_sel:[1,0,1]
	s_nop 0
	v_cvt_pk_bf16_f32 v85, v122, v123
	v_lshlrev_b32_e32 v122, 16, v115
	v_lshlrev_b32_e32 v123, 16, v119
	v_and_b32_e32 v115, 0xffff0000, v119
	v_pk_add_f32 v[122:123], v[122:123], v[126:127] neg_lo:[0,1] neg_hi:[0,1]
	v_pk_add_f32 v[114:115], v[114:115], v[126:127] neg_lo:[0,1] neg_hi:[0,1]
	v_pk_mul_f32 v[122:123], v[124:125], v[122:123]
	v_pk_mul_f32 v[114:115], v[124:125], v[114:115]
	ds_write_b32 v178, v85 offset:3360
	v_pk_fma_f32 v[122:123], v[104:105], v[122:123], v[100:101] op_sel_hi:[0,1,0]
	v_cvt_pk_bf16_f32 v85, v122, v123
	v_pk_fma_f32 v[114:115], v[160:161], v[114:115], v[162:163] op_sel_hi:[0,1,0]
	ds_write_b32 v178, v85 offset:5536
	v_cvt_pk_bf16_f32 v85, v114, v115
	v_lshlrev_b32_e32 v114, 16, v116
	v_lshlrev_b32_e32 v115, 16, v120
	v_pk_add_f32 v[114:115], v[114:115], v[126:127] neg_lo:[0,1] neg_hi:[0,1]
	ds_write_b32 v178, v85 offset:7712
	v_pk_mul_f32 v[114:115], v[124:125], v[114:115]
	s_nop 0
	v_pk_fma_f32 v[114:115], v[82:83], v[114:115], v[86:87] op_sel_hi:[0,1,0]
	v_cvt_pk_bf16_f32 v85, v114, v115
	v_and_b32_e32 v114, 0xffff0000, v116
	v_and_b32_e32 v115, 0xffff0000, v120
	v_pk_add_f32 v[114:115], v[114:115], v[126:127] neg_lo:[0,1] neg_hi:[0,1]
	ds_write_b32 v178, v85 offset:9888
	v_pk_mul_f32 v[114:115], v[124:125], v[114:115]
	s_nop 0
	v_pk_fma_f32 v[114:115], v[82:83], v[114:115], v[86:87] op_sel:[1,0,1]
	s_nop 0
	v_cvt_pk_bf16_f32 v85, v114, v115
	v_lshlrev_b32_e32 v114, 16, v117
	v_lshlrev_b32_e32 v115, 16, v121
	v_pk_add_f32 v[114:115], v[114:115], v[126:127] neg_lo:[0,1] neg_hi:[0,1]
	ds_write_b32 v178, v85 offset:12064
	v_pk_mul_f32 v[114:115], v[124:125], v[114:115]
	s_nop 0
	v_pk_fma_f32 v[114:115], v[84:85], v[114:115], v[88:89] op_sel_hi:[0,1,0]
	v_cvt_pk_bf16_f32 v85, v114, v115
	v_and_b32_e32 v114, 0xffff0000, v117
	v_and_b32_e32 v115, 0xffff0000, v121
	v_pk_add_f32 v[114:115], v[114:115], v[126:127] neg_lo:[0,1] neg_hi:[0,1]
	ds_write_b32 v178, v85 offset:14240
	v_pk_mul_f32 v[114:115], v[124:125], v[114:115]
	s_nop 0
	v_pk_fma_f32 v[114:115], v[164:165], v[114:115], v[166:167] op_sel_hi:[0,1,0]
	v_cvt_pk_bf16_f32 v85, v114, v115
	ds_write_b32 v178, v85 offset:16416
	ds_read_b128 v[114:117], v182 offset:768
	s_waitcnt lgkmcnt(0)
	v_mov_b32_e32 v118, v114
	v_mov_b32_e32 v119, v116
	v_mov_b32_e32 v116, v115
	s_waitcnt vmcnt(3)
	v_lshlrev_b32_e32 v114, 16, v106
	s_waitcnt vmcnt(2)
	v_lshlrev_b32_e32 v115, 16, v110
	v_pk_add_f32 v[114:115], v[114:115], v[118:119] neg_lo:[0,1] neg_hi:[0,1]
	s_nop 0
	v_pk_mul_f32 v[114:115], v[116:117], v[114:115]
	s_nop 0
	v_pk_fma_f32 v[114:115], v[102:103], v[114:115], v[98:99] op_sel_hi:[0,1,0]
	v_cvt_pk_bf16_f32 v85, v114, v115
	v_and_b32_e32 v114, 0xffff0000, v106
	v_and_b32_e32 v115, 0xffff0000, v110
	v_pk_add_f32 v[114:115], v[114:115], v[118:119] neg_lo:[0,1] neg_hi:[0,1]
	ds_write_b32 v178, v85 offset:1216
	v_pk_mul_f32 v[114:115], v[116:117], v[114:115]
	v_and_b32_e32 v106, 0xffff0000, v107
	v_pk_fma_f32 v[114:115], v[102:103], v[114:115], v[98:99] op_sel:[1,0,1]
	s_nop 0
	v_cvt_pk_bf16_f32 v85, v114, v115
	v_lshlrev_b32_e32 v114, 16, v107
	v_lshlrev_b32_e32 v115, 16, v111
	v_and_b32_e32 v107, 0xffff0000, v111
	v_pk_add_f32 v[114:115], v[114:115], v[118:119] neg_lo:[0,1] neg_hi:[0,1]
	v_pk_add_f32 v[106:107], v[106:107], v[118:119] neg_lo:[0,1] neg_hi:[0,1]
	v_pk_mul_f32 v[114:115], v[116:117], v[114:115]
	v_pk_mul_f32 v[106:107], v[116:117], v[106:107]
	ds_write_b32 v178, v85 offset:3392
	v_pk_fma_f32 v[114:115], v[104:105], v[114:115], v[100:101] op_sel_hi:[0,1,0]
	v_cvt_pk_bf16_f32 v85, v114, v115
	v_pk_fma_f32 v[106:107], v[160:161], v[106:107], v[162:163] op_sel_hi:[0,1,0]
	ds_write_b32 v178, v85 offset:5568
	v_cvt_pk_bf16_f32 v85, v106, v107
	v_lshlrev_b32_e32 v106, 16, v108
	v_lshlrev_b32_e32 v107, 16, v112
	v_pk_add_f32 v[106:107], v[106:107], v[118:119] neg_lo:[0,1] neg_hi:[0,1]
	ds_write_b32 v178, v85 offset:7744
	v_pk_mul_f32 v[106:107], v[116:117], v[106:107]
	s_nop 0
	v_pk_fma_f32 v[106:107], v[82:83], v[106:107], v[86:87] op_sel_hi:[0,1,0]
	v_cvt_pk_bf16_f32 v85, v106, v107
	v_and_b32_e32 v106, 0xffff0000, v108
	v_and_b32_e32 v107, 0xffff0000, v112
	v_pk_add_f32 v[106:107], v[106:107], v[118:119] neg_lo:[0,1] neg_hi:[0,1]
	ds_write_b32 v178, v85 offset:9920
	v_pk_mul_f32 v[106:107], v[116:117], v[106:107]
	s_nop 0
	v_pk_fma_f32 v[106:107], v[82:83], v[106:107], v[86:87] op_sel:[1,0,1]
	s_nop 0
	v_cvt_pk_bf16_f32 v85, v106, v107
	v_lshlrev_b32_e32 v106, 16, v109
	v_lshlrev_b32_e32 v107, 16, v113
	v_pk_add_f32 v[106:107], v[106:107], v[118:119] neg_lo:[0,1] neg_hi:[0,1]
	ds_write_b32 v178, v85 offset:12096
	v_pk_mul_f32 v[106:107], v[116:117], v[106:107]
	s_nop 0
	v_pk_fma_f32 v[106:107], v[84:85], v[106:107], v[88:89] op_sel_hi:[0,1,0]
	v_cvt_pk_bf16_f32 v85, v106, v107
	v_and_b32_e32 v106, 0xffff0000, v109
	v_and_b32_e32 v107, 0xffff0000, v113
	v_pk_add_f32 v[106:107], v[106:107], v[118:119] neg_lo:[0,1] neg_hi:[0,1]
	ds_write_b32 v178, v85 offset:14272
	v_pk_mul_f32 v[106:107], v[116:117], v[106:107]
	s_nop 0
	v_pk_fma_f32 v[106:107], v[164:165], v[106:107], v[166:167] op_sel_hi:[0,1,0]
	v_cvt_pk_bf16_f32 v85, v106, v107
	ds_write_b32 v178, v85 offset:16448
	ds_read_b128 v[106:109], v182 offset:896
	s_waitcnt lgkmcnt(0)
; __device__ __forceinline__ unsigned cvt_pk_bf16(float lo, float hi) { unsigned r; asm volatile("v_cvt_pk_bf16_f32 %0, %1, %2" : "=v"(r) : "v"(lo), "v"(hi)); return r; }
; __device__ __forceinline__ float bf_lo(unsigned w) { return __uint_as_float(w << 16); }
; __device__ __forceinline__ float bf_hi(unsigned w) { return __uint_as_float(w & 0xffff0000u); }
; #define LAS __attribute__((address_space(3)))
; __device__ __forceinline__ void sgu_unit(LAS unsigned char* lds, bf16* U, const bf16* VS, const float* SGS, const float* lnw, const float* lnb, const v4u* WF, const float* bsl, int unit, int tid) {
;     ...
;         for (int i = 0; i < 8; ++i) {
;             const f32x4 st4 = *(const LAS f32x4*)(stat + 4 * (rp + 8 * i));
;             const v4u w0 = sl[i][0], w1 = sl[i][1];
;             const unsigned A0[4] = {w0.x, w0.y, w0.z, w0.w}, A1[4] = {w1.x, w1.y, w1.z, w1.w};
; #pragma unroll
;             for (int e = 0; e < 8; ++e) { typedef float f32x2p __attribute__((ext_vector_type(2)));
;                 f32x2p v; v.x = (e & 1) ? bf_hi(A0[e >> 1]) : bf_lo(A0[e >> 1]); v.y = (e & 1) ? bf_hi(A1[e >> 1]) : bf_lo(A1[e >> 1]);
;                 const f32x2p mn = {st4.x, st4.z}, rs = {st4.y, st4.w};
;                 const f32x2p o = ((v - mn) * rs) * lw[e] + lb[e];
;                 *(LAS unsigned*)(wbase + e * 8 * SGU_VP + i * 32) = cvt_pk_bf16(o.x, o.y); }
;         }
;     }
;     v2u uu[8][4];
; #pragma unroll
;     for (int mt = 0; mt < 8; ++mt)
; #pragma unroll
;         for (int nt = 0; nt < 4; ++nt) uu[mt][nt] = *(const v2u*)(U + (size_t)(r0 + 16 * mt + fr) * 1024 + colbase + 16 * nt + 4 * fq);
	v_mov_b32_e32 v110, v106
	v_mov_b32_e32 v111, v108
	v_mov_b32_e32 v108, v107
	s_waitcnt vmcnt(1)
	v_lshlrev_b32_e32 v106, 16, v90
	s_waitcnt vmcnt(0)
	v_lshlrev_b32_e32 v107, 16, v94
	v_pk_add_f32 v[106:107], v[106:107], v[110:111] neg_lo:[0,1] neg_hi:[0,1]
	s_nop 0
	v_pk_mul_f32 v[106:107], v[108:109], v[106:107]
	s_nop 0
	v_pk_fma_f32 v[106:107], v[102:103], v[106:107], v[98:99] op_sel_hi:[0,1,0]
	v_cvt_pk_bf16_f32 v85, v106, v107
	v_and_b32_e32 v106, 0xffff0000, v90
	v_and_b32_e32 v107, 0xffff0000, v94
	v_pk_add_f32 v[106:107], v[106:107], v[110:111] neg_lo:[0,1] neg_hi:[0,1]
	ds_write_b32 v178, v85 offset:1248
	v_pk_mul_f32 v[106:107], v[108:109], v[106:107]
	v_and_b32_e32 v90, 0xffff0000, v91
	v_pk_fma_f32 v[98:99], v[102:103], v[106:107], v[98:99] op_sel:[1,0,1]
	s_nop 0
	v_cvt_pk_bf16_f32 v85, v98, v99
	v_lshlrev_b32_e32 v98, 16, v91
	v_lshlrev_b32_e32 v99, 16, v95
	v_and_b32_e32 v91, 0xffff0000, v95
	v_pk_add_f32 v[98:99], v[98:99], v[110:111] neg_lo:[0,1] neg_hi:[0,1]
	v_pk_add_f32 v[90:91], v[90:91], v[110:111] neg_lo:[0,1] neg_hi:[0,1]
	v_pk_mul_f32 v[98:99], v[108:109], v[98:99]
	v_pk_mul_f32 v[90:91], v[108:109], v[90:91]
	ds_write_b32 v178, v85 offset:3424
	v_pk_fma_f32 v[98:99], v[104:105], v[98:99], v[100:101] op_sel_hi:[0,1,0]
	v_cvt_pk_bf16_f32 v85, v98, v99
	v_pk_fma_f32 v[90:91], v[160:161], v[90:91], v[162:163] op_sel_hi:[0,1,0]
	ds_write_b32 v178, v85 offset:5600
	v_cvt_pk_bf16_f32 v85, v90, v91
	v_lshlrev_b32_e32 v90, 16, v92
	v_lshlrev_b32_e32 v91, 16, v96
	v_pk_add_f32 v[90:91], v[90:91], v[110:111] neg_lo:[0,1] neg_hi:[0,1]
	ds_write_b32 v178, v85 offset:7776
	v_pk_mul_f32 v[90:91], v[108:109], v[90:91]
	s_nop 0
	v_pk_fma_f32 v[90:91], v[82:83], v[90:91], v[86:87] op_sel_hi:[0,1,0]
	v_cvt_pk_bf16_f32 v85, v90, v91
	v_and_b32_e32 v90, 0xffff0000, v92
	v_and_b32_e32 v91, 0xffff0000, v96
	v_pk_add_f32 v[90:91], v[90:91], v[110:111] neg_lo:[0,1] neg_hi:[0,1]
	ds_write_b32 v178, v85 offset:9952
	v_pk_mul_f32 v[90:91], v[108:109], v[90:91]
	s_nop 0
	v_pk_fma_f32 v[82:83], v[82:83], v[90:91], v[86:87] op_sel:[1,0,1]
	s_nop 0
	v_cvt_pk_bf16_f32 v82, v82, v83
	ds_write_b32 v178, v82 offset:12128
	v_lshlrev_b32_e32 v82, 16, v93
	v_lshlrev_b32_e32 v83, 16, v97
	v_pk_add_f32 v[82:83], v[82:83], v[110:111] neg_lo:[0,1] neg_hi:[0,1]
	s_nop 0
	v_pk_mul_f32 v[82:83], v[108:109], v[82:83]
	s_nop 0
	v_pk_fma_f32 v[82:83], v[84:85], v[82:83], v[88:89] op_sel_hi:[0,1,0]
	v_cvt_pk_bf16_f32 v82, v82, v83
	ds_write_b32 v178, v82 offset:14304
	v_and_b32_e32 v82, 0xffff0000, v93
	v_and_b32_e32 v83, 0xffff0000, v97
	v_pk_add_f32 v[82:83], v[82:83], v[110:111] neg_lo:[0,1] neg_hi:[0,1]
	v_or_b32_e32 v84, s16, v163
	v_pk_mul_f32 v[82:83], v[108:109], v[82:83]
	v_lshlrev_b32_e32 v84, 11, v84
	v_pk_fma_f32 v[82:83], v[164:165], v[82:83], v[166:167] op_sel_hi:[0,1,0]
	v_cvt_pk_bf16_f32 v82, v82, v83
	ds_write_b32 v178, v82 offset:16480
	v_lshl_add_u64 v[82:83], v[158:159], 1, v[150:151]
	v_mov_b32_e32 v85, v147
	v_lshl_add_u64 v[144:145], v[82:83], 0, v[84:85]
	global_load_dwordx2 v[158:159], v[144:145], off
	global_load_dwordx2 v[218:219], v[144:145], off offset:32
	global_load_dwordx2 v[220:221], v[144:145], off offset:64
	global_load_dwordx2 v[222:223], v[144:145], off offset:96
	v_add_co_u32_e32 v226, vcc, s40, v144
	s_waitcnt vmcnt(3)
	v_lshlrev_b32_e32 v160, 16, v158
	v_addc_co_u32_e32 v227, vcc, 0, v145, vcc
	global_load_dwordx2 v[224:225], v[226:227], off
	global_load_dwordx2 v[228:229], v[226:227], off offset:32
	global_load_dwordx2 v[230:231], v[226:227], off offset:64
	global_load_dwordx2 v[232:233], v[226:227], off offset:96
	v_add_co_u32_e32 v130, vcc, s41, v144
	v_and_b32_e32 v158, 0xffff0000, v158
	s_nop 0
	v_addc_co_u32_e32 v131, vcc, 0, v145, vcc
	v_add_co_u32_e32 v120, vcc, s44, v144
	global_load_dwordx2 v[234:235], v[130:131], off
	global_load_dwordx2 v[138:139], v[130:131], off offset:32
	global_load_dwordx2 v[136:137], v[130:131], off offset:64
	global_load_dwordx2 v[134:135], v[130:131], off offset:96
	v_addc_co_u32_e32 v121, vcc, 0, v145, vcc
	v_add_co_u32_e32 v110, vcc, s45, v144
	global_load_dwordx2 v[132:133], v[120:121], off
	global_load_dwordx2 v[128:129], v[120:121], off offset:32
	global_load_dwordx2 v[126:127], v[120:121], off offset:64
	global_load_dwordx2 v[124:125], v[120:121], off offset:96
	v_addc_co_u32_e32 v111, vcc, 0, v145, vcc
	v_add_co_u32_e32 v100, vcc, s46, v144
	global_load_dwordx2 v[122:123], v[110:111], off
	global_load_dwordx2 v[118:119], v[110:111], off offset:32
	global_load_dwordx2 v[116:117], v[110:111], off offset:64
	global_load_dwordx2 v[114:115], v[110:111], off offset:96
	v_addc_co_u32_e32 v101, vcc, 0, v145, vcc
	v_add_co_u32_e32 v90, vcc, s47, v144
	global_load_dwordx2 v[112:113], v[100:101], off
	global_load_dwordx2 v[108:109], v[100:101], off offset:32
	global_load_dwordx2 v[106:107], v[100:101], off offset:64
	global_load_dwordx2 v[104:105], v[100:101], off offset:96
	v_addc_co_u32_e32 v91, vcc, 0, v145, vcc
	v_lshrrev_b32_e32 v236, 4, v0
	v_and_b32_e32 v236, 1, v236
	v_mul_u32_u24_e32 v236, 24, v236
	v_mov_b32_e32 v237, 0
	v_add_co_u32_e32 v82, vcc, s59, v144
	global_load_dwordx2 v[102:103], v[90:91], off
	global_load_dwordx2 v[98:99], v[90:91], off offset:32
	global_load_dwordx2 v[96:97], v[90:91], off offset:64
	global_load_dwordx2 v[94:95], v[90:91], off offset:96
	v_addc_co_u32_e32 v83, vcc, 0, v145, vcc
	global_load_dwordx2 v[92:93], v[82:83], off
	global_load_dwordx2 v[88:89], v[82:83], off offset:32
	global_load_dwordx2 v[86:87], v[82:83], off offset:64
	global_load_dwordx2 v[84:85], v[82:83], off offset:96
	s_waitcnt lgkmcnt(0)
; __device__ __forceinline__ unsigned cvt_pk_bf16(float lo, float hi) { unsigned r; asm volatile("v_cvt_pk_bf16_f32 %0, %1, %2" : "=v"(r) : "v"(lo), "v"(hi)); return r; }
; __device__ __forceinline__ float bf_lo(unsigned w) { return __uint_as_float(w << 16); }
; __device__ __forceinline__ float bf_hi(unsigned w) { return __uint_as_float(w & 0xffff0000u); }
; #define LAS __attribute__((address_space(3)))
; __device__ __forceinline__ void sgu_unit(LAS unsigned char* lds, bf16* U, const bf16* VS, const float* SGS, const float* lnw, const float* lnb, const v4u* WF, const float* bsl, int unit, int tid) {
;     ...
;         for (int mt = 0; mt < 8; ++mt) {
;             const int t = 16 * mt + fr;
;             f32x4 acc[4];
; #pragma unroll
;             for (int nt = 0; nt < 4; ++nt) acc[nt] = (f32x4){0.f, 0.f, 0.f, 0.f};
; #pragma unroll
;             for (int ks = 0; ks <= (mt >> 1); ++ks) {
;                 const int sb = 32 * ks + 8 * fq; const bf16x8_t wf = __builtin_bit_cast(bf16x8_t, wfr[q++]);
; #pragma unroll
;                 for (int nt = 0; nt < 4; ++nt) { const bf16x8_t vf = *(const LAS bf16x8_t*)(vt + ((fr >> 3) + 8 * (fr & 7) + 2 * nt) * SGU_VP + sb * 2);
;                     acc[nt] = __builtin_amdgcn_mfma_f32_16x16x32_bf16(vf, wf, acc[nt], 0, 0, 0); }
;             }
;             const float bb = bbv[mt];
; #pragma unroll
;             for (int nt = 0; nt < 4; ++nt) { const v2u u2 = uu[mt][nt]; v2u w; w.x = cvt_pk_bf16(bf_lo(u2.x) * (acc[nt][0] + bb), bf_hi(u2.x) * (acc[nt][1] + bb)); w.y = cvt_pk_bf16(bf_lo(u2.y) * (acc[nt][2] + bb), bf_hi(u2.y) * (acc[nt][3] + bb));
;                 *(v2u*)(U + (size_t)(r0 + t) * 1024 + colbase + 16 * nt + 4 * fq) = w; }
	ds_read_b128 v[140:143], v183 offset:1024
	ds_read_b128 v[206:209], v183 offset:1568
	s_waitcnt lgkmcnt(1)
	v_mfma_f32_16x16x32_bf16 v[140:143], v[140:143], v[78:81], 0
	ds_read_b128 v[210:213], v183 offset:2112
	ds_read_b128 v[214:217], v183 offset:2656
	s_nop 5
	v_add_f32_e32 v140, v198, v140
	v_add_f32_e32 v141, v198, v141
	s_waitcnt lgkmcnt(2)
	v_mfma_f32_16x16x32_bf16 v[206:209], v[206:209], v[78:81], 0
	v_mul_f32_e32 v140, v140, v160
	v_mul_f32_e32 v141, v141, v158
	v_cvt_pk_bf16_f32 v248, v140, v141
	v_lshlrev_b32_e32 v141, 16, v159
	v_add_f32_e32 v142, v198, v142
	v_mul_f32_e32 v141, v142, v141
	v_and_b32_e32 v142, 0xffff0000, v159
	v_add_f32_e32 v143, v198, v143
	v_mul_f32_e32 v142, v143, v142
	v_cvt_pk_bf16_f32 v249, v141, v142
	v_lshl_add_u64 v[238:239], v[144:145], 0, v[236:237]
	s_waitcnt vmcnt(30)
	v_lshlrev_b32_e32 v140, 16, v218
	v_add_f32_e32 v141, v198, v206
	v_mul_f32_e32 v140, v141, v140
	v_and_b32_e32 v141, 0xffff0000, v218
	v_add_f32_e32 v142, v198, v207
	s_waitcnt lgkmcnt(1)
	v_mfma_f32_16x16x32_bf16 v[210:213], v[210:213], v[78:81], 0
	v_mul_f32_e32 v141, v142, v141
	v_cvt_pk_bf16_f32 v250, v140, v141
	v_lshlrev_b32_e32 v141, 16, v219
	v_add_f32_e32 v142, v198, v208
	v_mul_f32_e32 v141, v142, v141
	v_and_b32_e32 v142, 0xffff0000, v219
	v_add_f32_e32 v143, v198, v209
	v_mul_f32_e32 v142, v143, v142
	v_cvt_pk_bf16_f32 v251, v141, v142
	s_nop 1
	v_permlane16_swap_b32_e32 v248, v250
	v_permlane16_swap_b32_e32 v249, v251
	global_store_dwordx4 v[238:239], v[248:251], off
	s_waitcnt vmcnt(30)
	v_lshlrev_b32_e32 v140, 16, v220
	v_add_f32_e32 v141, v198, v210
	s_waitcnt lgkmcnt(0)
	v_mfma_f32_16x16x32_bf16 v[78:81], v[214:217], v[78:81], 0
	v_mul_f32_e32 v140, v141, v140
	v_and_b32_e32 v141, 0xffff0000, v220
	v_add_f32_e32 v142, v198, v211
	v_mul_f32_e32 v141, v142, v141
	v_cvt_pk_bf16_f32 v252, v140, v141
	v_lshlrev_b32_e32 v141, 16, v221
	v_add_f32_e32 v142, v198, v212
	v_mul_f32_e32 v141, v142, v141
	v_and_b32_e32 v142, 0xffff0000, v221
	v_add_f32_e32 v143, v198, v213
	v_mul_f32_e32 v142, v143, v142
	v_cvt_pk_bf16_f32 v253, v141, v142
	s_waitcnt vmcnt(29)
	v_lshlrev_b32_e32 v140, 16, v222
	v_add_f32_e32 v78, v198, v78
	v_mul_f32_e32 v78, v78, v140
	v_and_b32_e32 v140, 0xffff0000, v222
	v_add_f32_e32 v79, v198, v79
	v_mul_f32_e32 v79, v79, v140
	v_cvt_pk_bf16_f32 v254, v78, v79
	v_lshlrev_b32_e32 v78, 16, v223
	v_add_f32_e32 v79, v198, v80
	v_mul_f32_e32 v78, v79, v78
	v_and_b32_e32 v79, 0xffff0000, v223
	v_add_f32_e32 v80, v198, v81
	v_mul_f32_e32 v79, v80, v79
	v_cvt_pk_bf16_f32 v255, v78, v79
	ds_read_b128 v[78:81], v183 offset:1024
	ds_read_b128 v[140:143], v183 offset:1568
	s_waitcnt lgkmcnt(1)
	v_mfma_f32_16x16x32_bf16 v[78:81], v[78:81], v[74:77], 0
	ds_read_b128 v[206:209], v183 offset:2112
	ds_read_b128 v[210:213], v183 offset:2656
	s_nop 1
	v_permlane16_swap_b32_e32 v252, v254
	v_permlane16_swap_b32_e32 v253, v255
	global_store_dwordx4 v[238:239], v[252:255], off offset:64
	s_waitcnt vmcnt(29)
	v_lshlrev_b32_e32 v144, 16, v224
	s_nop 2
	v_add_f32_e32 v78, v197, v78
	v_mul_f32_e32 v78, v78, v144
	v_and_b32_e32 v144, 0xffff0000, v224
	v_add_f32_e32 v79, v197, v79
	s_waitcnt lgkmcnt(2)
	v_mfma_f32_16x16x32_bf16 v[140:143], v[140:143], v[74:77], 0
	v_mul_f32_e32 v79, v79, v144
	v_cvt_pk_bf16_f32 v248, v78, v79
	v_lshlrev_b32_e32 v79, 16, v225
	v_add_f32_e32 v80, v197, v80
	v_mul_f32_e32 v79, v80, v79
	v_and_b32_e32 v80, 0xffff0000, v225
	v_add_f32_e32 v81, v197, v81
	v_mul_f32_e32 v80, v81, v80
	v_cvt_pk_bf16_f32 v249, v79, v80
	v_lshl_add_u64 v[238:239], v[226:227], 0, v[236:237]
	s_waitcnt vmcnt(28)
	v_lshlrev_b32_e32 v78, 16, v228
	v_add_f32_e32 v79, v197, v140
	v_mul_f32_e32 v78, v79, v78
	v_and_b32_e32 v79, 0xffff0000, v228
	v_add_f32_e32 v80, v197, v141
	s_waitcnt lgkmcnt(1)
	v_mfma_f32_16x16x32_bf16 v[206:209], v[206:209], v[74:77], 0
	v_mul_f32_e32 v79, v80, v79
	v_cvt_pk_bf16_f32 v250, v78, v79
	v_lshlrev_b32_e32 v79, 16, v229
	v_add_f32_e32 v80, v197, v142
	v_mul_f32_e32 v79, v80, v79
	v_and_b32_e32 v80, 0xffff0000, v229
	v_add_f32_e32 v81, v197, v143
	v_mul_f32_e32 v80, v81, v80
	v_cvt_pk_bf16_f32 v251, v79, v80
	s_nop 1
	v_permlane16_swap_b32_e32 v248, v250
	v_permlane16_swap_b32_e32 v249, v251
	global_store_dwordx4 v[238:239], v[248:251], off
	s_waitcnt vmcnt(28)
	v_lshlrev_b32_e32 v78, 16, v230
	v_add_f32_e32 v79, v197, v206
	s_waitcnt lgkmcnt(0)
	v_mfma_f32_16x16x32_bf16 v[74:77], v[210:213], v[74:77], 0
	v_mul_f32_e32 v78, v79, v78
	v_and_b32_e32 v79, 0xffff0000, v230
	v_add_f32_e32 v80, v197, v207
	v_mul_f32_e32 v79, v80, v79
	v_cvt_pk_bf16_f32 v252, v78, v79
	v_lshlrev_b32_e32 v79, 16, v231
	v_add_f32_e32 v80, v197, v208
	v_mul_f32_e32 v79, v80, v79
	v_and_b32_e32 v80, 0xffff0000, v231
	v_add_f32_e32 v81, v197, v209
	v_mul_f32_e32 v80, v81, v80
	v_cvt_pk_bf16_f32 v253, v79, v80
	s_waitcnt vmcnt(27)
	v_lshlrev_b32_e32 v78, 16, v232
	v_add_f32_e32 v74, v197, v74
	v_mul_f32_e32 v74, v74, v78
	v_and_b32_e32 v78, 0xffff0000, v232
	v_add_f32_e32 v75, v197, v75
	v_mul_f32_e32 v75, v75, v78
	v_cvt_pk_bf16_f32 v254, v74, v75
	v_lshlrev_b32_e32 v74, 16, v233
	v_add_f32_e32 v75, v197, v76
	v_mul_f32_e32 v74, v75, v74
	v_and_b32_e32 v75, 0xffff0000, v233
	v_add_f32_e32 v76, v197, v77
	v_mul_f32_e32 v75, v76, v75
	v_cvt_pk_bf16_f32 v255, v74, v75
	ds_read_b128 v[74:77], v183 offset:1024
	ds_read_b128 v[78:81], v183 offset:1088
	s_waitcnt lgkmcnt(1)
	v_mfma_f32_16x16x32_bf16 v[74:77], v[74:77], v[70:73], 0
	ds_read_b128 v[140:143], v183 offset:1568
	ds_read_b128 v[206:209], v183 offset:1632
	ds_read_b128 v[210:213], v183 offset:2112
	ds_read_b128 v[214:217], v183 offset:2176
	ds_read_b128 v[218:221], v183 offset:2656
	ds_read_b128 v[222:225], v183 offset:2720
	s_waitcnt lgkmcnt(5)
; __device__ __forceinline__ unsigned cvt_pk_bf16(float lo, float hi) { unsigned r; asm volatile("v_cvt_pk_bf16_f32 %0, %1, %2" : "=v"(r) : "v"(lo), "v"(hi)); return r; }
; __device__ __forceinline__ float bf_lo(unsigned w) { return __uint_as_float(w << 16); }
; __device__ __forceinline__ float bf_hi(unsigned w) { return __uint_as_float(w & 0xffff0000u); }
; #define LAS __attribute__((address_space(3)))
; __device__ __forceinline__ void sgu_unit(LAS unsigned char* lds, bf16* U, const bf16* VS, const float* SGS, const float* lnw, const float* lnb, const v4u* WF, const float* bsl, int unit, int tid) {
;     ...
;         for (int mt = 0; mt < 8; ++mt) {
;             const int t = 16 * mt + fr;
;             f32x4 acc[4];
; #pragma unroll
;             for (int nt = 0; nt < 4; ++nt) acc[nt] = (f32x4){0.f, 0.f, 0.f, 0.f};
; #pragma unroll
;             for (int ks = 0; ks <= (mt >> 1); ++ks) {
;                 const int sb = 32 * ks + 8 * fq; const bf16x8_t wf = __builtin_bit_cast(bf16x8_t, wfr[q++]);
; #pragma unroll
;                 for (int nt = 0; nt < 4; ++nt) { const bf16x8_t vf = *(const LAS bf16x8_t*)(vt + ((fr >> 3) + 8 * (fr & 7) + 2 * nt) * SGU_VP + sb * 2);
;                     acc[nt] = __builtin_amdgcn_mfma_f32_16x16x32_bf16(vf, wf, acc[nt], 0, 0, 0); }
;             }
;             const float bb = bbv[mt];
; #pragma unroll
;             for (int nt = 0; nt < 4; ++nt) { const v2u u2 = uu[mt][nt]; v2u w; w.x = cvt_pk_bf16(bf_lo(u2.x) * (acc[nt][0] + bb), bf_hi(u2.x) * (acc[nt][1] + bb)); w.y = cvt_pk_bf16(bf_lo(u2.y) * (acc[nt][2] + bb), bf_hi(u2.y) * (acc[nt][3] + bb));
;                 *(v2u*)(U + (size_t)(r0 + t) * 1024 + colbase + 16 * nt + 4 * fq) = w; }
	v_mfma_f32_16x16x32_bf16 v[140:143], v[140:143], v[70:73], 0
	s_nop 1
	v_permlane16_swap_b32_e32 v252, v254
	v_permlane16_swap_b32_e32 v253, v255
	global_store_dwordx4 v[238:239], v[252:255], off offset:64
	s_waitcnt lgkmcnt(3)
	v_mfma_f32_16x16x32_bf16 v[210:213], v[210:213], v[70:73], 0
	s_waitcnt lgkmcnt(1)
	v_mfma_f32_16x16x32_bf16 v[70:73], v[218:221], v[70:73], 0
	v_mfma_f32_16x16x32_bf16 v[74:77], v[78:81], v[66:69], v[74:77]
	v_mfma_f32_16x16x32_bf16 v[78:81], v[206:209], v[66:69], v[140:143]
	v_mfma_f32_16x16x32_bf16 v[140:143], v[214:217], v[66:69], v[210:213]
	s_waitcnt lgkmcnt(0)
	v_mfma_f32_16x16x32_bf16 v[66:69], v[222:225], v[66:69], v[70:73]
	s_waitcnt vmcnt(27)
	s_nop 1
	v_lshlrev_b32_e32 v70, 16, v234
	v_add_f32_e32 v71, v196, v74
	v_mul_f32_e32 v70, v71, v70
	v_and_b32_e32 v71, 0xffff0000, v234
	v_add_f32_e32 v72, v196, v75
	v_mul_f32_e32 v71, v72, v71
	v_cvt_pk_bf16_f32 v248, v70, v71
	v_lshlrev_b32_e32 v71, 16, v235
	v_add_f32_e32 v72, v196, v76
	v_mul_f32_e32 v71, v72, v71
	v_and_b32_e32 v72, 0xffff0000, v235
	v_add_f32_e32 v73, v196, v77
	v_mul_f32_e32 v72, v73, v72
	v_cvt_pk_bf16_f32 v249, v71, v72
	v_lshl_add_u64 v[238:239], v[130:131], 0, v[236:237]
	s_waitcnt vmcnt(26)
	v_lshlrev_b32_e32 v70, 16, v138
	v_add_f32_e32 v71, v196, v78
	v_mul_f32_e32 v70, v71, v70
	v_and_b32_e32 v71, 0xffff0000, v138
	v_add_f32_e32 v72, v196, v79
	v_mul_f32_e32 v71, v72, v71
	v_cvt_pk_bf16_f32 v250, v70, v71
	v_lshlrev_b32_e32 v71, 16, v139
	v_add_f32_e32 v72, v196, v80
	v_mul_f32_e32 v71, v72, v71
	v_and_b32_e32 v72, 0xffff0000, v139
	v_add_f32_e32 v73, v196, v81
	v_mul_f32_e32 v72, v73, v72
	v_cvt_pk_bf16_f32 v251, v71, v72
	s_nop 1
	v_permlane16_swap_b32_e32 v248, v250
	v_permlane16_swap_b32_e32 v249, v251
	global_store_dwordx4 v[238:239], v[248:251], off
	s_waitcnt vmcnt(26)
	v_lshlrev_b32_e32 v70, 16, v136
	v_add_f32_e32 v71, v196, v140
	v_mul_f32_e32 v70, v71, v70
	v_and_b32_e32 v71, 0xffff0000, v136
	v_add_f32_e32 v72, v196, v141
	v_mul_f32_e32 v71, v72, v71
	v_cvt_pk_bf16_f32 v252, v70, v71
	v_lshlrev_b32_e32 v71, 16, v137
	v_add_f32_e32 v72, v196, v142
	v_mul_f32_e32 v71, v72, v71
	v_and_b32_e32 v72, 0xffff0000, v137
	v_add_f32_e32 v73, v196, v143
	v_mul_f32_e32 v72, v73, v72
	v_cvt_pk_bf16_f32 v253, v71, v72
	s_waitcnt vmcnt(25)
	v_lshlrev_b32_e32 v70, 16, v134
	v_add_f32_e32 v66, v196, v66
	v_mul_f32_e32 v66, v66, v70
	v_and_b32_e32 v70, 0xffff0000, v134
	v_add_f32_e32 v67, v196, v67
	v_mul_f32_e32 v67, v67, v70
	v_cvt_pk_bf16_f32 v254, v66, v67
	v_lshlrev_b32_e32 v66, 16, v135
	v_add_f32_e32 v67, v196, v68
	v_mul_f32_e32 v66, v67, v66
	v_and_b32_e32 v67, 0xffff0000, v135
	v_add_f32_e32 v68, v196, v69
	v_mul_f32_e32 v67, v68, v67
	v_cvt_pk_bf16_f32 v255, v66, v67
	ds_read_b128 v[66:69], v183 offset:1024
	ds_read_b128 v[70:73], v183 offset:1088
	s_waitcnt lgkmcnt(1)
	v_mfma_f32_16x16x32_bf16 v[66:69], v[66:69], v[62:65], 0
	ds_read_b128 v[74:77], v183 offset:1568
	ds_read_b128 v[78:81], v183 offset:1632
	ds_read_b128 v[134:137], v183 offset:2112
	ds_read_b128 v[138:141], v183 offset:2176
	ds_read_b128 v[142:145], v183 offset:2656
	ds_read_b128 v[196:199], v183 offset:2720
	s_waitcnt lgkmcnt(5)
	v_mfma_f32_16x16x32_bf16 v[74:77], v[74:77], v[62:65], 0
	s_nop 1
	v_permlane16_swap_b32_e32 v252, v254
	v_permlane16_swap_b32_e32 v253, v255
	global_store_dwordx4 v[238:239], v[252:255], off offset:64
	s_waitcnt lgkmcnt(3)
	v_mfma_f32_16x16x32_bf16 v[134:137], v[134:137], v[62:65], 0
	s_waitcnt lgkmcnt(1)
	v_mfma_f32_16x16x32_bf16 v[62:65], v[142:145], v[62:65], 0
	v_mfma_f32_16x16x32_bf16 v[66:69], v[70:73], v[58:61], v[66:69]
	v_mfma_f32_16x16x32_bf16 v[70:73], v[78:81], v[58:61], v[74:77]
	v_mfma_f32_16x16x32_bf16 v[74:77], v[138:141], v[58:61], v[134:137]
	s_waitcnt lgkmcnt(0)
	v_mfma_f32_16x16x32_bf16 v[58:61], v[196:199], v[58:61], v[62:65]
	s_waitcnt vmcnt(25)
	s_nop 1
	v_lshlrev_b32_e32 v62, 16, v132
	v_add_f32_e32 v63, v195, v66
	v_mul_f32_e32 v62, v63, v62
	v_and_b32_e32 v63, 0xffff0000, v132
	v_add_f32_e32 v64, v195, v67
	v_mul_f32_e32 v63, v64, v63
	v_cvt_pk_bf16_f32 v248, v62, v63
	v_lshlrev_b32_e32 v63, 16, v133
	v_add_f32_e32 v64, v195, v68
	v_mul_f32_e32 v63, v64, v63
	v_and_b32_e32 v64, 0xffff0000, v133
	v_add_f32_e32 v65, v195, v69
	v_mul_f32_e32 v64, v65, v64
	v_cvt_pk_bf16_f32 v249, v63, v64
	v_lshl_add_u64 v[238:239], v[120:121], 0, v[236:237]
	s_waitcnt vmcnt(24)
	v_lshlrev_b32_e32 v62, 16, v128
	v_add_f32_e32 v63, v195, v70
	v_mul_f32_e32 v62, v63, v62
	v_and_b32_e32 v63, 0xffff0000, v128
	v_add_f32_e32 v64, v195, v71
	v_mul_f32_e32 v63, v64, v63
	v_cvt_pk_bf16_f32 v250, v62, v63
	v_lshlrev_b32_e32 v63, 16, v129
	v_add_f32_e32 v64, v195, v72
	v_mul_f32_e32 v63, v64, v63
	v_and_b32_e32 v64, 0xffff0000, v129
	v_add_f32_e32 v65, v195, v73
	v_mul_f32_e32 v64, v65, v64
	v_cvt_pk_bf16_f32 v251, v63, v64
	s_nop 1
	v_permlane16_swap_b32_e32 v248, v250
	v_permlane16_swap_b32_e32 v249, v251
	global_store_dwordx4 v[238:239], v[248:251], off
	s_waitcnt vmcnt(24)
	v_lshlrev_b32_e32 v62, 16, v126
	v_add_f32_e32 v63, v195, v74
	v_mul_f32_e32 v62, v63, v62
	v_and_b32_e32 v63, 0xffff0000, v126
	v_add_f32_e32 v64, v195, v75
	v_mul_f32_e32 v63, v64, v63
	v_cvt_pk_bf16_f32 v252, v62, v63
	v_lshlrev_b32_e32 v63, 16, v127
	v_add_f32_e32 v64, v195, v76
	v_mul_f32_e32 v63, v64, v63
	v_and_b32_e32 v64, 0xffff0000, v127
	v_add_f32_e32 v65, v195, v77
	v_mul_f32_e32 v64, v65, v64
	v_cvt_pk_bf16_f32 v253, v63, v64
	s_waitcnt vmcnt(23)
; __device__ __forceinline__ unsigned cvt_pk_bf16(float lo, float hi) { unsigned r; asm volatile("v_cvt_pk_bf16_f32 %0, %1, %2" : "=v"(r) : "v"(lo), "v"(hi)); return r; }
; __device__ __forceinline__ float bf_lo(unsigned w) { return __uint_as_float(w << 16); }
; __device__ __forceinline__ float bf_hi(unsigned w) { return __uint_as_float(w & 0xffff0000u); }
; #define LAS __attribute__((address_space(3)))
; __device__ __forceinline__ void sgu_unit(LAS unsigned char* lds, bf16* U, const bf16* VS, const float* SGS, const float* lnw, const float* lnb, const v4u* WF, const float* bsl, int unit, int tid) {
;     ...
;             for (int ks = 0; ks <= (mt >> 1); ++ks) {
;                 const int sb = 32 * ks + 8 * fq; const bf16x8_t wf = __builtin_bit_cast(bf16x8_t, wfr[q++]);
; #pragma unroll
;                 for (int nt = 0; nt < 4; ++nt) { const bf16x8_t vf = *(const LAS bf16x8_t*)(vt + ((fr >> 3) + 8 * (fr & 7) + 2 * nt) * SGU_VP + sb * 2);
;                     acc[nt] = __builtin_amdgcn_mfma_f32_16x16x32_bf16(vf, wf, acc[nt], 0, 0, 0); }
;             }
;             const float bb = bbv[mt];
; #pragma unroll
;             for (int nt = 0; nt < 4; ++nt) { const v2u u2 = uu[mt][nt]; v2u w; w.x = cvt_pk_bf16(bf_lo(u2.x) * (acc[nt][0] + bb), bf_hi(u2.x) * (acc[nt][1] + bb)); w.y = cvt_pk_bf16(bf_lo(u2.y) * (acc[nt][2] + bb), bf_hi(u2.y) * (acc[nt][3] + bb));
;                 *(v2u*)(U + (size_t)(r0 + t) * 1024 + colbase + 16 * nt + 4 * fq) = w; }
	v_lshlrev_b32_e32 v62, 16, v124
	v_add_f32_e32 v58, v195, v58
	v_mul_f32_e32 v58, v58, v62
	v_and_b32_e32 v62, 0xffff0000, v124
	v_add_f32_e32 v59, v195, v59
	v_mul_f32_e32 v59, v59, v62
	v_cvt_pk_bf16_f32 v254, v58, v59
	v_lshlrev_b32_e32 v58, 16, v125
	v_add_f32_e32 v59, v195, v60
	v_mul_f32_e32 v58, v59, v58
	v_and_b32_e32 v59, 0xffff0000, v125
	v_add_f32_e32 v60, v195, v61
	v_mul_f32_e32 v59, v60, v59
	v_cvt_pk_bf16_f32 v255, v58, v59
	ds_read_b128 v[58:61], v183 offset:1024
	ds_read_b128 v[62:65], v183 offset:1088
	s_waitcnt lgkmcnt(1)
	v_mfma_f32_16x16x32_bf16 v[58:61], v[58:61], v[50:53], 0
	ds_read_b128 v[66:69], v183 offset:1568
	ds_read_b128 v[70:73], v183 offset:1152
	ds_read_b128 v[74:77], v183 offset:2112
	ds_read_b128 v[78:81], v183 offset:2176
	ds_read_b128 v[124:127], v183 offset:2656
	ds_read_b128 v[128:131], v183 offset:2240
	s_waitcnt lgkmcnt(5)
	v_mfma_f32_16x16x32_bf16 v[66:69], v[66:69], v[50:53], 0
	s_waitcnt lgkmcnt(3)
	v_mfma_f32_16x16x32_bf16 v[74:77], v[74:77], v[50:53], 0
	s_waitcnt lgkmcnt(1)
	v_mfma_f32_16x16x32_bf16 v[50:53], v[124:127], v[50:53], 0
	v_mfma_f32_16x16x32_bf16 v[58:61], v[62:65], v[54:57], v[58:61]
	ds_read_b128 v[62:65], v183 offset:1632
	ds_read_b128 v[124:127], v183 offset:1696
	s_waitcnt lgkmcnt(1)
	v_mfma_f32_16x16x32_bf16 v[62:65], v[62:65], v[54:57], v[66:69]
	v_mfma_f32_16x16x32_bf16 v[66:69], v[78:81], v[54:57], v[74:77]
	s_nop 2
	ds_read_b128 v[74:77], v183 offset:2720
	ds_read_b128 v[78:81], v183 offset:2784
	s_nop 1
	v_permlane16_swap_b32_e32 v252, v254
	v_permlane16_swap_b32_e32 v253, v255
	global_store_dwordx4 v[238:239], v[252:255], off offset:64
	s_waitcnt lgkmcnt(1)
	v_mfma_f32_16x16x32_bf16 v[50:53], v[74:77], v[54:57], v[50:53]
	v_mfma_f32_16x16x32_bf16 v[54:57], v[70:73], v[46:49], v[58:61]
	v_mfma_f32_16x16x32_bf16 v[58:61], v[124:127], v[46:49], v[62:65]
	v_mfma_f32_16x16x32_bf16 v[62:65], v[128:131], v[46:49], v[66:69]
	s_waitcnt lgkmcnt(0)
	v_mfma_f32_16x16x32_bf16 v[46:49], v[78:81], v[46:49], v[50:53]
	s_waitcnt vmcnt(23)
	s_nop 1
	v_lshlrev_b32_e32 v50, 16, v122
	v_add_f32_e32 v51, v194, v54
	v_mul_f32_e32 v50, v51, v50
	v_and_b32_e32 v51, 0xffff0000, v122
	v_add_f32_e32 v52, v194, v55
	v_mul_f32_e32 v51, v52, v51
	v_cvt_pk_bf16_f32 v248, v50, v51
	v_lshlrev_b32_e32 v51, 16, v123
	v_add_f32_e32 v52, v194, v56
	v_mul_f32_e32 v51, v52, v51
	v_and_b32_e32 v52, 0xffff0000, v123
	v_add_f32_e32 v53, v194, v57
	v_mul_f32_e32 v52, v53, v52
	v_cvt_pk_bf16_f32 v249, v51, v52
	v_lshl_add_u64 v[238:239], v[110:111], 0, v[236:237]
	s_waitcnt vmcnt(22)
	v_lshlrev_b32_e32 v50, 16, v118
	v_add_f32_e32 v51, v194, v58
	v_mul_f32_e32 v50, v51, v50
	v_and_b32_e32 v51, 0xffff0000, v118
	v_add_f32_e32 v52, v194, v59
	v_mul_f32_e32 v51, v52, v51
	v_cvt_pk_bf16_f32 v250, v50, v51
	v_lshlrev_b32_e32 v51, 16, v119
	v_add_f32_e32 v52, v194, v60
	v_mul_f32_e32 v51, v52, v51
	v_and_b32_e32 v52, 0xffff0000, v119
	v_add_f32_e32 v53, v194, v61
	v_mul_f32_e32 v52, v53, v52
	v_cvt_pk_bf16_f32 v251, v51, v52
	s_nop 1
	v_permlane16_swap_b32_e32 v248, v250
	v_permlane16_swap_b32_e32 v249, v251
	global_store_dwordx4 v[238:239], v[248:251], off
	s_waitcnt vmcnt(22)
	v_lshlrev_b32_e32 v50, 16, v116
	v_add_f32_e32 v51, v194, v62
	v_mul_f32_e32 v50, v51, v50
	v_and_b32_e32 v51, 0xffff0000, v116
	v_add_f32_e32 v52, v194, v63
	v_mul_f32_e32 v51, v52, v51
	v_cvt_pk_bf16_f32 v252, v50, v51
	v_lshlrev_b32_e32 v51, 16, v117
	v_add_f32_e32 v52, v194, v64
	v_mul_f32_e32 v51, v52, v51
	v_and_b32_e32 v52, 0xffff0000, v117
	v_add_f32_e32 v53, v194, v65
	v_mul_f32_e32 v52, v53, v52
	v_cvt_pk_bf16_f32 v253, v51, v52
	s_waitcnt vmcnt(21)
	v_lshlrev_b32_e32 v50, 16, v114
	v_add_f32_e32 v46, v194, v46
	v_mul_f32_e32 v46, v46, v50
	v_and_b32_e32 v50, 0xffff0000, v114
	v_add_f32_e32 v47, v194, v47
	v_mul_f32_e32 v47, v47, v50
	v_cvt_pk_bf16_f32 v254, v46, v47
	v_lshlrev_b32_e32 v46, 16, v115
	v_add_f32_e32 v47, v194, v48
	v_mul_f32_e32 v46, v47, v46
	v_and_b32_e32 v47, 0xffff0000, v115
	v_add_f32_e32 v48, v194, v49
	v_mul_f32_e32 v47, v48, v47
	v_cvt_pk_bf16_f32 v255, v46, v47
	ds_read_b128 v[46:49], v183 offset:1024
	ds_read_b128 v[50:53], v183 offset:1088
	s_waitcnt lgkmcnt(1)
	v_mfma_f32_16x16x32_bf16 v[46:49], v[46:49], v[42:45], 0
	ds_read_b128 v[54:57], v183 offset:1568
	ds_read_b128 v[58:61], v183 offset:1152
	ds_read_b128 v[62:65], v183 offset:2112
	ds_read_b128 v[66:69], v183 offset:2176
	ds_read_b128 v[70:73], v183 offset:2656
	ds_read_b128 v[74:77], v183 offset:2240
	s_waitcnt lgkmcnt(5)
	v_mfma_f32_16x16x32_bf16 v[54:57], v[54:57], v[42:45], 0
	s_waitcnt lgkmcnt(3)
	v_mfma_f32_16x16x32_bf16 v[62:65], v[62:65], v[42:45], 0
	s_waitcnt lgkmcnt(1)
	v_mfma_f32_16x16x32_bf16 v[42:45], v[70:73], v[42:45], 0
	v_mfma_f32_16x16x32_bf16 v[46:49], v[50:53], v[34:37], v[46:49]
	ds_read_b128 v[50:53], v183 offset:1632
	ds_read_b128 v[70:73], v183 offset:1696
	s_waitcnt lgkmcnt(1)
	v_mfma_f32_16x16x32_bf16 v[50:53], v[50:53], v[34:37], v[54:57]
	v_mfma_f32_16x16x32_bf16 v[54:57], v[66:69], v[34:37], v[62:65]
	s_nop 2
	ds_read_b128 v[62:65], v183 offset:2720
	ds_read_b128 v[66:69], v183 offset:2784
	s_nop 1
	v_permlane16_swap_b32_e32 v252, v254
	v_permlane16_swap_b32_e32 v253, v255
	global_store_dwordx4 v[238:239], v[252:255], off offset:64
	s_waitcnt lgkmcnt(1)
	v_mfma_f32_16x16x32_bf16 v[34:37], v[62:65], v[34:37], v[42:45]
	v_mfma_f32_16x16x32_bf16 v[42:45], v[58:61], v[38:41], v[46:49]
	v_mfma_f32_16x16x32_bf16 v[46:49], v[70:73], v[38:41], v[50:53]
	v_mfma_f32_16x16x32_bf16 v[50:53], v[74:77], v[38:41], v[54:57]
	s_waitcnt lgkmcnt(0)
	v_mfma_f32_16x16x32_bf16 v[34:37], v[66:69], v[38:41], v[34:37]
	s_waitcnt vmcnt(21)
; __device__ __forceinline__ unsigned cvt_pk_bf16(float lo, float hi) { unsigned r; asm volatile("v_cvt_pk_bf16_f32 %0, %1, %2" : "=v"(r) : "v"(lo), "v"(hi)); return r; }
; __device__ __forceinline__ float bf_lo(unsigned w) { return __uint_as_float(w << 16); }
; __device__ __forceinline__ float bf_hi(unsigned w) { return __uint_as_float(w & 0xffff0000u); }
; #define LAS __attribute__((address_space(3)))
; __device__ __forceinline__ void sgu_unit(LAS unsigned char* lds, bf16* U, const bf16* VS, const float* SGS, const float* lnw, const float* lnb, const v4u* WF, const float* bsl, int unit, int tid) {
;     ...
;             for (int ks = 0; ks <= (mt >> 1); ++ks) {
;                 const int sb = 32 * ks + 8 * fq; const bf16x8_t wf = __builtin_bit_cast(bf16x8_t, wfr[q++]);
; #pragma unroll
;                 for (int nt = 0; nt < 4; ++nt) { const bf16x8_t vf = *(const LAS bf16x8_t*)(vt + ((fr >> 3) + 8 * (fr & 7) + 2 * nt) * SGU_VP + sb * 2);
;                     acc[nt] = __builtin_amdgcn_mfma_f32_16x16x32_bf16(vf, wf, acc[nt], 0, 0, 0); }
;             }
;             const float bb = bbv[mt];
; #pragma unroll
;             for (int nt = 0; nt < 4; ++nt) { const v2u u2 = uu[mt][nt]; v2u w; w.x = cvt_pk_bf16(bf_lo(u2.x) * (acc[nt][0] + bb), bf_hi(u2.x) * (acc[nt][1] + bb)); w.y = cvt_pk_bf16(bf_lo(u2.y) * (acc[nt][2] + bb), bf_hi(u2.y) * (acc[nt][3] + bb));
;                 *(v2u*)(U + (size_t)(r0 + t) * 1024 + colbase + 16 * nt + 4 * fq) = w; }
	v_lshlrev_b32_e32 v38, 16, v112
	s_nop 1
	v_add_f32_e32 v39, v193, v42
	v_mul_f32_e32 v38, v39, v38
	v_and_b32_e32 v39, 0xffff0000, v112
	v_add_f32_e32 v40, v193, v43
	v_mul_f32_e32 v39, v40, v39
	v_cvt_pk_bf16_f32 v248, v38, v39
	v_lshlrev_b32_e32 v39, 16, v113
	v_add_f32_e32 v40, v193, v44
	v_mul_f32_e32 v39, v40, v39
	v_and_b32_e32 v40, 0xffff0000, v113
	v_add_f32_e32 v41, v193, v45
	v_mul_f32_e32 v40, v41, v40
	v_cvt_pk_bf16_f32 v249, v39, v40
	v_lshl_add_u64 v[238:239], v[100:101], 0, v[236:237]
	s_waitcnt vmcnt(20)
	v_lshlrev_b32_e32 v38, 16, v108
	v_add_f32_e32 v39, v193, v46
	v_mul_f32_e32 v38, v39, v38
	v_and_b32_e32 v39, 0xffff0000, v108
	v_add_f32_e32 v40, v193, v47
	v_mul_f32_e32 v39, v40, v39
	v_cvt_pk_bf16_f32 v250, v38, v39
	v_lshlrev_b32_e32 v39, 16, v109
	v_add_f32_e32 v40, v193, v48
	v_mul_f32_e32 v39, v40, v39
	v_and_b32_e32 v40, 0xffff0000, v109
	v_add_f32_e32 v41, v193, v49
	v_mul_f32_e32 v40, v41, v40
	v_cvt_pk_bf16_f32 v251, v39, v40
	s_nop 1
	v_permlane16_swap_b32_e32 v248, v250
	v_permlane16_swap_b32_e32 v249, v251
	global_store_dwordx4 v[238:239], v[248:251], off
	s_waitcnt vmcnt(20)
	v_lshlrev_b32_e32 v38, 16, v106
	v_add_f32_e32 v39, v193, v50
	v_mul_f32_e32 v38, v39, v38
	v_and_b32_e32 v39, 0xffff0000, v106
	v_add_f32_e32 v40, v193, v51
	v_mul_f32_e32 v39, v40, v39
	v_cvt_pk_bf16_f32 v252, v38, v39
	v_lshlrev_b32_e32 v39, 16, v107
	v_add_f32_e32 v40, v193, v52
	v_mul_f32_e32 v39, v40, v39
	v_and_b32_e32 v40, 0xffff0000, v107
	v_add_f32_e32 v41, v193, v53
	v_mul_f32_e32 v40, v41, v40
	v_cvt_pk_bf16_f32 v253, v39, v40
	s_waitcnt vmcnt(19)
	v_lshlrev_b32_e32 v38, 16, v104
	v_add_f32_e32 v34, v193, v34
	v_mul_f32_e32 v34, v34, v38
	v_and_b32_e32 v38, 0xffff0000, v104
	v_add_f32_e32 v35, v193, v35
	v_mul_f32_e32 v35, v35, v38
	v_cvt_pk_bf16_f32 v254, v34, v35
	v_lshlrev_b32_e32 v34, 16, v105
	v_add_f32_e32 v35, v193, v36
	v_mul_f32_e32 v34, v35, v34
	v_and_b32_e32 v35, 0xffff0000, v105
	v_add_f32_e32 v36, v193, v37
	v_mul_f32_e32 v35, v36, v35
	v_cvt_pk_bf16_f32 v255, v34, v35
	ds_read_b128 v[34:37], v183 offset:1024
	ds_read_b128 v[38:41], v183 offset:1088
	ds_read_b128 v[42:45], v183 offset:1568
	ds_read_b128 v[46:49], v183 offset:1632
	ds_read_b128 v[50:53], v183 offset:2112
	ds_read_b128 v[54:57], v183 offset:2176
	ds_read_b128 v[58:61], v183 offset:2656
	ds_read_b128 v[62:65], v183 offset:2720
	s_waitcnt lgkmcnt(7)
	v_mfma_f32_16x16x32_bf16 v[34:37], v[34:37], v[30:33], 0
	s_waitcnt lgkmcnt(5)
	v_mfma_f32_16x16x32_bf16 v[42:45], v[42:45], v[30:33], 0
	s_waitcnt lgkmcnt(3)
	v_mfma_f32_16x16x32_bf16 v[50:53], v[50:53], v[30:33], 0
	s_waitcnt lgkmcnt(1)
	v_mfma_f32_16x16x32_bf16 v[30:33], v[58:61], v[30:33], 0
	v_mfma_f32_16x16x32_bf16 v[34:37], v[38:41], v[26:29], v[34:37]
	v_mfma_f32_16x16x32_bf16 v[38:41], v[46:49], v[26:29], v[42:45]
	v_mfma_f32_16x16x32_bf16 v[42:45], v[54:57], v[26:29], v[50:53]
	s_waitcnt lgkmcnt(0)
	v_mfma_f32_16x16x32_bf16 v[26:29], v[62:65], v[26:29], v[30:33]
	s_nop 2
	ds_read_b128 v[30:33], v183 offset:1152
	ds_read_b128 v[46:49], v183 offset:1216
	s_waitcnt lgkmcnt(1)
	v_mfma_f32_16x16x32_bf16 v[30:33], v[30:33], v[22:25], v[34:37]
	s_nop 2
	ds_read_b128 v[34:37], v183 offset:1696
	ds_read_b128 v[50:53], v183 offset:1760
	s_waitcnt lgkmcnt(1)
	v_mfma_f32_16x16x32_bf16 v[34:37], v[34:37], v[22:25], v[38:41]
	s_nop 2
	ds_read_b128 v[38:41], v183 offset:2240
	ds_read_b128 v[54:57], v183 offset:2304
	s_waitcnt lgkmcnt(1)
	v_mfma_f32_16x16x32_bf16 v[38:41], v[38:41], v[22:25], v[42:45]
	s_nop 2
	ds_read_b128 v[42:45], v183 offset:2784
	ds_read_b128 v[58:61], v183 offset:2848
	s_nop 1
	v_permlane16_swap_b32_e32 v252, v254
	v_permlane16_swap_b32_e32 v253, v255
	global_store_dwordx4 v[238:239], v[252:255], off offset:64
	s_waitcnt lgkmcnt(1)
	v_mfma_f32_16x16x32_bf16 v[22:25], v[42:45], v[22:25], v[26:29]
	v_mfma_f32_16x16x32_bf16 v[26:29], v[46:49], v[18:21], v[30:33]
	v_mfma_f32_16x16x32_bf16 v[30:33], v[50:53], v[18:21], v[34:37]
	v_mfma_f32_16x16x32_bf16 v[34:37], v[54:57], v[18:21], v[38:41]
	s_waitcnt lgkmcnt(0)
	v_mfma_f32_16x16x32_bf16 v[18:21], v[58:61], v[18:21], v[22:25]
	s_waitcnt vmcnt(19)
	s_nop 1
	v_lshlrev_b32_e32 v22, 16, v102
	v_add_f32_e32 v23, v192, v26
	v_mul_f32_e32 v22, v23, v22
	v_and_b32_e32 v23, 0xffff0000, v102
	v_add_f32_e32 v24, v192, v27
	v_mul_f32_e32 v23, v24, v23
	v_cvt_pk_bf16_f32 v248, v22, v23
	v_lshlrev_b32_e32 v23, 16, v103
	v_add_f32_e32 v24, v192, v28
	v_mul_f32_e32 v23, v24, v23
	v_and_b32_e32 v24, 0xffff0000, v103
	v_add_f32_e32 v25, v192, v29
	v_mul_f32_e32 v24, v25, v24
	v_cvt_pk_bf16_f32 v249, v23, v24
	v_lshl_add_u64 v[238:239], v[90:91], 0, v[236:237]
	s_waitcnt vmcnt(18)
	v_lshlrev_b32_e32 v22, 16, v98
	v_add_f32_e32 v23, v192, v30
	v_mul_f32_e32 v22, v23, v22
	v_and_b32_e32 v23, 0xffff0000, v98
	v_add_f32_e32 v24, v192, v31
	v_mul_f32_e32 v23, v24, v23
	v_cvt_pk_bf16_f32 v250, v22, v23
	v_lshlrev_b32_e32 v23, 16, v99
	v_add_f32_e32 v24, v192, v32
	v_mul_f32_e32 v23, v24, v23
	v_and_b32_e32 v24, 0xffff0000, v99
	v_add_f32_e32 v25, v192, v33
	v_mul_f32_e32 v24, v25, v24
	v_cvt_pk_bf16_f32 v251, v23, v24
	s_nop 1
	v_permlane16_swap_b32_e32 v248, v250
	v_permlane16_swap_b32_e32 v249, v251
	global_store_dwordx4 v[238:239], v[248:251], off
	s_waitcnt vmcnt(18)
; __device__ __forceinline__ unsigned cvt_pk_bf16(float lo, float hi) { unsigned r; asm volatile("v_cvt_pk_bf16_f32 %0, %1, %2" : "=v"(r) : "v"(lo), "v"(hi)); return r; }
; __device__ __forceinline__ float bf_lo(unsigned w) { return __uint_as_float(w << 16); }
; __device__ __forceinline__ float bf_hi(unsigned w) { return __uint_as_float(w & 0xffff0000u); }
; #define LAS __attribute__((address_space(3)))
; __device__ __forceinline__ void sgu_unit(LAS unsigned char* lds, bf16* U, const bf16* VS, const float* SGS, const float* lnw, const float* lnb, const v4u* WF, const float* bsl, int unit, int tid) {
;     ...
;             for (int ks = 0; ks <= (mt >> 1); ++ks) {
;                 const int sb = 32 * ks + 8 * fq; const bf16x8_t wf = __builtin_bit_cast(bf16x8_t, wfr[q++]);
; #pragma unroll
;                 for (int nt = 0; nt < 4; ++nt) { const bf16x8_t vf = *(const LAS bf16x8_t*)(vt + ((fr >> 3) + 8 * (fr & 7) + 2 * nt) * SGU_VP + sb * 2);
;                     acc[nt] = __builtin_amdgcn_mfma_f32_16x16x32_bf16(vf, wf, acc[nt], 0, 0, 0); }
;             }
;             const float bb = bbv[mt];
; #pragma unroll
;             for (int nt = 0; nt < 4; ++nt) { const v2u u2 = uu[mt][nt]; v2u w; w.x = cvt_pk_bf16(bf_lo(u2.x) * (acc[nt][0] + bb), bf_hi(u2.x) * (acc[nt][1] + bb)); w.y = cvt_pk_bf16(bf_lo(u2.y) * (acc[nt][2] + bb), bf_hi(u2.y) * (acc[nt][3] + bb));
;                 *(v2u*)(U + (size_t)(r0 + t) * 1024 + colbase + 16 * nt + 4 * fq) = w; }
;         }
;     }
;     __syncthreads();
	v_lshlrev_b32_e32 v22, 16, v96
	v_add_f32_e32 v23, v192, v34
	v_mul_f32_e32 v22, v23, v22
	v_and_b32_e32 v23, 0xffff0000, v96
	v_add_f32_e32 v24, v192, v35
	v_mul_f32_e32 v23, v24, v23
	v_cvt_pk_bf16_f32 v252, v22, v23
	v_lshlrev_b32_e32 v23, 16, v97
	v_add_f32_e32 v24, v192, v36
	v_mul_f32_e32 v23, v24, v23
	v_and_b32_e32 v24, 0xffff0000, v97
	v_add_f32_e32 v25, v192, v37
	v_mul_f32_e32 v24, v25, v24
	v_cvt_pk_bf16_f32 v253, v23, v24
	s_waitcnt vmcnt(17)
	v_lshlrev_b32_e32 v22, 16, v94
	v_add_f32_e32 v18, v192, v18
	v_mul_f32_e32 v18, v18, v22
	v_and_b32_e32 v22, 0xffff0000, v94
	v_add_f32_e32 v19, v192, v19
	v_mul_f32_e32 v19, v19, v22
	v_cvt_pk_bf16_f32 v254, v18, v19
	v_lshlrev_b32_e32 v18, 16, v95
	v_add_f32_e32 v19, v192, v20
	v_mul_f32_e32 v18, v19, v18
	v_and_b32_e32 v19, 0xffff0000, v95
	v_add_f32_e32 v20, v192, v21
	v_mul_f32_e32 v19, v20, v19
	v_cvt_pk_bf16_f32 v255, v18, v19
	ds_read_b128 v[18:21], v183 offset:1024
	ds_read_b128 v[22:25], v183 offset:1088
	ds_read_b128 v[26:29], v183 offset:1568
	ds_read_b128 v[30:33], v183 offset:1632
	ds_read_b128 v[34:37], v183 offset:2112
	ds_read_b128 v[38:41], v183 offset:2176
	ds_read_b128 v[42:45], v183 offset:2656
	ds_read_b128 v[46:49], v183 offset:2720
	s_waitcnt lgkmcnt(7)
	v_mfma_f32_16x16x32_bf16 v[18:21], v[18:21], v[14:17], 0
	s_waitcnt lgkmcnt(5)
	v_mfma_f32_16x16x32_bf16 v[26:29], v[26:29], v[14:17], 0
	s_waitcnt lgkmcnt(3)
	v_mfma_f32_16x16x32_bf16 v[34:37], v[34:37], v[14:17], 0
	s_waitcnt lgkmcnt(1)
	v_mfma_f32_16x16x32_bf16 v[14:17], v[42:45], v[14:17], 0
	v_mfma_f32_16x16x32_bf16 v[18:21], v[22:25], v[10:13], v[18:21]
	v_mfma_f32_16x16x32_bf16 v[22:25], v[30:33], v[10:13], v[26:29]
	v_mfma_f32_16x16x32_bf16 v[26:29], v[38:41], v[10:13], v[34:37]
	s_waitcnt lgkmcnt(0)
	v_mfma_f32_16x16x32_bf16 v[10:13], v[46:49], v[10:13], v[14:17]
	s_nop 2
	ds_read_b128 v[14:17], v183 offset:1152
	ds_read_b128 v[30:33], v183 offset:1216
	s_waitcnt lgkmcnt(1)
	v_mfma_f32_16x16x32_bf16 v[14:17], v[14:17], v[6:9], v[18:21]
	s_nop 2
	ds_read_b128 v[18:21], v183 offset:1696
	ds_read_b128 v[34:37], v183 offset:1760
	s_waitcnt lgkmcnt(1)
	v_mfma_f32_16x16x32_bf16 v[18:21], v[18:21], v[6:9], v[22:25]
	s_nop 2
	ds_read_b128 v[22:25], v183 offset:2240
	ds_read_b128 v[38:41], v183 offset:2304
	s_waitcnt lgkmcnt(1)
	v_mfma_f32_16x16x32_bf16 v[22:25], v[22:25], v[6:9], v[26:29]
	s_nop 2
	ds_read_b128 v[26:29], v183 offset:2784
	ds_read_b128 v[42:45], v183 offset:2848
	s_nop 1
	v_permlane16_swap_b32_e32 v252, v254
	v_permlane16_swap_b32_e32 v253, v255
	global_store_dwordx4 v[238:239], v[252:255], off offset:64
	s_waitcnt lgkmcnt(1)
	v_mfma_f32_16x16x32_bf16 v[6:9], v[26:29], v[6:9], v[10:13]
	v_mfma_f32_16x16x32_bf16 v[10:13], v[30:33], v[2:5], v[14:17]
	v_mfma_f32_16x16x32_bf16 v[14:17], v[34:37], v[2:5], v[18:21]
	v_mfma_f32_16x16x32_bf16 v[18:21], v[38:41], v[2:5], v[22:25]
	s_waitcnt lgkmcnt(0)
	v_mfma_f32_16x16x32_bf16 v[2:5], v[42:45], v[2:5], v[6:9]
	s_waitcnt vmcnt(17)
	s_nop 1
	v_lshlrev_b32_e32 v6, 16, v92
	v_add_f32_e32 v7, v157, v10
	v_mul_f32_e32 v6, v7, v6
	v_and_b32_e32 v7, 0xffff0000, v92
	v_add_f32_e32 v8, v157, v11
	v_mul_f32_e32 v7, v8, v7
	v_cvt_pk_bf16_f32 v248, v6, v7
	v_lshlrev_b32_e32 v7, 16, v93
	v_add_f32_e32 v8, v157, v12
	v_mul_f32_e32 v7, v8, v7
	v_and_b32_e32 v8, 0xffff0000, v93
	v_add_f32_e32 v9, v157, v13
	v_mul_f32_e32 v8, v9, v8
	v_cvt_pk_bf16_f32 v249, v7, v8
	v_lshl_add_u64 v[238:239], v[82:83], 0, v[236:237]
	s_waitcnt vmcnt(16)
	v_lshlrev_b32_e32 v6, 16, v88
	v_add_f32_e32 v7, v157, v14
	v_mul_f32_e32 v6, v7, v6
	v_and_b32_e32 v7, 0xffff0000, v88
	v_add_f32_e32 v8, v157, v15
	v_mul_f32_e32 v7, v8, v7
	v_cvt_pk_bf16_f32 v250, v6, v7
	v_lshlrev_b32_e32 v7, 16, v89
	v_add_f32_e32 v8, v157, v16
	v_mul_f32_e32 v7, v8, v7
	v_and_b32_e32 v8, 0xffff0000, v89
	v_add_f32_e32 v9, v157, v17
	v_mul_f32_e32 v8, v9, v8
	v_cvt_pk_bf16_f32 v251, v7, v8
	s_nop 1
	v_permlane16_swap_b32_e32 v248, v250
	v_permlane16_swap_b32_e32 v249, v251
	global_store_dwordx4 v[238:239], v[248:251], off
	s_waitcnt vmcnt(16)
	v_lshlrev_b32_e32 v6, 16, v86
	v_add_f32_e32 v7, v157, v18
	v_mul_f32_e32 v6, v7, v6
	v_and_b32_e32 v7, 0xffff0000, v86
	v_add_f32_e32 v8, v157, v19
	v_mul_f32_e32 v7, v8, v7
	v_cvt_pk_bf16_f32 v252, v6, v7
	v_lshlrev_b32_e32 v7, 16, v87
	v_add_f32_e32 v8, v157, v20
	v_mul_f32_e32 v7, v8, v7
	v_and_b32_e32 v8, 0xffff0000, v87
	v_add_f32_e32 v9, v157, v21
	v_mul_f32_e32 v8, v9, v8
	v_cvt_pk_bf16_f32 v253, v7, v8
	s_waitcnt vmcnt(15)
	v_lshlrev_b32_e32 v6, 16, v84
	v_add_f32_e32 v2, v157, v2
	v_mul_f32_e32 v2, v2, v6
	v_and_b32_e32 v6, 0xffff0000, v84
	v_add_f32_e32 v3, v157, v3
	v_mul_f32_e32 v3, v3, v6
	v_cvt_pk_bf16_f32 v254, v2, v3
	v_lshlrev_b32_e32 v3, 16, v85
	v_add_f32_e32 v4, v157, v4
	v_mul_f32_e32 v3, v4, v3
	v_and_b32_e32 v4, 0xffff0000, v85
	v_add_f32_e32 v5, v157, v5
	v_mul_f32_e32 v4, v5, v4
	v_cvt_pk_bf16_f32 v255, v3, v4
	s_nop 1
	v_permlane16_swap_b32_e32 v252, v254
	v_permlane16_swap_b32_e32 v253, v255
	global_store_dwordx4 v[238:239], v[252:255], off offset:64
	s_barrier

; __device__ __forceinline__ unsigned cvt_pk_bf16(float lo, float hi) { unsigned r; asm volatile("v_cvt_pk_bf16_f32 %0, %1, %2" : "=v"(r) : "v"(lo), "v"(hi)); return r; }
; __device__ __forceinline__ float bf_lo(unsigned w) { return __uint_as_float(w << 16); }
; __device__ __forceinline__ float bf_hi(unsigned w) { return __uint_as_float(w & 0xffff0000u); }
; #define LAS __attribute__((address_space(3)))
; __device__ __forceinline__ void sgu_unit(LAS unsigned char* lds, bf16* U, const bf16* VS, const float* SGS, const float* lnw, const float* lnb, const v4u* WF, const float* bsl, int unit, int tid) {
;     ...
;         const int c8 = lane & 7, rp = lane >> 3, col = colbase + 8 * c8;
;         v4u sl[8][2];
; #pragma unroll
;         for (int i = 0; i < 8; ++i) { const int s0 = 2 * (rp + 8 * i); sl[i][0] = *(const v4u*)(VS + (size_t)(r0 + s0) * 1024 + col); sl[i][1] = *(const v4u*)(VS + (size_t)(r0 + s0 + 1) * 1024 + col); }
;         const f32x4 lw0 = *(const f32x4*)(lnw + col), lw1 = *(const f32x4*)(lnw + col + 4), lb0 = *(const f32x4*)(lnb + col), lb1 = *(const f32x4*)(lnb + col + 4);
;         const float lw[8] = {lw0.x, lw0.y, lw0.z, lw0.w, lw1.x, lw1.y, lw1.z, lw1.w}, lb[8] = {lb0.x, lb0.y, lb0.z, lb0.w, lb1.x, lb1.y, lb1.z, lb1.w};
;         __syncthreads();
;         LAS unsigned char* wbase = vt + c8 * SGU_VP + rp * 4;
; #pragma unroll
;         for (int i = 0; i < 8; ++i) {
;             const f32x4 st4 = *(const LAS f32x4*)(stat + 4 * (rp + 8 * i));
;             const v4u w0 = sl[i][0], w1 = sl[i][1];
;             const unsigned A0[4] = {w0.x, w0.y, w0.z, w0.w}, A1[4] = {w1.x, w1.y, w1.z, w1.w};
; #pragma unroll
;             for (int e = 0; e < 8; ++e) { typedef float f32x2p __attribute__((ext_vector_type(2)));
;                 f32x2p v; v.x = (e & 1) ? bf_hi(A0[e >> 1]) : bf_lo(A0[e >> 1]); v.y = (e & 1) ? bf_hi(A1[e >> 1]) : bf_lo(A1[e >> 1]);
;                 const f32x2p mn = {st4.x, st4.z}, rs = {st4.y, st4.w};
;                 const f32x2p o = ((v - mn) * rs) * lw[e] + lb[e];
;                 *(LAS unsigned*)(wbase + e * 8 * SGU_VP + i * 32) = cvt_pk_bf16(o.x, o.y); }
;         }
.LBB0_1401:
	s_or_b64 exec, exec, s[16:17]
	v_mov_b32_e32 v122, v214
	v_mov_b32_e32 v123, v215
	v_mov_b32_e32 v124, v216
	v_mov_b32_e32 v125, v217
	v_mov_b32_e32 v126, v218
	v_mov_b32_e32 v127, v219
	v_mov_b32_e32 v128, v220
	v_mov_b32_e32 v129, v221
	v_mov_b32_e32 v114, v222
	v_mov_b32_e32 v115, v223
	v_mov_b32_e32 v116, v224
	v_mov_b32_e32 v117, v225
	v_mov_b32_e32 v118, v226
	v_mov_b32_e32 v119, v227
	v_mov_b32_e32 v120, v228
	v_mov_b32_e32 v121, v229
	v_mov_b32_e32 v106, v230
	v_mov_b32_e32 v107, v231
	v_mov_b32_e32 v108, v232
	v_mov_b32_e32 v109, v233
	v_mov_b32_e32 v110, v234
	v_mov_b32_e32 v111, v235
	v_mov_b32_e32 v112, v236
	v_mov_b32_e32 v113, v237
	v_or_b32_e32 v158, v82, v168
	v_or_b32_e32 v82, v158, v170
	v_lshl_or_b32 v84, s18, 11, v180
	v_mov_b32_e32 v85, v147
	v_ashrrev_i32_e32 v83, 31, v82
	v_lshl_add_u64 v[84:85], s[38:39], 0, v[84:85]
	v_lshl_add_u64 v[90:91], v[82:83], 1, v[84:85]
	v_lshlrev_b64 v[82:83], 2, v[82:83]
	v_lshl_add_u64 v[84:85], s[30:31], 0, v[82:83]
	v_lshl_add_u64 v[86:87], s[40:41], 0, v[82:83]
	global_load_dwordx4 v[98:101], v[86:87], off
	global_load_dwordx4 v[102:105], v[84:85], off
	s_nop 0
	global_load_dwordx4 v[82:85], v[84:85], off offset:16
	s_nop 0
	global_load_dwordx4 v[86:89], v[86:87], off offset:16
	v_add_co_u32_e32 v92, vcc, 0x8000, v90
	s_mov_b64 s[16:17], 0
	s_nop 0
	v_addc_co_u32_e32 v93, vcc, 0, v91, vcc
	v_add_co_u32_e32 v94, vcc, 0x10000, v90
	s_waitcnt vmcnt(7)
	v_and_b32_e32 v220, 0xffff0000, v198
	v_addc_co_u32_e32 v95, vcc, 0, v91, vcc
	v_add_co_u32_e32 v92, vcc, 0x18000, v90
	s_waitcnt vmcnt(8)
	v_and_b32_e32 v221, 0xffff0000, v202
	v_addc_co_u32_e32 v93, vcc, 0, v91, vcc
	v_add_co_u32_e32 v94, vcc, 0x20000, v90
	v_addc_co_u32_e32 v95, vcc, 0, v91, vcc
	v_add_co_u32_e32 v92, vcc, 0x28000, v90
	v_addc_co_u32_e32 v93, vcc, 0, v91, vcc
	v_add_co_u32_e32 v94, vcc, 0x30000, v90
	v_addc_co_u32_e32 v95, vcc, 0, v91, vcc
	v_add_co_u32_e32 v96, vcc, 0x38000, v90
	v_addc_co_u32_e32 v97, vcc, 0, v91, vcc
	v_mov_b32_e32 v90, v248
	v_mov_b32_e32 v91, v249
	v_mov_b32_e32 v92, v250
	v_mov_b32_e32 v93, v251
	s_nop 0
	v_mov_b32_e32 v94, v252
	v_mov_b32_e32 v95, v253
	v_mov_b32_e32 v96, v254
	v_mov_b32_e32 v97, v255
	s_waitcnt lgkmcnt(0)
	s_barrier
	ds_read_b128 v[214:217], v181
	v_lshlrev_b32_e32 v222, 16, v199
	v_lshlrev_b32_e32 v223, 16, v203
	s_waitcnt vmcnt(2)
	v_mov_b32_e32 v160, v105
	v_mov_b32_e32 v162, v101
	s_waitcnt lgkmcnt(0)
	v_mov_b32_e32 v218, v214
	v_mov_b32_e32 v219, v216
	v_mov_b32_e32 v216, v215
	v_lshlrev_b32_e32 v214, 16, v198
	v_lshlrev_b32_e32 v215, 16, v202
	v_pk_add_f32 v[214:215], v[214:215], v[218:219] neg_lo:[0,1] neg_hi:[0,1]
	v_and_b32_e32 v198, 0xffff0000, v199
	v_and_b32_e32 v199, 0xffff0000, v203
	v_pk_add_f32 v[220:221], v[220:221], v[218:219] neg_lo:[0,1] neg_hi:[0,1]
	v_pk_mul_f32 v[214:215], v[216:217], v[214:215]
	v_pk_add_f32 v[198:199], v[198:199], v[218:219] neg_lo:[0,1] neg_hi:[0,1]
	v_pk_add_f32 v[222:223], v[222:223], v[218:219] neg_lo:[0,1] neg_hi:[0,1]
	v_pk_mul_f32 v[220:221], v[216:217], v[220:221]
	v_pk_fma_f32 v[214:215], v[102:103], v[214:215], v[98:99] op_sel_hi:[0,1,0]
	v_cvt_pk_bf16_f32 v159, v214, v215
	v_pk_mul_f32 v[198:199], v[216:217], v[198:199]
	v_pk_mul_f32 v[222:223], v[216:217], v[222:223]
	v_pk_fma_f32 v[220:221], v[102:103], v[220:221], v[98:99] op_sel:[1,0,1]
	ds_write_b32 v177, v159 offset:1024
	v_cvt_pk_bf16_f32 v159, v220, v221
	v_pk_fma_f32 v[198:199], v[160:161], v[198:199], v[162:163] op_sel_hi:[0,1,0]
	v_pk_fma_f32 v[222:223], v[104:105], v[222:223], v[100:101] op_sel_hi:[0,1,0]
	ds_write_b32 v177, v159 offset:3200
	v_cvt_pk_bf16_f32 v159, v222, v223
	ds_write_b32 v177, v159 offset:5376
	v_cvt_pk_bf16_f32 v101, v198, v199
	v_lshlrev_b32_e32 v198, 16, v200
	v_lshlrev_b32_e32 v199, 16, v204
	v_pk_add_f32 v[198:199], v[198:199], v[218:219] neg_lo:[0,1] neg_hi:[0,1]
	ds_write_b32 v177, v101 offset:7552
	v_pk_mul_f32 v[198:199], v[216:217], v[198:199]
	s_waitcnt vmcnt(1)
	v_mov_b32_e32 v164, v85
	s_waitcnt vmcnt(0)
	v_pk_fma_f32 v[198:199], v[82:83], v[198:199], v[86:87] op_sel_hi:[0,1,0]
	v_cvt_pk_bf16_f32 v101, v198, v199
	v_and_b32_e32 v198, 0xffff0000, v200
	v_and_b32_e32 v199, 0xffff0000, v204
	v_pk_add_f32 v[198:199], v[198:199], v[218:219] neg_lo:[0,1] neg_hi:[0,1]
	ds_write_b32 v177, v101 offset:9728
	v_pk_mul_f32 v[198:199], v[216:217], v[198:199]
	v_mov_b32_e32 v166, v89
	v_pk_fma_f32 v[198:199], v[82:83], v[198:199], v[86:87] op_sel:[1,0,1]
	v_ashrrev_i32_e32 v159, 31, v158
	v_cvt_pk_bf16_f32 v101, v198, v199
	v_lshlrev_b32_e32 v198, 16, v201
	v_lshlrev_b32_e32 v199, 16, v205
	v_pk_add_f32 v[198:199], v[198:199], v[218:219] neg_lo:[0,1] neg_hi:[0,1]
	ds_write_b32 v177, v101 offset:11904
	v_pk_mul_f32 v[198:199], v[216:217], v[198:199]
	s_nop 0
	v_pk_fma_f32 v[198:199], v[84:85], v[198:199], v[88:89] op_sel_hi:[0,1,0]
	v_cvt_pk_bf16_f32 v101, v198, v199
	v_and_b32_e32 v198, 0xffff0000, v201
	v_and_b32_e32 v199, 0xffff0000, v205
	v_pk_add_f32 v[198:199], v[198:199], v[218:219] neg_lo:[0,1] neg_hi:[0,1]
	ds_write_b32 v177, v101 offset:14080
	v_pk_mul_f32 v[198:199], v[216:217], v[198:199]
	s_nop 0
	v_pk_fma_f32 v[198:199], v[164:165], v[198:199], v[166:167] op_sel_hi:[0,1,0]
	v_cvt_pk_bf16_f32 v85, v198, v199
	ds_write_b32 v177, v85 offset:16256
	ds_read_b128 v[198:201], v181 offset:128
	s_waitcnt lgkmcnt(0)
	v_mov_b32_e32 v202, v198
	v_mov_b32_e32 v203, v200
	v_mov_b32_e32 v200, v199
	s_waitcnt vmcnt(13)
	v_lshlrev_b32_e32 v198, 16, v206
	s_waitcnt vmcnt(12)
; __device__ __forceinline__ unsigned cvt_pk_bf16(float lo, float hi) { unsigned r; asm volatile("v_cvt_pk_bf16_f32 %0, %1, %2" : "=v"(r) : "v"(lo), "v"(hi)); return r; }
; __device__ __forceinline__ float bf_lo(unsigned w) { return __uint_as_float(w << 16); }
; __device__ __forceinline__ float bf_hi(unsigned w) { return __uint_as_float(w & 0xffff0000u); }
; #define LAS __attribute__((address_space(3)))
; __device__ __forceinline__ void sgu_unit(LAS unsigned char* lds, bf16* U, const bf16* VS, const float* SGS, const float* lnw, const float* lnb, const v4u* WF, const float* bsl, int unit, int tid) {
;     ...
;         for (int i = 0; i < 8; ++i) {
;             const f32x4 st4 = *(const LAS f32x4*)(stat + 4 * (rp + 8 * i));
;             const v4u w0 = sl[i][0], w1 = sl[i][1];
;             const unsigned A0[4] = {w0.x, w0.y, w0.z, w0.w}, A1[4] = {w1.x, w1.y, w1.z, w1.w};
; #pragma unroll
;             for (int e = 0; e < 8; ++e) { typedef float f32x2p __attribute__((ext_vector_type(2)));
;                 f32x2p v; v.x = (e & 1) ? bf_hi(A0[e >> 1]) : bf_lo(A0[e >> 1]); v.y = (e & 1) ? bf_hi(A1[e >> 1]) : bf_lo(A1[e >> 1]);
;                 const f32x2p mn = {st4.x, st4.z}, rs = {st4.y, st4.w};
;                 const f32x2p o = ((v - mn) * rs) * lw[e] + lb[e];
;                 *(LAS unsigned*)(wbase + e * 8 * SGU_VP + i * 32) = cvt_pk_bf16(o.x, o.y); }
;         }
	v_lshlrev_b32_e32 v199, 16, v210
	v_pk_add_f32 v[198:199], v[198:199], v[202:203] neg_lo:[0,1] neg_hi:[0,1]
	s_nop 0
	v_pk_mul_f32 v[198:199], v[200:201], v[198:199]
	s_nop 0
	v_pk_fma_f32 v[198:199], v[102:103], v[198:199], v[98:99] op_sel_hi:[0,1,0]
	v_cvt_pk_bf16_f32 v85, v198, v199
	v_and_b32_e32 v198, 0xffff0000, v206
	v_and_b32_e32 v199, 0xffff0000, v210
	v_pk_add_f32 v[198:199], v[198:199], v[202:203] neg_lo:[0,1] neg_hi:[0,1]
	ds_write_b32 v177, v85 offset:1056
	v_pk_mul_f32 v[198:199], v[200:201], v[198:199]
	s_nop 0
	v_pk_fma_f32 v[198:199], v[102:103], v[198:199], v[98:99] op_sel:[1,0,1]
	s_nop 0
	v_cvt_pk_bf16_f32 v85, v198, v199
	v_lshlrev_b32_e32 v198, 16, v207
	v_lshlrev_b32_e32 v199, 16, v211
	v_pk_add_f32 v[198:199], v[198:199], v[202:203] neg_lo:[0,1] neg_hi:[0,1]
	ds_write_b32 v177, v85 offset:3232
	v_pk_mul_f32 v[198:199], v[200:201], v[198:199]
	s_nop 0
	v_pk_fma_f32 v[198:199], v[104:105], v[198:199], v[100:101] op_sel_hi:[0,1,0]
	v_cvt_pk_bf16_f32 v85, v198, v199
	v_and_b32_e32 v198, 0xffff0000, v207
	v_and_b32_e32 v199, 0xffff0000, v211
	v_pk_add_f32 v[198:199], v[198:199], v[202:203] neg_lo:[0,1] neg_hi:[0,1]
	ds_write_b32 v177, v85 offset:5408
	v_pk_mul_f32 v[198:199], v[200:201], v[198:199]
	s_nop 0
	v_pk_fma_f32 v[198:199], v[160:161], v[198:199], v[162:163] op_sel_hi:[0,1,0]
	v_cvt_pk_bf16_f32 v85, v198, v199
	v_lshlrev_b32_e32 v198, 16, v208
	v_lshlrev_b32_e32 v199, 16, v212
	v_pk_add_f32 v[198:199], v[198:199], v[202:203] neg_lo:[0,1] neg_hi:[0,1]
	ds_write_b32 v177, v85 offset:7584
	v_pk_mul_f32 v[198:199], v[200:201], v[198:199]
	s_nop 0
	v_pk_fma_f32 v[198:199], v[82:83], v[198:199], v[86:87] op_sel_hi:[0,1,0]
	v_cvt_pk_bf16_f32 v85, v198, v199
	v_and_b32_e32 v198, 0xffff0000, v208
	v_and_b32_e32 v199, 0xffff0000, v212
	v_pk_add_f32 v[198:199], v[198:199], v[202:203] neg_lo:[0,1] neg_hi:[0,1]
	ds_write_b32 v177, v85 offset:9760
	v_pk_mul_f32 v[198:199], v[200:201], v[198:199]
	s_nop 0
	v_pk_fma_f32 v[198:199], v[82:83], v[198:199], v[86:87] op_sel:[1,0,1]
	s_nop 0
	v_cvt_pk_bf16_f32 v85, v198, v199
	v_lshlrev_b32_e32 v198, 16, v209
	v_lshlrev_b32_e32 v199, 16, v213
	v_pk_add_f32 v[198:199], v[198:199], v[202:203] neg_lo:[0,1] neg_hi:[0,1]
	ds_write_b32 v177, v85 offset:11936
	v_pk_mul_f32 v[198:199], v[200:201], v[198:199]
	s_nop 0
	v_pk_fma_f32 v[198:199], v[84:85], v[198:199], v[88:89] op_sel_hi:[0,1,0]
	v_cvt_pk_bf16_f32 v85, v198, v199
	v_and_b32_e32 v198, 0xffff0000, v209
	v_and_b32_e32 v199, 0xffff0000, v213
	v_pk_add_f32 v[198:199], v[198:199], v[202:203] neg_lo:[0,1] neg_hi:[0,1]
	ds_write_b32 v177, v85 offset:14112
	v_pk_mul_f32 v[198:199], v[200:201], v[198:199]
	s_nop 0
	v_pk_fma_f32 v[198:199], v[164:165], v[198:199], v[166:167] op_sel_hi:[0,1,0]
	v_cvt_pk_bf16_f32 v85, v198, v199
	ds_write_b32 v177, v85 offset:16288
	ds_read_b128 v[198:201], v181 offset:256
	s_waitcnt lgkmcnt(0)
	v_mov_b32_e32 v202, v198
	v_mov_b32_e32 v203, v200
	v_mov_b32_e32 v200, v199
	s_waitcnt vmcnt(11)
	v_lshlrev_b32_e32 v198, 16, v138
	s_waitcnt vmcnt(10)
	v_lshlrev_b32_e32 v199, 16, v142
	v_pk_add_f32 v[198:199], v[198:199], v[202:203] neg_lo:[0,1] neg_hi:[0,1]
	s_nop 0
	v_pk_mul_f32 v[198:199], v[200:201], v[198:199]
	s_nop 0
	v_pk_fma_f32 v[198:199], v[102:103], v[198:199], v[98:99] op_sel_hi:[0,1,0]
	v_cvt_pk_bf16_f32 v85, v198, v199
	v_and_b32_e32 v198, 0xffff0000, v138
	v_and_b32_e32 v199, 0xffff0000, v142
	v_pk_add_f32 v[198:199], v[198:199], v[202:203] neg_lo:[0,1] neg_hi:[0,1]
	ds_write_b32 v177, v85 offset:1088
	v_pk_mul_f32 v[198:199], v[200:201], v[198:199]
	v_and_b32_e32 v138, 0xffff0000, v139
	v_pk_fma_f32 v[198:199], v[102:103], v[198:199], v[98:99] op_sel:[1,0,1]
	s_nop 0
	v_cvt_pk_bf16_f32 v85, v198, v199
	v_lshlrev_b32_e32 v198, 16, v139
	v_lshlrev_b32_e32 v199, 16, v143
	v_and_b32_e32 v139, 0xffff0000, v143
	v_pk_add_f32 v[198:199], v[198:199], v[202:203] neg_lo:[0,1] neg_hi:[0,1]
	v_pk_add_f32 v[138:139], v[138:139], v[202:203] neg_lo:[0,1] neg_hi:[0,1]
	v_pk_mul_f32 v[198:199], v[200:201], v[198:199]
	v_pk_mul_f32 v[138:139], v[200:201], v[138:139]
	ds_write_b32 v177, v85 offset:3264
	v_pk_fma_f32 v[198:199], v[104:105], v[198:199], v[100:101] op_sel_hi:[0,1,0]
	v_cvt_pk_bf16_f32 v85, v198, v199
	v_pk_fma_f32 v[138:139], v[160:161], v[138:139], v[162:163] op_sel_hi:[0,1,0]
	ds_write_b32 v177, v85 offset:5440
	v_cvt_pk_bf16_f32 v85, v138, v139
	v_lshlrev_b32_e32 v138, 16, v140
	v_lshlrev_b32_e32 v139, 16, v144
	v_pk_add_f32 v[138:139], v[138:139], v[202:203] neg_lo:[0,1] neg_hi:[0,1]
	ds_write_b32 v177, v85 offset:7616
	v_pk_mul_f32 v[138:139], v[200:201], v[138:139]
	s_nop 0
	v_pk_fma_f32 v[138:139], v[82:83], v[138:139], v[86:87] op_sel_hi:[0,1,0]
	v_cvt_pk_bf16_f32 v85, v138, v139
	v_and_b32_e32 v138, 0xffff0000, v140
	v_and_b32_e32 v139, 0xffff0000, v144
	v_pk_add_f32 v[138:139], v[138:139], v[202:203] neg_lo:[0,1] neg_hi:[0,1]
	ds_write_b32 v177, v85 offset:9792
	v_pk_mul_f32 v[138:139], v[200:201], v[138:139]
	s_nop 0
	v_pk_fma_f32 v[138:139], v[82:83], v[138:139], v[86:87] op_sel:[1,0,1]
	s_nop 0
	v_cvt_pk_bf16_f32 v85, v138, v139
	v_lshlrev_b32_e32 v138, 16, v141
	v_lshlrev_b32_e32 v139, 16, v145
	v_pk_add_f32 v[138:139], v[138:139], v[202:203] neg_lo:[0,1] neg_hi:[0,1]
	ds_write_b32 v177, v85 offset:11968
	v_pk_mul_f32 v[138:139], v[200:201], v[138:139]
	s_nop 0
	v_pk_fma_f32 v[138:139], v[84:85], v[138:139], v[88:89] op_sel_hi:[0,1,0]
	v_cvt_pk_bf16_f32 v85, v138, v139
	v_and_b32_e32 v138, 0xffff0000, v141
	v_and_b32_e32 v139, 0xffff0000, v145
	v_pk_add_f32 v[138:139], v[138:139], v[202:203] neg_lo:[0,1] neg_hi:[0,1]
	ds_write_b32 v177, v85 offset:14144
	v_pk_mul_f32 v[138:139], v[200:201], v[138:139]
	s_nop 0
	v_pk_fma_f32 v[138:139], v[164:165], v[138:139], v[166:167] op_sel_hi:[0,1,0]
	v_cvt_pk_bf16_f32 v85, v138, v139
	ds_write_b32 v177, v85 offset:16320
	ds_read_b128 v[138:141], v181 offset:384
	s_waitcnt lgkmcnt(0)
; __device__ __forceinline__ unsigned cvt_pk_bf16(float lo, float hi) { unsigned r; asm volatile("v_cvt_pk_bf16_f32 %0, %1, %2" : "=v"(r) : "v"(lo), "v"(hi)); return r; }
; __device__ __forceinline__ float bf_lo(unsigned w) { return __uint_as_float(w << 16); }
; __device__ __forceinline__ float bf_hi(unsigned w) { return __uint_as_float(w & 0xffff0000u); }
; #define LAS __attribute__((address_space(3)))
; __device__ __forceinline__ void sgu_unit(LAS unsigned char* lds, bf16* U, const bf16* VS, const float* SGS, const float* lnw, const float* lnb, const v4u* WF, const float* bsl, int unit, int tid) {
;     ...
;         for (int i = 0; i < 8; ++i) {
;             const f32x4 st4 = *(const LAS f32x4*)(stat + 4 * (rp + 8 * i));
;             const v4u w0 = sl[i][0], w1 = sl[i][1];
;             const unsigned A0[4] = {w0.x, w0.y, w0.z, w0.w}, A1[4] = {w1.x, w1.y, w1.z, w1.w};
; #pragma unroll
;             for (int e = 0; e < 8; ++e) { typedef float f32x2p __attribute__((ext_vector_type(2)));
;                 f32x2p v; v.x = (e & 1) ? bf_hi(A0[e >> 1]) : bf_lo(A0[e >> 1]); v.y = (e & 1) ? bf_hi(A1[e >> 1]) : bf_lo(A1[e >> 1]);
;                 const f32x2p mn = {st4.x, st4.z}, rs = {st4.y, st4.w};
;                 const f32x2p o = ((v - mn) * rs) * lw[e] + lb[e];
;                 *(LAS unsigned*)(wbase + e * 8 * SGU_VP + i * 32) = cvt_pk_bf16(o.x, o.y); }
;         }
	v_mov_b32_e32 v142, v138
	v_mov_b32_e32 v143, v140
	v_mov_b32_e32 v140, v139
	s_waitcnt vmcnt(9)
	v_lshlrev_b32_e32 v138, 16, v130
	s_waitcnt vmcnt(8)
	v_lshlrev_b32_e32 v139, 16, v134
	v_pk_add_f32 v[138:139], v[138:139], v[142:143] neg_lo:[0,1] neg_hi:[0,1]
	s_nop 0
	v_pk_mul_f32 v[138:139], v[140:141], v[138:139]
	s_nop 0
	v_pk_fma_f32 v[138:139], v[102:103], v[138:139], v[98:99] op_sel_hi:[0,1,0]
	v_cvt_pk_bf16_f32 v85, v138, v139
	v_and_b32_e32 v138, 0xffff0000, v130
	v_and_b32_e32 v139, 0xffff0000, v134
	v_pk_add_f32 v[138:139], v[138:139], v[142:143] neg_lo:[0,1] neg_hi:[0,1]
	ds_write_b32 v177, v85 offset:1120
	v_pk_mul_f32 v[138:139], v[140:141], v[138:139]
	v_and_b32_e32 v130, 0xffff0000, v131
	v_pk_fma_f32 v[138:139], v[102:103], v[138:139], v[98:99] op_sel:[1,0,1]
	s_nop 0
	v_cvt_pk_bf16_f32 v85, v138, v139
	v_lshlrev_b32_e32 v138, 16, v131
	v_lshlrev_b32_e32 v139, 16, v135
	v_and_b32_e32 v131, 0xffff0000, v135
	v_pk_add_f32 v[138:139], v[138:139], v[142:143] neg_lo:[0,1] neg_hi:[0,1]
	v_pk_add_f32 v[130:131], v[130:131], v[142:143] neg_lo:[0,1] neg_hi:[0,1]
	v_pk_mul_f32 v[138:139], v[140:141], v[138:139]
	v_pk_mul_f32 v[130:131], v[140:141], v[130:131]
	ds_write_b32 v177, v85 offset:3296
	v_pk_fma_f32 v[138:139], v[104:105], v[138:139], v[100:101] op_sel_hi:[0,1,0]
	v_cvt_pk_bf16_f32 v85, v138, v139
	v_pk_fma_f32 v[130:131], v[160:161], v[130:131], v[162:163] op_sel_hi:[0,1,0]
	ds_write_b32 v177, v85 offset:5472
	v_cvt_pk_bf16_f32 v85, v130, v131
	v_lshlrev_b32_e32 v130, 16, v132
	v_lshlrev_b32_e32 v131, 16, v136
	v_pk_add_f32 v[130:131], v[130:131], v[142:143] neg_lo:[0,1] neg_hi:[0,1]
	ds_write_b32 v177, v85 offset:7648
	v_pk_mul_f32 v[130:131], v[140:141], v[130:131]
	s_nop 0
	v_pk_fma_f32 v[130:131], v[82:83], v[130:131], v[86:87] op_sel_hi:[0,1,0]
	v_cvt_pk_bf16_f32 v85, v130, v131
	v_and_b32_e32 v130, 0xffff0000, v132
	v_and_b32_e32 v131, 0xffff0000, v136
	v_pk_add_f32 v[130:131], v[130:131], v[142:143] neg_lo:[0,1] neg_hi:[0,1]
	ds_write_b32 v177, v85 offset:9824
	v_pk_mul_f32 v[130:131], v[140:141], v[130:131]
	s_nop 0
	v_pk_fma_f32 v[130:131], v[82:83], v[130:131], v[86:87] op_sel:[1,0,1]
	s_nop 0
	v_cvt_pk_bf16_f32 v85, v130, v131
	v_lshlrev_b32_e32 v130, 16, v133
	v_lshlrev_b32_e32 v131, 16, v137
	v_pk_add_f32 v[130:131], v[130:131], v[142:143] neg_lo:[0,1] neg_hi:[0,1]
	ds_write_b32 v177, v85 offset:12000
	v_pk_mul_f32 v[130:131], v[140:141], v[130:131]
	s_nop 0
	v_pk_fma_f32 v[130:131], v[84:85], v[130:131], v[88:89] op_sel_hi:[0,1,0]
	v_cvt_pk_bf16_f32 v85, v130, v131
	v_and_b32_e32 v130, 0xffff0000, v133
	v_and_b32_e32 v131, 0xffff0000, v137
	v_pk_add_f32 v[130:131], v[130:131], v[142:143] neg_lo:[0,1] neg_hi:[0,1]
	ds_write_b32 v177, v85 offset:14176
	v_pk_mul_f32 v[130:131], v[140:141], v[130:131]
	s_nop 0
	v_pk_fma_f32 v[130:131], v[164:165], v[130:131], v[166:167] op_sel_hi:[0,1,0]
	v_cvt_pk_bf16_f32 v85, v130, v131
	ds_write_b32 v177, v85 offset:16352
	ds_read_b128 v[130:133], v181 offset:512
	s_waitcnt lgkmcnt(0)
	v_mov_b32_e32 v134, v130
	v_mov_b32_e32 v135, v132
	v_mov_b32_e32 v132, v131
	s_waitcnt vmcnt(7)
	v_lshlrev_b32_e32 v130, 16, v122
	s_waitcnt vmcnt(6)
	v_lshlrev_b32_e32 v131, 16, v126
	v_pk_add_f32 v[130:131], v[130:131], v[134:135] neg_lo:[0,1] neg_hi:[0,1]
	s_nop 0
	v_pk_mul_f32 v[130:131], v[132:133], v[130:131]
	s_nop 0
	v_pk_fma_f32 v[130:131], v[102:103], v[130:131], v[98:99] op_sel_hi:[0,1,0]
	v_cvt_pk_bf16_f32 v85, v130, v131
	v_and_b32_e32 v130, 0xffff0000, v122
	v_and_b32_e32 v131, 0xffff0000, v126
	v_pk_add_f32 v[130:131], v[130:131], v[134:135] neg_lo:[0,1] neg_hi:[0,1]
	ds_write_b32 v177, v85 offset:1152
	v_pk_mul_f32 v[130:131], v[132:133], v[130:131]
	v_and_b32_e32 v122, 0xffff0000, v123
	v_pk_fma_f32 v[130:131], v[102:103], v[130:131], v[98:99] op_sel:[1,0,1]
	s_nop 0
	v_cvt_pk_bf16_f32 v85, v130, v131
	v_lshlrev_b32_e32 v130, 16, v123
	v_lshlrev_b32_e32 v131, 16, v127
	v_and_b32_e32 v123, 0xffff0000, v127
	v_pk_add_f32 v[130:131], v[130:131], v[134:135] neg_lo:[0,1] neg_hi:[0,1]
	v_pk_add_f32 v[122:123], v[122:123], v[134:135] neg_lo:[0,1] neg_hi:[0,1]
	v_pk_mul_f32 v[130:131], v[132:133], v[130:131]
	v_pk_mul_f32 v[122:123], v[132:133], v[122:123]
	ds_write_b32 v177, v85 offset:3328
	v_pk_fma_f32 v[130:131], v[104:105], v[130:131], v[100:101] op_sel_hi:[0,1,0]
	v_cvt_pk_bf16_f32 v85, v130, v131
	v_pk_fma_f32 v[122:123], v[160:161], v[122:123], v[162:163] op_sel_hi:[0,1,0]
	ds_write_b32 v177, v85 offset:5504
	v_cvt_pk_bf16_f32 v85, v122, v123
	v_lshlrev_b32_e32 v122, 16, v124
	v_lshlrev_b32_e32 v123, 16, v128
	v_pk_add_f32 v[122:123], v[122:123], v[134:135] neg_lo:[0,1] neg_hi:[0,1]
	ds_write_b32 v177, v85 offset:7680
	v_pk_mul_f32 v[122:123], v[132:133], v[122:123]
	s_nop 0
	v_pk_fma_f32 v[122:123], v[82:83], v[122:123], v[86:87] op_sel_hi:[0,1,0]
	v_cvt_pk_bf16_f32 v85, v122, v123
	v_and_b32_e32 v122, 0xffff0000, v124
	v_and_b32_e32 v123, 0xffff0000, v128
	v_pk_add_f32 v[122:123], v[122:123], v[134:135] neg_lo:[0,1] neg_hi:[0,1]
	ds_write_b32 v177, v85 offset:9856
	v_pk_mul_f32 v[122:123], v[132:133], v[122:123]
	s_nop 0
	v_pk_fma_f32 v[122:123], v[82:83], v[122:123], v[86:87] op_sel:[1,0,1]
	s_nop 0
	v_cvt_pk_bf16_f32 v85, v122, v123
	v_lshlrev_b32_e32 v122, 16, v125
	v_lshlrev_b32_e32 v123, 16, v129
	v_pk_add_f32 v[122:123], v[122:123], v[134:135] neg_lo:[0,1] neg_hi:[0,1]
	ds_write_b32 v177, v85 offset:12032
	v_pk_mul_f32 v[122:123], v[132:133], v[122:123]
	s_nop 0
	v_pk_fma_f32 v[122:123], v[84:85], v[122:123], v[88:89] op_sel_hi:[0,1,0]
	v_cvt_pk_bf16_f32 v85, v122, v123
	v_and_b32_e32 v122, 0xffff0000, v125
	v_and_b32_e32 v123, 0xffff0000, v129
	v_pk_add_f32 v[122:123], v[122:123], v[134:135] neg_lo:[0,1] neg_hi:[0,1]
	ds_write_b32 v177, v85 offset:14208
	v_pk_mul_f32 v[122:123], v[132:133], v[122:123]
	s_nop 0
	v_pk_fma_f32 v[122:123], v[164:165], v[122:123], v[166:167] op_sel_hi:[0,1,0]
	v_cvt_pk_bf16_f32 v85, v122, v123
	ds_write_b32 v177, v85 offset:16384
	ds_read_b128 v[122:125], v181 offset:640
	s_waitcnt lgkmcnt(0)
; __device__ __forceinline__ unsigned cvt_pk_bf16(float lo, float hi) { unsigned r; asm volatile("v_cvt_pk_bf16_f32 %0, %1, %2" : "=v"(r) : "v"(lo), "v"(hi)); return r; }
; __device__ __forceinline__ float bf_lo(unsigned w) { return __uint_as_float(w << 16); }
; __device__ __forceinline__ float bf_hi(unsigned w) { return __uint_as_float(w & 0xffff0000u); }
; #define LAS __attribute__((address_space(3)))
; __device__ __forceinline__ void sgu_unit(LAS unsigned char* lds, bf16* U, const bf16* VS, const float* SGS, const float* lnw, const float* lnb, const v4u* WF, const float* bsl, int unit, int tid) {
;     ...
;         for (int i = 0; i < 8; ++i) {
;             const f32x4 st4 = *(const LAS f32x4*)(stat + 4 * (rp + 8 * i));
;             const v4u w0 = sl[i][0], w1 = sl[i][1];
;             const unsigned A0[4] = {w0.x, w0.y, w0.z, w0.w}, A1[4] = {w1.x, w1.y, w1.z, w1.w};
; #pragma unroll
;             for (int e = 0; e < 8; ++e) { typedef float f32x2p __attribute__((ext_vector_type(2)));
;                 f32x2p v; v.x = (e & 1) ? bf_hi(A0[e >> 1]) : bf_lo(A0[e >> 1]); v.y = (e & 1) ? bf_hi(A1[e >> 1]) : bf_lo(A1[e >> 1]);
;                 const f32x2p mn = {st4.x, st4.z}, rs = {st4.y, st4.w};
;                 const f32x2p o = ((v - mn) * rs) * lw[e] + lb[e];
;                 *(LAS unsigned*)(wbase + e * 8 * SGU_VP + i * 32) = cvt_pk_bf16(o.x, o.y); }
;         }
	v_mov_b32_e32 v126, v122
	v_mov_b32_e32 v127, v124
	v_mov_b32_e32 v124, v123
	s_waitcnt vmcnt(5)
	v_lshlrev_b32_e32 v122, 16, v114
	s_waitcnt vmcnt(4)
	v_lshlrev_b32_e32 v123, 16, v118
	v_pk_add_f32 v[122:123], v[122:123], v[126:127] neg_lo:[0,1] neg_hi:[0,1]
	s_nop 0
	v_pk_mul_f32 v[122:123], v[124:125], v[122:123]
	s_nop 0
	v_pk_fma_f32 v[122:123], v[102:103], v[122:123], v[98:99] op_sel_hi:[0,1,0]
	v_cvt_pk_bf16_f32 v85, v122, v123
	v_and_b32_e32 v122, 0xffff0000, v114
	v_and_b32_e32 v123, 0xffff0000, v118
	v_pk_add_f32 v[122:123], v[122:123], v[126:127] neg_lo:[0,1] neg_hi:[0,1]
	ds_write_b32 v177, v85 offset:1184
	v_pk_mul_f32 v[122:123], v[124:125], v[122:123]
	v_and_b32_e32 v114, 0xffff0000, v115
	v_pk_fma_f32 v[122:123], v[102:103], v[122:123], v[98:99] op_sel:[1,0,1]
	s_nop 0
	v_cvt_pk_bf16_f32 v85, v122, v123
	v_lshlrev_b32_e32 v122, 16, v115
	v_lshlrev_b32_e32 v123, 16, v119
	v_and_b32_e32 v115, 0xffff0000, v119
	v_pk_add_f32 v[122:123], v[122:123], v[126:127] neg_lo:[0,1] neg_hi:[0,1]
	v_pk_add_f32 v[114:115], v[114:115], v[126:127] neg_lo:[0,1] neg_hi:[0,1]
	v_pk_mul_f32 v[122:123], v[124:125], v[122:123]
	v_pk_mul_f32 v[114:115], v[124:125], v[114:115]
	ds_write_b32 v177, v85 offset:3360
	v_pk_fma_f32 v[122:123], v[104:105], v[122:123], v[100:101] op_sel_hi:[0,1,0]
	v_cvt_pk_bf16_f32 v85, v122, v123
	v_pk_fma_f32 v[114:115], v[160:161], v[114:115], v[162:163] op_sel_hi:[0,1,0]
	ds_write_b32 v177, v85 offset:5536
	v_cvt_pk_bf16_f32 v85, v114, v115
	v_lshlrev_b32_e32 v114, 16, v116
	v_lshlrev_b32_e32 v115, 16, v120
	v_pk_add_f32 v[114:115], v[114:115], v[126:127] neg_lo:[0,1] neg_hi:[0,1]
	ds_write_b32 v177, v85 offset:7712
	v_pk_mul_f32 v[114:115], v[124:125], v[114:115]
	s_nop 0
	v_pk_fma_f32 v[114:115], v[82:83], v[114:115], v[86:87] op_sel_hi:[0,1,0]
	v_cvt_pk_bf16_f32 v85, v114, v115
	v_and_b32_e32 v114, 0xffff0000, v116
	v_and_b32_e32 v115, 0xffff0000, v120
	v_pk_add_f32 v[114:115], v[114:115], v[126:127] neg_lo:[0,1] neg_hi:[0,1]
	ds_write_b32 v177, v85 offset:9888
	v_pk_mul_f32 v[114:115], v[124:125], v[114:115]
	s_nop 0
	v_pk_fma_f32 v[114:115], v[82:83], v[114:115], v[86:87] op_sel:[1,0,1]
	s_nop 0
	v_cvt_pk_bf16_f32 v85, v114, v115
	v_lshlrev_b32_e32 v114, 16, v117
	v_lshlrev_b32_e32 v115, 16, v121
	v_pk_add_f32 v[114:115], v[114:115], v[126:127] neg_lo:[0,1] neg_hi:[0,1]
	ds_write_b32 v177, v85 offset:12064
	v_pk_mul_f32 v[114:115], v[124:125], v[114:115]
	s_nop 0
	v_pk_fma_f32 v[114:115], v[84:85], v[114:115], v[88:89] op_sel_hi:[0,1,0]
	v_cvt_pk_bf16_f32 v85, v114, v115
	v_and_b32_e32 v114, 0xffff0000, v117
	v_and_b32_e32 v115, 0xffff0000, v121
	v_pk_add_f32 v[114:115], v[114:115], v[126:127] neg_lo:[0,1] neg_hi:[0,1]
	ds_write_b32 v177, v85 offset:14240
	v_pk_mul_f32 v[114:115], v[124:125], v[114:115]
	s_nop 0
	v_pk_fma_f32 v[114:115], v[164:165], v[114:115], v[166:167] op_sel_hi:[0,1,0]
	v_cvt_pk_bf16_f32 v85, v114, v115
	ds_write_b32 v177, v85 offset:16416
	ds_read_b128 v[114:117], v181 offset:768
	s_waitcnt lgkmcnt(0)
	v_mov_b32_e32 v118, v114
	v_mov_b32_e32 v119, v116
	v_mov_b32_e32 v116, v115
	s_waitcnt vmcnt(3)
	v_lshlrev_b32_e32 v114, 16, v106
	s_waitcnt vmcnt(2)
	v_lshlrev_b32_e32 v115, 16, v110
	v_pk_add_f32 v[114:115], v[114:115], v[118:119] neg_lo:[0,1] neg_hi:[0,1]
	s_nop 0
	v_pk_mul_f32 v[114:115], v[116:117], v[114:115]
	s_nop 0
	v_pk_fma_f32 v[114:115], v[102:103], v[114:115], v[98:99] op_sel_hi:[0,1,0]
	v_cvt_pk_bf16_f32 v85, v114, v115
	v_and_b32_e32 v114, 0xffff0000, v106
	v_and_b32_e32 v115, 0xffff0000, v110
	v_pk_add_f32 v[114:115], v[114:115], v[118:119] neg_lo:[0,1] neg_hi:[0,1]
	ds_write_b32 v177, v85 offset:1216
	v_pk_mul_f32 v[114:115], v[116:117], v[114:115]
	v_and_b32_e32 v106, 0xffff0000, v107
	v_pk_fma_f32 v[114:115], v[102:103], v[114:115], v[98:99] op_sel:[1,0,1]
	s_nop 0
	v_cvt_pk_bf16_f32 v85, v114, v115
	v_lshlrev_b32_e32 v114, 16, v107
	v_lshlrev_b32_e32 v115, 16, v111
	v_and_b32_e32 v107, 0xffff0000, v111
	v_pk_add_f32 v[114:115], v[114:115], v[118:119] neg_lo:[0,1] neg_hi:[0,1]
	v_pk_add_f32 v[106:107], v[106:107], v[118:119] neg_lo:[0,1] neg_hi:[0,1]
	v_pk_mul_f32 v[114:115], v[116:117], v[114:115]
	v_pk_mul_f32 v[106:107], v[116:117], v[106:107]
	ds_write_b32 v177, v85 offset:3392
	v_pk_fma_f32 v[114:115], v[104:105], v[114:115], v[100:101] op_sel_hi:[0,1,0]
	v_cvt_pk_bf16_f32 v85, v114, v115
	v_pk_fma_f32 v[106:107], v[160:161], v[106:107], v[162:163] op_sel_hi:[0,1,0]
	ds_write_b32 v177, v85 offset:5568
	v_cvt_pk_bf16_f32 v85, v106, v107
	v_lshlrev_b32_e32 v106, 16, v108
	v_lshlrev_b32_e32 v107, 16, v112
	v_pk_add_f32 v[106:107], v[106:107], v[118:119] neg_lo:[0,1] neg_hi:[0,1]
	ds_write_b32 v177, v85 offset:7744
	v_pk_mul_f32 v[106:107], v[116:117], v[106:107]
	s_nop 0
	v_pk_fma_f32 v[106:107], v[82:83], v[106:107], v[86:87] op_sel_hi:[0,1,0]
	v_cvt_pk_bf16_f32 v85, v106, v107
	v_and_b32_e32 v106, 0xffff0000, v108
	v_and_b32_e32 v107, 0xffff0000, v112
	v_pk_add_f32 v[106:107], v[106:107], v[118:119] neg_lo:[0,1] neg_hi:[0,1]
	ds_write_b32 v177, v85 offset:9920
	v_pk_mul_f32 v[106:107], v[116:117], v[106:107]
	s_nop 0
	v_pk_fma_f32 v[106:107], v[82:83], v[106:107], v[86:87] op_sel:[1,0,1]
	s_nop 0
	v_cvt_pk_bf16_f32 v85, v106, v107
	v_lshlrev_b32_e32 v106, 16, v109
	v_lshlrev_b32_e32 v107, 16, v113
	v_pk_add_f32 v[106:107], v[106:107], v[118:119] neg_lo:[0,1] neg_hi:[0,1]
	ds_write_b32 v177, v85 offset:12096
	v_pk_mul_f32 v[106:107], v[116:117], v[106:107]
	s_nop 0
	v_pk_fma_f32 v[106:107], v[84:85], v[106:107], v[88:89] op_sel_hi:[0,1,0]
	v_cvt_pk_bf16_f32 v85, v106, v107
	v_and_b32_e32 v106, 0xffff0000, v109
	v_and_b32_e32 v107, 0xffff0000, v113
	v_pk_add_f32 v[106:107], v[106:107], v[118:119] neg_lo:[0,1] neg_hi:[0,1]
	ds_write_b32 v177, v85 offset:14272
	v_pk_mul_f32 v[106:107], v[116:117], v[106:107]
	s_nop 0
	v_pk_fma_f32 v[106:107], v[164:165], v[106:107], v[166:167] op_sel_hi:[0,1,0]
	v_cvt_pk_bf16_f32 v85, v106, v107
	ds_write_b32 v177, v85 offset:16448
	ds_read_b128 v[106:109], v181 offset:896
	s_waitcnt lgkmcnt(0)
; __device__ __forceinline__ unsigned cvt_pk_bf16(float lo, float hi) { unsigned r; asm volatile("v_cvt_pk_bf16_f32 %0, %1, %2" : "=v"(r) : "v"(lo), "v"(hi)); return r; }
; __device__ __forceinline__ float bf_lo(unsigned w) { return __uint_as_float(w << 16); }
; __device__ __forceinline__ float bf_hi(unsigned w) { return __uint_as_float(w & 0xffff0000u); }
; #define LAS __attribute__((address_space(3)))
; __device__ __forceinline__ void sgu_unit(LAS unsigned char* lds, bf16* U, const bf16* VS, const float* SGS, const float* lnw, const float* lnb, const v4u* WF, const float* bsl, int unit, int tid) {
;     ...
;         for (int i = 0; i < 8; ++i) {
;             const f32x4 st4 = *(const LAS f32x4*)(stat + 4 * (rp + 8 * i));
;             const v4u w0 = sl[i][0], w1 = sl[i][1];
;             const unsigned A0[4] = {w0.x, w0.y, w0.z, w0.w}, A1[4] = {w1.x, w1.y, w1.z, w1.w};
; #pragma unroll
;             for (int e = 0; e < 8; ++e) { typedef float f32x2p __attribute__((ext_vector_type(2)));
;                 f32x2p v; v.x = (e & 1) ? bf_hi(A0[e >> 1]) : bf_lo(A0[e >> 1]); v.y = (e & 1) ? bf_hi(A1[e >> 1]) : bf_lo(A1[e >> 1]);
;                 const f32x2p mn = {st4.x, st4.z}, rs = {st4.y, st4.w};
;                 const f32x2p o = ((v - mn) * rs) * lw[e] + lb[e];
;                 *(LAS unsigned*)(wbase + e * 8 * SGU_VP + i * 32) = cvt_pk_bf16(o.x, o.y); }
;         }
;     }
;     v2u uu[8][4];
; #pragma unroll
;     for (int mt = 0; mt < 8; ++mt)
; #pragma unroll
;         for (int nt = 0; nt < 4; ++nt) uu[mt][nt] = *(const v2u*)(U + (size_t)(r0 + 16 * mt + fr) * 1024 + colbase + 16 * nt + 4 * fq);
	v_mov_b32_e32 v110, v106
	v_mov_b32_e32 v111, v108
	v_mov_b32_e32 v108, v107
	s_waitcnt vmcnt(1)
	v_lshlrev_b32_e32 v106, 16, v90
	s_waitcnt vmcnt(0)
	v_lshlrev_b32_e32 v107, 16, v94
	v_pk_add_f32 v[106:107], v[106:107], v[110:111] neg_lo:[0,1] neg_hi:[0,1]
	s_nop 0
	v_pk_mul_f32 v[106:107], v[108:109], v[106:107]
	s_nop 0
	v_pk_fma_f32 v[106:107], v[102:103], v[106:107], v[98:99] op_sel_hi:[0,1,0]
	v_cvt_pk_bf16_f32 v85, v106, v107
	v_and_b32_e32 v106, 0xffff0000, v90
	v_and_b32_e32 v107, 0xffff0000, v94
	v_pk_add_f32 v[106:107], v[106:107], v[110:111] neg_lo:[0,1] neg_hi:[0,1]
	ds_write_b32 v177, v85 offset:1248
	v_pk_mul_f32 v[106:107], v[108:109], v[106:107]
	v_and_b32_e32 v90, 0xffff0000, v91
	v_pk_fma_f32 v[98:99], v[102:103], v[106:107], v[98:99] op_sel:[1,0,1]
	s_nop 0
	v_cvt_pk_bf16_f32 v85, v98, v99
	v_lshlrev_b32_e32 v98, 16, v91
	v_lshlrev_b32_e32 v99, 16, v95
	v_and_b32_e32 v91, 0xffff0000, v95
	v_pk_add_f32 v[98:99], v[98:99], v[110:111] neg_lo:[0,1] neg_hi:[0,1]
	v_pk_add_f32 v[90:91], v[90:91], v[110:111] neg_lo:[0,1] neg_hi:[0,1]
	v_pk_mul_f32 v[98:99], v[108:109], v[98:99]
	v_pk_mul_f32 v[90:91], v[108:109], v[90:91]
	ds_write_b32 v177, v85 offset:3424
	v_pk_fma_f32 v[98:99], v[104:105], v[98:99], v[100:101] op_sel_hi:[0,1,0]
	v_cvt_pk_bf16_f32 v85, v98, v99
	v_pk_fma_f32 v[90:91], v[160:161], v[90:91], v[162:163] op_sel_hi:[0,1,0]
	ds_write_b32 v177, v85 offset:5600
	v_cvt_pk_bf16_f32 v85, v90, v91
	v_lshlrev_b32_e32 v90, 16, v92
	v_lshlrev_b32_e32 v91, 16, v96
	v_pk_add_f32 v[90:91], v[90:91], v[110:111] neg_lo:[0,1] neg_hi:[0,1]
	ds_write_b32 v177, v85 offset:7776
	v_pk_mul_f32 v[90:91], v[108:109], v[90:91]
	s_nop 0
	v_pk_fma_f32 v[90:91], v[82:83], v[90:91], v[86:87] op_sel_hi:[0,1,0]
	v_cvt_pk_bf16_f32 v85, v90, v91
	v_and_b32_e32 v90, 0xffff0000, v92
	v_and_b32_e32 v91, 0xffff0000, v96
	v_pk_add_f32 v[90:91], v[90:91], v[110:111] neg_lo:[0,1] neg_hi:[0,1]
	ds_write_b32 v177, v85 offset:9952
	v_pk_mul_f32 v[90:91], v[108:109], v[90:91]
	s_nop 0
	v_pk_fma_f32 v[82:83], v[82:83], v[90:91], v[86:87] op_sel:[1,0,1]
	s_nop 0
	v_cvt_pk_bf16_f32 v82, v82, v83
	ds_write_b32 v177, v82 offset:12128
	v_lshlrev_b32_e32 v82, 16, v93
	v_lshlrev_b32_e32 v83, 16, v97
	v_pk_add_f32 v[82:83], v[82:83], v[110:111] neg_lo:[0,1] neg_hi:[0,1]
	s_nop 0
	v_pk_mul_f32 v[82:83], v[108:109], v[82:83]
	s_nop 0
	v_pk_fma_f32 v[82:83], v[84:85], v[82:83], v[88:89] op_sel_hi:[0,1,0]
	v_cvt_pk_bf16_f32 v82, v82, v83
	ds_write_b32 v177, v82 offset:14304
	v_and_b32_e32 v82, 0xffff0000, v93
	v_and_b32_e32 v83, 0xffff0000, v97
	v_pk_add_f32 v[82:83], v[82:83], v[110:111] neg_lo:[0,1] neg_hi:[0,1]
	v_or_b32_e32 v84, s18, v163
	v_pk_mul_f32 v[82:83], v[108:109], v[82:83]
	v_lshlrev_b32_e32 v84, 11, v84
	v_pk_fma_f32 v[82:83], v[164:165], v[82:83], v[166:167] op_sel_hi:[0,1,0]
	v_cvt_pk_bf16_f32 v82, v82, v83
	ds_write_b32 v177, v82 offset:16480
	v_lshl_add_u64 v[82:83], v[158:159], 1, v[150:151]
	v_mov_b32_e32 v85, v147
	v_lshl_add_u64 v[144:145], v[82:83], 0, v[84:85]
	global_load_dwordx2 v[158:159], v[144:145], off
	global_load_dwordx2 v[210:211], v[144:145], off offset:32
	global_load_dwordx2 v[212:213], v[144:145], off offset:64
	global_load_dwordx2 v[214:215], v[144:145], off offset:96
	v_add_co_u32_e32 v216, vcc, s43, v144
	s_waitcnt vmcnt(3)
	v_lshlrev_b32_e32 v160, 16, v158
	v_addc_co_u32_e32 v217, vcc, 0, v145, vcc
	global_load_dwordx2 v[218:219], v[216:217], off
	global_load_dwordx2 v[220:221], v[216:217], off offset:32
	global_load_dwordx2 v[222:223], v[216:217], off offset:64
	global_load_dwordx2 v[224:225], v[216:217], off offset:96
	v_add_co_u32_e32 v130, vcc, s53, v144
	v_and_b32_e32 v158, 0xffff0000, v158
	s_nop 0
	v_addc_co_u32_e32 v131, vcc, 0, v145, vcc
	v_add_co_u32_e32 v120, vcc, s54, v144
	global_load_dwordx2 v[226:227], v[130:131], off
	global_load_dwordx2 v[138:139], v[130:131], off offset:32
	global_load_dwordx2 v[136:137], v[130:131], off offset:64
	global_load_dwordx2 v[134:135], v[130:131], off offset:96
	v_addc_co_u32_e32 v121, vcc, 0, v145, vcc
	v_add_co_u32_e32 v110, vcc, s55, v144
	global_load_dwordx2 v[132:133], v[120:121], off
	global_load_dwordx2 v[128:129], v[120:121], off offset:32
	global_load_dwordx2 v[126:127], v[120:121], off offset:64
	global_load_dwordx2 v[124:125], v[120:121], off offset:96
	v_addc_co_u32_e32 v111, vcc, 0, v145, vcc
	v_add_co_u32_e32 v100, vcc, s56, v144
	global_load_dwordx2 v[122:123], v[110:111], off
	global_load_dwordx2 v[118:119], v[110:111], off offset:32
	global_load_dwordx2 v[116:117], v[110:111], off offset:64
	global_load_dwordx2 v[114:115], v[110:111], off offset:96
	v_addc_co_u32_e32 v101, vcc, 0, v145, vcc
	v_add_co_u32_e32 v90, vcc, s57, v144
	global_load_dwordx2 v[112:113], v[100:101], off
	global_load_dwordx2 v[108:109], v[100:101], off offset:32
	global_load_dwordx2 v[106:107], v[100:101], off offset:64
	global_load_dwordx2 v[104:105], v[100:101], off offset:96
	v_addc_co_u32_e32 v91, vcc, 0, v145, vcc
	v_lshrrev_b32_e32 v236, 4, v0
	v_and_b32_e32 v236, 1, v236
	v_mul_u32_u24_e32 v236, 24, v236
	v_mov_b32_e32 v237, 0
	v_add_co_u32_e32 v82, vcc, s58, v144
	global_load_dwordx2 v[102:103], v[90:91], off
	global_load_dwordx2 v[98:99], v[90:91], off offset:32
	global_load_dwordx2 v[96:97], v[90:91], off offset:64
	global_load_dwordx2 v[94:95], v[90:91], off offset:96
	v_addc_co_u32_e32 v83, vcc, 0, v145, vcc
	global_load_dwordx2 v[92:93], v[82:83], off
	global_load_dwordx2 v[88:89], v[82:83], off offset:32
	global_load_dwordx2 v[86:87], v[82:83], off offset:64
	global_load_dwordx2 v[84:85], v[82:83], off offset:96
	s_waitcnt lgkmcnt(0)
; __device__ __forceinline__ unsigned cvt_pk_bf16(float lo, float hi) { unsigned r; asm volatile("v_cvt_pk_bf16_f32 %0, %1, %2" : "=v"(r) : "v"(lo), "v"(hi)); return r; }
; __device__ __forceinline__ float bf_lo(unsigned w) { return __uint_as_float(w << 16); }
; __device__ __forceinline__ float bf_hi(unsigned w) { return __uint_as_float(w & 0xffff0000u); }
; #define LAS __attribute__((address_space(3)))
; __device__ __forceinline__ void sgu_unit(LAS unsigned char* lds, bf16* U, const bf16* VS, const float* SGS, const float* lnw, const float* lnb, const v4u* WF, const float* bsl, int unit, int tid) {
;     ...
;         for (int mt = 0; mt < 8; ++mt) {
;             const int t = 16 * mt + fr;
;             f32x4 acc[4];
; #pragma unroll
;             for (int nt = 0; nt < 4; ++nt) acc[nt] = (f32x4){0.f, 0.f, 0.f, 0.f};
; #pragma unroll
;             for (int ks = 0; ks <= (mt >> 1); ++ks) {
;                 const int sb = 32 * ks + 8 * fq; const bf16x8_t wf = __builtin_bit_cast(bf16x8_t, wfr[q++]);
; #pragma unroll
;                 for (int nt = 0; nt < 4; ++nt) { const bf16x8_t vf = *(const LAS bf16x8_t*)(vt + ((fr >> 3) + 8 * (fr & 7) + 2 * nt) * SGU_VP + sb * 2);
;                     acc[nt] = __builtin_amdgcn_mfma_f32_16x16x32_bf16(vf, wf, acc[nt], 0, 0, 0); }
;             }
;             const float bb = bbv[mt];
; #pragma unroll
;             for (int nt = 0; nt < 4; ++nt) { const v2u u2 = uu[mt][nt]; v2u w; w.x = cvt_pk_bf16(bf_lo(u2.x) * (acc[nt][0] + bb), bf_hi(u2.x) * (acc[nt][1] + bb)); w.y = cvt_pk_bf16(bf_lo(u2.y) * (acc[nt][2] + bb), bf_hi(u2.y) * (acc[nt][3] + bb));
;                 *(v2u*)(U + (size_t)(r0 + t) * 1024 + colbase + 16 * nt + 4 * fq) = w; }
	ds_read_b128 v[140:143], v182 offset:1024
	ds_read_b128 v[198:201], v182 offset:1568
	s_waitcnt lgkmcnt(1)
	v_mfma_f32_16x16x32_bf16 v[140:143], v[140:143], v[78:81], 0
	ds_read_b128 v[202:205], v182 offset:2112
	ds_read_b128 v[206:209], v182 offset:2656
	s_nop 5
	v_add_f32_e32 v140, v197, v140
	v_add_f32_e32 v141, v197, v141
	s_waitcnt lgkmcnt(2)
	v_mfma_f32_16x16x32_bf16 v[198:201], v[198:201], v[78:81], 0
	v_mul_f32_e32 v140, v140, v160
	v_mul_f32_e32 v141, v141, v158
	v_cvt_pk_bf16_f32 v248, v140, v141
	v_lshlrev_b32_e32 v141, 16, v159
	v_add_f32_e32 v142, v197, v142
	v_mul_f32_e32 v141, v142, v141
	v_and_b32_e32 v142, 0xffff0000, v159
	v_add_f32_e32 v143, v197, v143
	v_mul_f32_e32 v142, v143, v142
	v_cvt_pk_bf16_f32 v249, v141, v142
	v_lshl_add_u64 v[238:239], v[144:145], 0, v[236:237]
	s_waitcnt vmcnt(30)
	v_lshlrev_b32_e32 v140, 16, v210
	v_add_f32_e32 v141, v197, v198
	v_mul_f32_e32 v140, v141, v140
	v_and_b32_e32 v141, 0xffff0000, v210
	v_add_f32_e32 v142, v197, v199
	s_waitcnt lgkmcnt(1)
	v_mfma_f32_16x16x32_bf16 v[202:205], v[202:205], v[78:81], 0
	v_mul_f32_e32 v141, v142, v141
	v_cvt_pk_bf16_f32 v250, v140, v141
	v_lshlrev_b32_e32 v141, 16, v211
	v_add_f32_e32 v142, v197, v200
	v_mul_f32_e32 v141, v142, v141
	v_and_b32_e32 v142, 0xffff0000, v211
	v_add_f32_e32 v143, v197, v201
	v_mul_f32_e32 v142, v143, v142
	v_cvt_pk_bf16_f32 v251, v141, v142
	s_nop 1
	v_permlane16_swap_b32_e32 v248, v250
	v_permlane16_swap_b32_e32 v249, v251
	global_store_dwordx4 v[238:239], v[248:251], off
	s_waitcnt vmcnt(30)
	v_lshlrev_b32_e32 v140, 16, v212
	v_add_f32_e32 v141, v197, v202
	s_waitcnt lgkmcnt(0)
	v_mfma_f32_16x16x32_bf16 v[78:81], v[206:209], v[78:81], 0
	v_mul_f32_e32 v140, v141, v140
	v_and_b32_e32 v141, 0xffff0000, v212
	v_add_f32_e32 v142, v197, v203
	v_mul_f32_e32 v141, v142, v141
	v_cvt_pk_bf16_f32 v252, v140, v141
	v_lshlrev_b32_e32 v141, 16, v213
	v_add_f32_e32 v142, v197, v204
	v_mul_f32_e32 v141, v142, v141
	v_and_b32_e32 v142, 0xffff0000, v213
	v_add_f32_e32 v143, v197, v205
	v_mul_f32_e32 v142, v143, v142
	v_cvt_pk_bf16_f32 v253, v141, v142
	s_waitcnt vmcnt(29)
	v_lshlrev_b32_e32 v140, 16, v214
	v_add_f32_e32 v78, v197, v78
	v_mul_f32_e32 v78, v78, v140
	v_and_b32_e32 v140, 0xffff0000, v214
	v_add_f32_e32 v79, v197, v79
	v_mul_f32_e32 v79, v79, v140
	v_cvt_pk_bf16_f32 v254, v78, v79
	v_lshlrev_b32_e32 v78, 16, v215
	v_add_f32_e32 v79, v197, v80
	v_mul_f32_e32 v78, v79, v78
	v_and_b32_e32 v79, 0xffff0000, v215
	v_add_f32_e32 v80, v197, v81
	v_mul_f32_e32 v79, v80, v79
	v_cvt_pk_bf16_f32 v255, v78, v79
	ds_read_b128 v[78:81], v182 offset:1024
	ds_read_b128 v[140:143], v182 offset:1568
	s_waitcnt lgkmcnt(1)
	v_mfma_f32_16x16x32_bf16 v[78:81], v[78:81], v[74:77], 0
	ds_read_b128 v[198:201], v182 offset:2112
	ds_read_b128 v[202:205], v182 offset:2656
	s_nop 1
	v_permlane16_swap_b32_e32 v252, v254
	v_permlane16_swap_b32_e32 v253, v255
	global_store_dwordx4 v[238:239], v[252:255], off offset:64
	s_waitcnt vmcnt(29)
	v_lshlrev_b32_e32 v144, 16, v218
	s_nop 2
	v_add_f32_e32 v78, v196, v78
	v_mul_f32_e32 v78, v78, v144
	v_and_b32_e32 v144, 0xffff0000, v218
	v_add_f32_e32 v79, v196, v79
	s_waitcnt lgkmcnt(2)
	v_mfma_f32_16x16x32_bf16 v[140:143], v[140:143], v[74:77], 0
	v_mul_f32_e32 v79, v79, v144
	v_cvt_pk_bf16_f32 v248, v78, v79
	v_lshlrev_b32_e32 v79, 16, v219
	v_add_f32_e32 v80, v196, v80
	v_mul_f32_e32 v79, v80, v79
	v_and_b32_e32 v80, 0xffff0000, v219
	v_add_f32_e32 v81, v196, v81
	v_mul_f32_e32 v80, v81, v80
	v_cvt_pk_bf16_f32 v249, v79, v80
	v_lshl_add_u64 v[238:239], v[216:217], 0, v[236:237]
	s_waitcnt vmcnt(28)
	v_lshlrev_b32_e32 v78, 16, v220
	v_add_f32_e32 v79, v196, v140
	v_mul_f32_e32 v78, v79, v78
	v_and_b32_e32 v79, 0xffff0000, v220
	v_add_f32_e32 v80, v196, v141
	s_waitcnt lgkmcnt(1)
	v_mfma_f32_16x16x32_bf16 v[198:201], v[198:201], v[74:77], 0
	v_mul_f32_e32 v79, v80, v79
	v_cvt_pk_bf16_f32 v250, v78, v79
	v_lshlrev_b32_e32 v79, 16, v221
	v_add_f32_e32 v80, v196, v142
	v_mul_f32_e32 v79, v80, v79
	v_and_b32_e32 v80, 0xffff0000, v221
	v_add_f32_e32 v81, v196, v143
	v_mul_f32_e32 v80, v81, v80
	v_cvt_pk_bf16_f32 v251, v79, v80
	s_nop 1
	v_permlane16_swap_b32_e32 v248, v250
	v_permlane16_swap_b32_e32 v249, v251
	global_store_dwordx4 v[238:239], v[248:251], off
	s_waitcnt vmcnt(28)
	v_lshlrev_b32_e32 v78, 16, v222
	v_add_f32_e32 v79, v196, v198
	s_waitcnt lgkmcnt(0)
	v_mfma_f32_16x16x32_bf16 v[74:77], v[202:205], v[74:77], 0
	v_mul_f32_e32 v78, v79, v78
	v_and_b32_e32 v79, 0xffff0000, v222
	v_add_f32_e32 v80, v196, v199
	v_mul_f32_e32 v79, v80, v79
	v_cvt_pk_bf16_f32 v252, v78, v79
	v_lshlrev_b32_e32 v79, 16, v223
	v_add_f32_e32 v80, v196, v200
	v_mul_f32_e32 v79, v80, v79
	v_and_b32_e32 v80, 0xffff0000, v223
	v_add_f32_e32 v81, v196, v201
	v_mul_f32_e32 v80, v81, v80
	v_cvt_pk_bf16_f32 v253, v79, v80
	s_waitcnt vmcnt(27)
	v_lshlrev_b32_e32 v78, 16, v224
	v_add_f32_e32 v74, v196, v74
	v_mul_f32_e32 v74, v74, v78
	v_and_b32_e32 v78, 0xffff0000, v224
	v_add_f32_e32 v75, v196, v75
	v_mul_f32_e32 v75, v75, v78
	v_cvt_pk_bf16_f32 v254, v74, v75
	v_lshlrev_b32_e32 v74, 16, v225
	v_add_f32_e32 v75, v196, v76
	v_mul_f32_e32 v74, v75, v74
	v_and_b32_e32 v75, 0xffff0000, v225
	v_add_f32_e32 v76, v196, v77
	v_mul_f32_e32 v75, v76, v75
	v_cvt_pk_bf16_f32 v255, v74, v75
	ds_read_b128 v[74:77], v182 offset:1024
	ds_read_b128 v[78:81], v182 offset:1088
	s_waitcnt lgkmcnt(1)
	v_mfma_f32_16x16x32_bf16 v[74:77], v[74:77], v[70:73], 0
	ds_read_b128 v[140:143], v182 offset:1568
	ds_read_b128 v[196:199], v182 offset:1632
	ds_read_b128 v[200:203], v182 offset:2112
	ds_read_b128 v[204:207], v182 offset:2176
	ds_read_b128 v[208:211], v182 offset:2656
	ds_read_b128 v[212:215], v182 offset:2720
	s_waitcnt lgkmcnt(5)
; __device__ __forceinline__ unsigned cvt_pk_bf16(float lo, float hi) { unsigned r; asm volatile("v_cvt_pk_bf16_f32 %0, %1, %2" : "=v"(r) : "v"(lo), "v"(hi)); return r; }
; __device__ __forceinline__ float bf_lo(unsigned w) { return __uint_as_float(w << 16); }
; __device__ __forceinline__ float bf_hi(unsigned w) { return __uint_as_float(w & 0xffff0000u); }
; #define LAS __attribute__((address_space(3)))
; __device__ __forceinline__ void sgu_unit(LAS unsigned char* lds, bf16* U, const bf16* VS, const float* SGS, const float* lnw, const float* lnb, const v4u* WF, const float* bsl, int unit, int tid) {
;     ...
;         for (int mt = 0; mt < 8; ++mt) {
;             const int t = 16 * mt + fr;
;             f32x4 acc[4];
; #pragma unroll
;             for (int nt = 0; nt < 4; ++nt) acc[nt] = (f32x4){0.f, 0.f, 0.f, 0.f};
; #pragma unroll
;             for (int ks = 0; ks <= (mt >> 1); ++ks) {
;                 const int sb = 32 * ks + 8 * fq; const bf16x8_t wf = __builtin_bit_cast(bf16x8_t, wfr[q++]);
; #pragma unroll
;                 for (int nt = 0; nt < 4; ++nt) { const bf16x8_t vf = *(const LAS bf16x8_t*)(vt + ((fr >> 3) + 8 * (fr & 7) + 2 * nt) * SGU_VP + sb * 2);
;                     acc[nt] = __builtin_amdgcn_mfma_f32_16x16x32_bf16(vf, wf, acc[nt], 0, 0, 0); }
;             }
;             const float bb = bbv[mt];
; #pragma unroll
;             for (int nt = 0; nt < 4; ++nt) { const v2u u2 = uu[mt][nt]; v2u w; w.x = cvt_pk_bf16(bf_lo(u2.x) * (acc[nt][0] + bb), bf_hi(u2.x) * (acc[nt][1] + bb)); w.y = cvt_pk_bf16(bf_lo(u2.y) * (acc[nt][2] + bb), bf_hi(u2.y) * (acc[nt][3] + bb));
;                 *(v2u*)(U + (size_t)(r0 + t) * 1024 + colbase + 16 * nt + 4 * fq) = w; }
	v_mfma_f32_16x16x32_bf16 v[140:143], v[140:143], v[70:73], 0
	s_nop 1
	v_permlane16_swap_b32_e32 v252, v254
	v_permlane16_swap_b32_e32 v253, v255
	global_store_dwordx4 v[238:239], v[252:255], off offset:64
	s_waitcnt lgkmcnt(3)
	v_mfma_f32_16x16x32_bf16 v[200:203], v[200:203], v[70:73], 0
	s_waitcnt lgkmcnt(1)
	v_mfma_f32_16x16x32_bf16 v[70:73], v[208:211], v[70:73], 0
	v_mfma_f32_16x16x32_bf16 v[74:77], v[78:81], v[66:69], v[74:77]
	v_mfma_f32_16x16x32_bf16 v[78:81], v[196:199], v[66:69], v[140:143]
	v_mfma_f32_16x16x32_bf16 v[140:143], v[204:207], v[66:69], v[200:203]
	s_waitcnt lgkmcnt(0)
	v_mfma_f32_16x16x32_bf16 v[66:69], v[212:215], v[66:69], v[70:73]
	s_waitcnt vmcnt(27)
	s_nop 1
	v_lshlrev_b32_e32 v70, 16, v226
	v_add_f32_e32 v71, v195, v74
	v_mul_f32_e32 v70, v71, v70
	v_and_b32_e32 v71, 0xffff0000, v226
	v_add_f32_e32 v72, v195, v75
	v_mul_f32_e32 v71, v72, v71
	v_cvt_pk_bf16_f32 v248, v70, v71
	v_lshlrev_b32_e32 v71, 16, v227
	v_add_f32_e32 v72, v195, v76
	v_mul_f32_e32 v71, v72, v71
	v_and_b32_e32 v72, 0xffff0000, v227
	v_add_f32_e32 v73, v195, v77
	v_mul_f32_e32 v72, v73, v72
	v_cvt_pk_bf16_f32 v249, v71, v72
	v_lshl_add_u64 v[238:239], v[130:131], 0, v[236:237]
	s_waitcnt vmcnt(26)
	v_lshlrev_b32_e32 v70, 16, v138
	v_add_f32_e32 v71, v195, v78
	v_mul_f32_e32 v70, v71, v70
	v_and_b32_e32 v71, 0xffff0000, v138
	v_add_f32_e32 v72, v195, v79
	v_mul_f32_e32 v71, v72, v71
	v_cvt_pk_bf16_f32 v250, v70, v71
	v_lshlrev_b32_e32 v71, 16, v139
	v_add_f32_e32 v72, v195, v80
	v_mul_f32_e32 v71, v72, v71
	v_and_b32_e32 v72, 0xffff0000, v139
	v_add_f32_e32 v73, v195, v81
	v_mul_f32_e32 v72, v73, v72
	v_cvt_pk_bf16_f32 v251, v71, v72
	s_nop 1
	v_permlane16_swap_b32_e32 v248, v250
	v_permlane16_swap_b32_e32 v249, v251
	global_store_dwordx4 v[238:239], v[248:251], off
	s_waitcnt vmcnt(26)
	v_lshlrev_b32_e32 v70, 16, v136
	v_add_f32_e32 v71, v195, v140
	v_mul_f32_e32 v70, v71, v70
	v_and_b32_e32 v71, 0xffff0000, v136
	v_add_f32_e32 v72, v195, v141
	v_mul_f32_e32 v71, v72, v71
	v_cvt_pk_bf16_f32 v252, v70, v71
	v_lshlrev_b32_e32 v71, 16, v137
	v_add_f32_e32 v72, v195, v142
	v_mul_f32_e32 v71, v72, v71
	v_and_b32_e32 v72, 0xffff0000, v137
	v_add_f32_e32 v73, v195, v143
	v_mul_f32_e32 v72, v73, v72
	v_cvt_pk_bf16_f32 v253, v71, v72
	s_waitcnt vmcnt(25)
	v_lshlrev_b32_e32 v70, 16, v134
	v_add_f32_e32 v66, v195, v66
	v_mul_f32_e32 v66, v66, v70
	v_and_b32_e32 v70, 0xffff0000, v134
	v_add_f32_e32 v67, v195, v67
	v_mul_f32_e32 v67, v67, v70
	v_cvt_pk_bf16_f32 v254, v66, v67
	v_lshlrev_b32_e32 v66, 16, v135
	v_add_f32_e32 v67, v195, v68
	v_mul_f32_e32 v66, v67, v66
	v_and_b32_e32 v67, 0xffff0000, v135
	v_add_f32_e32 v68, v195, v69
	v_mul_f32_e32 v67, v68, v67
	v_cvt_pk_bf16_f32 v255, v66, v67
	ds_read_b128 v[66:69], v182 offset:1024
	ds_read_b128 v[70:73], v182 offset:1088
	s_waitcnt lgkmcnt(1)
	v_mfma_f32_16x16x32_bf16 v[66:69], v[66:69], v[62:65], 0
	ds_read_b128 v[74:77], v182 offset:1568
	ds_read_b128 v[78:81], v182 offset:1632
	ds_read_b128 v[134:137], v182 offset:2112
	ds_read_b128 v[138:141], v182 offset:2176
	ds_read_b128 v[142:145], v182 offset:2656
	ds_read_b128 v[196:199], v182 offset:2720
	s_waitcnt lgkmcnt(5)
	v_mfma_f32_16x16x32_bf16 v[74:77], v[74:77], v[62:65], 0
	s_nop 1
	v_permlane16_swap_b32_e32 v252, v254
	v_permlane16_swap_b32_e32 v253, v255
	global_store_dwordx4 v[238:239], v[252:255], off offset:64
	s_waitcnt lgkmcnt(3)
	v_mfma_f32_16x16x32_bf16 v[134:137], v[134:137], v[62:65], 0
	s_waitcnt lgkmcnt(1)
	v_mfma_f32_16x16x32_bf16 v[62:65], v[142:145], v[62:65], 0
	v_mfma_f32_16x16x32_bf16 v[66:69], v[70:73], v[58:61], v[66:69]
	v_mfma_f32_16x16x32_bf16 v[70:73], v[78:81], v[58:61], v[74:77]
	v_mfma_f32_16x16x32_bf16 v[74:77], v[138:141], v[58:61], v[134:137]
	s_waitcnt lgkmcnt(0)
	v_mfma_f32_16x16x32_bf16 v[58:61], v[196:199], v[58:61], v[62:65]
	s_waitcnt vmcnt(25)
	s_nop 1
	v_lshlrev_b32_e32 v62, 16, v132
	v_add_f32_e32 v63, v194, v66
	v_mul_f32_e32 v62, v63, v62
	v_and_b32_e32 v63, 0xffff0000, v132
	v_add_f32_e32 v64, v194, v67
	v_mul_f32_e32 v63, v64, v63
	v_cvt_pk_bf16_f32 v248, v62, v63
	v_lshlrev_b32_e32 v63, 16, v133
	v_add_f32_e32 v64, v194, v68
	v_mul_f32_e32 v63, v64, v63
	v_and_b32_e32 v64, 0xffff0000, v133
	v_add_f32_e32 v65, v194, v69
	v_mul_f32_e32 v64, v65, v64
	v_cvt_pk_bf16_f32 v249, v63, v64
	v_lshl_add_u64 v[238:239], v[120:121], 0, v[236:237]
	s_waitcnt vmcnt(24)
	v_lshlrev_b32_e32 v62, 16, v128
	v_add_f32_e32 v63, v194, v70
	v_mul_f32_e32 v62, v63, v62
	v_and_b32_e32 v63, 0xffff0000, v128
	v_add_f32_e32 v64, v194, v71
	v_mul_f32_e32 v63, v64, v63
	v_cvt_pk_bf16_f32 v250, v62, v63
	v_lshlrev_b32_e32 v63, 16, v129
	v_add_f32_e32 v64, v194, v72
	v_mul_f32_e32 v63, v64, v63
	v_and_b32_e32 v64, 0xffff0000, v129
	v_add_f32_e32 v65, v194, v73
	v_mul_f32_e32 v64, v65, v64
	v_cvt_pk_bf16_f32 v251, v63, v64
	s_nop 1
	v_permlane16_swap_b32_e32 v248, v250
	v_permlane16_swap_b32_e32 v249, v251
	global_store_dwordx4 v[238:239], v[248:251], off
	s_waitcnt vmcnt(24)
	v_lshlrev_b32_e32 v62, 16, v126
	v_add_f32_e32 v63, v194, v74
	v_mul_f32_e32 v62, v63, v62
	v_and_b32_e32 v63, 0xffff0000, v126
	v_add_f32_e32 v64, v194, v75
	v_mul_f32_e32 v63, v64, v63
	v_cvt_pk_bf16_f32 v252, v62, v63
	v_lshlrev_b32_e32 v63, 16, v127
	v_add_f32_e32 v64, v194, v76
	v_mul_f32_e32 v63, v64, v63
	v_and_b32_e32 v64, 0xffff0000, v127
	v_add_f32_e32 v65, v194, v77
	v_mul_f32_e32 v64, v65, v64
	v_cvt_pk_bf16_f32 v253, v63, v64
	s_waitcnt vmcnt(23)
; __device__ __forceinline__ unsigned cvt_pk_bf16(float lo, float hi) { unsigned r; asm volatile("v_cvt_pk_bf16_f32 %0, %1, %2" : "=v"(r) : "v"(lo), "v"(hi)); return r; }
; __device__ __forceinline__ float bf_lo(unsigned w) { return __uint_as_float(w << 16); }
; __device__ __forceinline__ float bf_hi(unsigned w) { return __uint_as_float(w & 0xffff0000u); }
; #define LAS __attribute__((address_space(3)))
; __device__ __forceinline__ void sgu_unit(LAS unsigned char* lds, bf16* U, const bf16* VS, const float* SGS, const float* lnw, const float* lnb, const v4u* WF, const float* bsl, int unit, int tid) {
;     ...
;             for (int ks = 0; ks <= (mt >> 1); ++ks) {
;                 const int sb = 32 * ks + 8 * fq; const bf16x8_t wf = __builtin_bit_cast(bf16x8_t, wfr[q++]);
; #pragma unroll
;                 for (int nt = 0; nt < 4; ++nt) { const bf16x8_t vf = *(const LAS bf16x8_t*)(vt + ((fr >> 3) + 8 * (fr & 7) + 2 * nt) * SGU_VP + sb * 2);
;                     acc[nt] = __builtin_amdgcn_mfma_f32_16x16x32_bf16(vf, wf, acc[nt], 0, 0, 0); }
;             }
;             const float bb = bbv[mt];
; #pragma unroll
;             for (int nt = 0; nt < 4; ++nt) { const v2u u2 = uu[mt][nt]; v2u w; w.x = cvt_pk_bf16(bf_lo(u2.x) * (acc[nt][0] + bb), bf_hi(u2.x) * (acc[nt][1] + bb)); w.y = cvt_pk_bf16(bf_lo(u2.y) * (acc[nt][2] + bb), bf_hi(u2.y) * (acc[nt][3] + bb));
;                 *(v2u*)(U + (size_t)(r0 + t) * 1024 + colbase + 16 * nt + 4 * fq) = w; }
	v_lshlrev_b32_e32 v62, 16, v124
	v_add_f32_e32 v58, v194, v58
	v_mul_f32_e32 v58, v58, v62
	v_and_b32_e32 v62, 0xffff0000, v124
	v_add_f32_e32 v59, v194, v59
	v_mul_f32_e32 v59, v59, v62
	v_cvt_pk_bf16_f32 v254, v58, v59
	v_lshlrev_b32_e32 v58, 16, v125
	v_add_f32_e32 v59, v194, v60
	v_mul_f32_e32 v58, v59, v58
	v_and_b32_e32 v59, 0xffff0000, v125
	v_add_f32_e32 v60, v194, v61
	v_mul_f32_e32 v59, v60, v59
	v_cvt_pk_bf16_f32 v255, v58, v59
	ds_read_b128 v[58:61], v182 offset:1024
	ds_read_b128 v[62:65], v182 offset:1088
	s_waitcnt lgkmcnt(1)
	v_mfma_f32_16x16x32_bf16 v[58:61], v[58:61], v[50:53], 0
	ds_read_b128 v[66:69], v182 offset:1568
	ds_read_b128 v[70:73], v182 offset:1152
	ds_read_b128 v[74:77], v182 offset:2112
	ds_read_b128 v[78:81], v182 offset:2176
	ds_read_b128 v[124:127], v182 offset:2656
	ds_read_b128 v[128:131], v182 offset:2240
	s_waitcnt lgkmcnt(5)
	v_mfma_f32_16x16x32_bf16 v[66:69], v[66:69], v[50:53], 0
	s_waitcnt lgkmcnt(3)
	v_mfma_f32_16x16x32_bf16 v[74:77], v[74:77], v[50:53], 0
	s_waitcnt lgkmcnt(1)
	v_mfma_f32_16x16x32_bf16 v[50:53], v[124:127], v[50:53], 0
	v_mfma_f32_16x16x32_bf16 v[58:61], v[62:65], v[54:57], v[58:61]
	ds_read_b128 v[62:65], v182 offset:1632
	ds_read_b128 v[124:127], v182 offset:1696
	s_waitcnt lgkmcnt(1)
	v_mfma_f32_16x16x32_bf16 v[62:65], v[62:65], v[54:57], v[66:69]
	v_mfma_f32_16x16x32_bf16 v[66:69], v[78:81], v[54:57], v[74:77]
	s_nop 2
	ds_read_b128 v[74:77], v182 offset:2720
	ds_read_b128 v[78:81], v182 offset:2784
	s_nop 1
	v_permlane16_swap_b32_e32 v252, v254
	v_permlane16_swap_b32_e32 v253, v255
	global_store_dwordx4 v[238:239], v[252:255], off offset:64
	s_waitcnt lgkmcnt(1)
	v_mfma_f32_16x16x32_bf16 v[50:53], v[74:77], v[54:57], v[50:53]
	v_mfma_f32_16x16x32_bf16 v[54:57], v[70:73], v[46:49], v[58:61]
	v_mfma_f32_16x16x32_bf16 v[58:61], v[124:127], v[46:49], v[62:65]
	v_mfma_f32_16x16x32_bf16 v[62:65], v[128:131], v[46:49], v[66:69]
	s_waitcnt lgkmcnt(0)
	v_mfma_f32_16x16x32_bf16 v[46:49], v[78:81], v[46:49], v[50:53]
	s_waitcnt vmcnt(23)
	s_nop 1
	v_lshlrev_b32_e32 v50, 16, v122
	v_add_f32_e32 v51, v193, v54
	v_mul_f32_e32 v50, v51, v50
	v_and_b32_e32 v51, 0xffff0000, v122
	v_add_f32_e32 v52, v193, v55
	v_mul_f32_e32 v51, v52, v51
	v_cvt_pk_bf16_f32 v248, v50, v51
	v_lshlrev_b32_e32 v51, 16, v123
	v_add_f32_e32 v52, v193, v56
	v_mul_f32_e32 v51, v52, v51
	v_and_b32_e32 v52, 0xffff0000, v123
	v_add_f32_e32 v53, v193, v57
	v_mul_f32_e32 v52, v53, v52
	v_cvt_pk_bf16_f32 v249, v51, v52
	v_lshl_add_u64 v[238:239], v[110:111], 0, v[236:237]
	s_waitcnt vmcnt(22)
	v_lshlrev_b32_e32 v50, 16, v118
	v_add_f32_e32 v51, v193, v58
	v_mul_f32_e32 v50, v51, v50
	v_and_b32_e32 v51, 0xffff0000, v118
	v_add_f32_e32 v52, v193, v59
	v_mul_f32_e32 v51, v52, v51
	v_cvt_pk_bf16_f32 v250, v50, v51
	v_lshlrev_b32_e32 v51, 16, v119
	v_add_f32_e32 v52, v193, v60
	v_mul_f32_e32 v51, v52, v51
	v_and_b32_e32 v52, 0xffff0000, v119
	v_add_f32_e32 v53, v193, v61
	v_mul_f32_e32 v52, v53, v52
	v_cvt_pk_bf16_f32 v251, v51, v52
	s_nop 1
	v_permlane16_swap_b32_e32 v248, v250
	v_permlane16_swap_b32_e32 v249, v251
	global_store_dwordx4 v[238:239], v[248:251], off
	s_waitcnt vmcnt(22)
	v_lshlrev_b32_e32 v50, 16, v116
	v_add_f32_e32 v51, v193, v62
	v_mul_f32_e32 v50, v51, v50
	v_and_b32_e32 v51, 0xffff0000, v116
	v_add_f32_e32 v52, v193, v63
	v_mul_f32_e32 v51, v52, v51
	v_cvt_pk_bf16_f32 v252, v50, v51
	v_lshlrev_b32_e32 v51, 16, v117
	v_add_f32_e32 v52, v193, v64
	v_mul_f32_e32 v51, v52, v51
	v_and_b32_e32 v52, 0xffff0000, v117
	v_add_f32_e32 v53, v193, v65
	v_mul_f32_e32 v52, v53, v52
	v_cvt_pk_bf16_f32 v253, v51, v52
	s_waitcnt vmcnt(21)
	v_lshlrev_b32_e32 v50, 16, v114
	v_add_f32_e32 v46, v193, v46
	v_mul_f32_e32 v46, v46, v50
	v_and_b32_e32 v50, 0xffff0000, v114
	v_add_f32_e32 v47, v193, v47
	v_mul_f32_e32 v47, v47, v50
	v_cvt_pk_bf16_f32 v254, v46, v47
	v_lshlrev_b32_e32 v46, 16, v115
	v_add_f32_e32 v47, v193, v48
	v_mul_f32_e32 v46, v47, v46
	v_and_b32_e32 v47, 0xffff0000, v115
	v_add_f32_e32 v48, v193, v49
	v_mul_f32_e32 v47, v48, v47
	v_cvt_pk_bf16_f32 v255, v46, v47
	ds_read_b128 v[46:49], v182 offset:1024
	ds_read_b128 v[50:53], v182 offset:1088
	s_waitcnt lgkmcnt(1)
	v_mfma_f32_16x16x32_bf16 v[46:49], v[46:49], v[42:45], 0
	ds_read_b128 v[54:57], v182 offset:1568
	ds_read_b128 v[58:61], v182 offset:1152
	ds_read_b128 v[62:65], v182 offset:2112
	ds_read_b128 v[66:69], v182 offset:2176
	ds_read_b128 v[70:73], v182 offset:2656
	ds_read_b128 v[74:77], v182 offset:2240
	s_waitcnt lgkmcnt(5)
	v_mfma_f32_16x16x32_bf16 v[54:57], v[54:57], v[42:45], 0
	s_waitcnt lgkmcnt(3)
	v_mfma_f32_16x16x32_bf16 v[62:65], v[62:65], v[42:45], 0
	s_waitcnt lgkmcnt(1)
	v_mfma_f32_16x16x32_bf16 v[42:45], v[70:73], v[42:45], 0
	v_mfma_f32_16x16x32_bf16 v[46:49], v[50:53], v[34:37], v[46:49]
	ds_read_b128 v[50:53], v182 offset:1632
	ds_read_b128 v[70:73], v182 offset:1696
	s_waitcnt lgkmcnt(1)
	v_mfma_f32_16x16x32_bf16 v[50:53], v[50:53], v[34:37], v[54:57]
	v_mfma_f32_16x16x32_bf16 v[54:57], v[66:69], v[34:37], v[62:65]
	s_nop 2
	ds_read_b128 v[62:65], v182 offset:2720
	ds_read_b128 v[66:69], v182 offset:2784
	s_nop 1
	v_permlane16_swap_b32_e32 v252, v254
	v_permlane16_swap_b32_e32 v253, v255
	global_store_dwordx4 v[238:239], v[252:255], off offset:64
	s_waitcnt lgkmcnt(1)
	v_mfma_f32_16x16x32_bf16 v[34:37], v[62:65], v[34:37], v[42:45]
	v_mfma_f32_16x16x32_bf16 v[42:45], v[58:61], v[38:41], v[46:49]
	v_mfma_f32_16x16x32_bf16 v[46:49], v[70:73], v[38:41], v[50:53]
	v_mfma_f32_16x16x32_bf16 v[50:53], v[74:77], v[38:41], v[54:57]
	s_waitcnt lgkmcnt(0)
	v_mfma_f32_16x16x32_bf16 v[34:37], v[66:69], v[38:41], v[34:37]
	s_waitcnt vmcnt(21)
; __device__ __forceinline__ unsigned cvt_pk_bf16(float lo, float hi) { unsigned r; asm volatile("v_cvt_pk_bf16_f32 %0, %1, %2" : "=v"(r) : "v"(lo), "v"(hi)); return r; }
; __device__ __forceinline__ float bf_lo(unsigned w) { return __uint_as_float(w << 16); }
; __device__ __forceinline__ float bf_hi(unsigned w) { return __uint_as_float(w & 0xffff0000u); }
; #define LAS __attribute__((address_space(3)))
; __device__ __forceinline__ void sgu_unit(LAS unsigned char* lds, bf16* U, const bf16* VS, const float* SGS, const float* lnw, const float* lnb, const v4u* WF, const float* bsl, int unit, int tid) {
;     ...
;             for (int ks = 0; ks <= (mt >> 1); ++ks) {
;                 const int sb = 32 * ks + 8 * fq; const bf16x8_t wf = __builtin_bit_cast(bf16x8_t, wfr[q++]);
; #pragma unroll
;                 for (int nt = 0; nt < 4; ++nt) { const bf16x8_t vf = *(const LAS bf16x8_t*)(vt + ((fr >> 3) + 8 * (fr & 7) + 2 * nt) * SGU_VP + sb * 2);
;                     acc[nt] = __builtin_amdgcn_mfma_f32_16x16x32_bf16(vf, wf, acc[nt], 0, 0, 0); }
;             }
;             const float bb = bbv[mt];
; #pragma unroll
;             for (int nt = 0; nt < 4; ++nt) { const v2u u2 = uu[mt][nt]; v2u w; w.x = cvt_pk_bf16(bf_lo(u2.x) * (acc[nt][0] + bb), bf_hi(u2.x) * (acc[nt][1] + bb)); w.y = cvt_pk_bf16(bf_lo(u2.y) * (acc[nt][2] + bb), bf_hi(u2.y) * (acc[nt][3] + bb));
;                 *(v2u*)(U + (size_t)(r0 + t) * 1024 + colbase + 16 * nt + 4 * fq) = w; }
	v_lshlrev_b32_e32 v38, 16, v112
	s_nop 1
	v_add_f32_e32 v39, v192, v42
	v_mul_f32_e32 v38, v39, v38
	v_and_b32_e32 v39, 0xffff0000, v112
	v_add_f32_e32 v40, v192, v43
	v_mul_f32_e32 v39, v40, v39
	v_cvt_pk_bf16_f32 v248, v38, v39
	v_lshlrev_b32_e32 v39, 16, v113
	v_add_f32_e32 v40, v192, v44
	v_mul_f32_e32 v39, v40, v39
	v_and_b32_e32 v40, 0xffff0000, v113
	v_add_f32_e32 v41, v192, v45
	v_mul_f32_e32 v40, v41, v40
	v_cvt_pk_bf16_f32 v249, v39, v40
	v_lshl_add_u64 v[238:239], v[100:101], 0, v[236:237]
	s_waitcnt vmcnt(20)
	v_lshlrev_b32_e32 v38, 16, v108
	v_add_f32_e32 v39, v192, v46
	v_mul_f32_e32 v38, v39, v38
	v_and_b32_e32 v39, 0xffff0000, v108
	v_add_f32_e32 v40, v192, v47
	v_mul_f32_e32 v39, v40, v39
	v_cvt_pk_bf16_f32 v250, v38, v39
	v_lshlrev_b32_e32 v39, 16, v109
	v_add_f32_e32 v40, v192, v48
	v_mul_f32_e32 v39, v40, v39
	v_and_b32_e32 v40, 0xffff0000, v109
	v_add_f32_e32 v41, v192, v49
	v_mul_f32_e32 v40, v41, v40
	v_cvt_pk_bf16_f32 v251, v39, v40
	s_nop 1
	v_permlane16_swap_b32_e32 v248, v250
	v_permlane16_swap_b32_e32 v249, v251
	global_store_dwordx4 v[238:239], v[248:251], off
	s_waitcnt vmcnt(20)
	v_lshlrev_b32_e32 v38, 16, v106
	v_add_f32_e32 v39, v192, v50
	v_mul_f32_e32 v38, v39, v38
	v_and_b32_e32 v39, 0xffff0000, v106
	v_add_f32_e32 v40, v192, v51
	v_mul_f32_e32 v39, v40, v39
	v_cvt_pk_bf16_f32 v252, v38, v39
	v_lshlrev_b32_e32 v39, 16, v107
	v_add_f32_e32 v40, v192, v52
	v_mul_f32_e32 v39, v40, v39
	v_and_b32_e32 v40, 0xffff0000, v107
	v_add_f32_e32 v41, v192, v53
	v_mul_f32_e32 v40, v41, v40
	v_cvt_pk_bf16_f32 v253, v39, v40
	s_waitcnt vmcnt(19)
	v_lshlrev_b32_e32 v38, 16, v104
	v_add_f32_e32 v34, v192, v34
	v_mul_f32_e32 v34, v34, v38
	v_and_b32_e32 v38, 0xffff0000, v104
	v_add_f32_e32 v35, v192, v35
	v_mul_f32_e32 v35, v35, v38
	v_cvt_pk_bf16_f32 v254, v34, v35
	v_lshlrev_b32_e32 v34, 16, v105
	v_add_f32_e32 v35, v192, v36
	v_mul_f32_e32 v34, v35, v34
	v_and_b32_e32 v35, 0xffff0000, v105
	v_add_f32_e32 v36, v192, v37
	v_mul_f32_e32 v35, v36, v35
	v_cvt_pk_bf16_f32 v255, v34, v35
	ds_read_b128 v[34:37], v182 offset:1024
	ds_read_b128 v[38:41], v182 offset:1088
	ds_read_b128 v[42:45], v182 offset:1568
	ds_read_b128 v[46:49], v182 offset:1632
	ds_read_b128 v[50:53], v182 offset:2112
	ds_read_b128 v[54:57], v182 offset:2176
	ds_read_b128 v[58:61], v182 offset:2656
	ds_read_b128 v[62:65], v182 offset:2720
	s_waitcnt lgkmcnt(7)
	v_mfma_f32_16x16x32_bf16 v[34:37], v[34:37], v[30:33], 0
	s_waitcnt lgkmcnt(5)
	v_mfma_f32_16x16x32_bf16 v[42:45], v[42:45], v[30:33], 0
	s_waitcnt lgkmcnt(3)
	v_mfma_f32_16x16x32_bf16 v[50:53], v[50:53], v[30:33], 0
	s_waitcnt lgkmcnt(1)
	v_mfma_f32_16x16x32_bf16 v[30:33], v[58:61], v[30:33], 0
	v_mfma_f32_16x16x32_bf16 v[34:37], v[38:41], v[26:29], v[34:37]
	v_mfma_f32_16x16x32_bf16 v[38:41], v[46:49], v[26:29], v[42:45]
	v_mfma_f32_16x16x32_bf16 v[42:45], v[54:57], v[26:29], v[50:53]
	s_waitcnt lgkmcnt(0)
	v_mfma_f32_16x16x32_bf16 v[26:29], v[62:65], v[26:29], v[30:33]
	s_nop 2
	ds_read_b128 v[30:33], v182 offset:1152
	ds_read_b128 v[46:49], v182 offset:1216
	s_waitcnt lgkmcnt(1)
	v_mfma_f32_16x16x32_bf16 v[30:33], v[30:33], v[22:25], v[34:37]
	s_nop 2
	ds_read_b128 v[34:37], v182 offset:1696
	ds_read_b128 v[50:53], v182 offset:1760
	s_waitcnt lgkmcnt(1)
	v_mfma_f32_16x16x32_bf16 v[34:37], v[34:37], v[22:25], v[38:41]
	s_nop 2
	ds_read_b128 v[38:41], v182 offset:2240
	ds_read_b128 v[54:57], v182 offset:2304
	s_waitcnt lgkmcnt(1)
	v_mfma_f32_16x16x32_bf16 v[38:41], v[38:41], v[22:25], v[42:45]
	s_nop 2
	ds_read_b128 v[42:45], v182 offset:2784
	ds_read_b128 v[58:61], v182 offset:2848
	s_nop 1
	v_permlane16_swap_b32_e32 v252, v254
	v_permlane16_swap_b32_e32 v253, v255
	global_store_dwordx4 v[238:239], v[252:255], off offset:64
	s_waitcnt lgkmcnt(1)
	v_mfma_f32_16x16x32_bf16 v[22:25], v[42:45], v[22:25], v[26:29]
	v_mfma_f32_16x16x32_bf16 v[26:29], v[46:49], v[18:21], v[30:33]
	v_mfma_f32_16x16x32_bf16 v[30:33], v[50:53], v[18:21], v[34:37]
	v_mfma_f32_16x16x32_bf16 v[34:37], v[54:57], v[18:21], v[38:41]
	s_waitcnt lgkmcnt(0)
	v_mfma_f32_16x16x32_bf16 v[18:21], v[58:61], v[18:21], v[22:25]
	s_waitcnt vmcnt(19)
	s_nop 1
	v_lshlrev_b32_e32 v22, 16, v102
	v_add_f32_e32 v23, v191, v26
	v_mul_f32_e32 v22, v23, v22
	v_and_b32_e32 v23, 0xffff0000, v102
	v_add_f32_e32 v24, v191, v27
	v_mul_f32_e32 v23, v24, v23
	v_cvt_pk_bf16_f32 v248, v22, v23
	v_lshlrev_b32_e32 v23, 16, v103
	v_add_f32_e32 v24, v191, v28
	v_mul_f32_e32 v23, v24, v23
	v_and_b32_e32 v24, 0xffff0000, v103
	v_add_f32_e32 v25, v191, v29
	v_mul_f32_e32 v24, v25, v24
	v_cvt_pk_bf16_f32 v249, v23, v24
	v_lshl_add_u64 v[238:239], v[90:91], 0, v[236:237]
	s_waitcnt vmcnt(18)
	v_lshlrev_b32_e32 v22, 16, v98
	v_add_f32_e32 v23, v191, v30
	v_mul_f32_e32 v22, v23, v22
	v_and_b32_e32 v23, 0xffff0000, v98
	v_add_f32_e32 v24, v191, v31
	v_mul_f32_e32 v23, v24, v23
	v_cvt_pk_bf16_f32 v250, v22, v23
	v_lshlrev_b32_e32 v23, 16, v99
	v_add_f32_e32 v24, v191, v32
	v_mul_f32_e32 v23, v24, v23
	v_and_b32_e32 v24, 0xffff0000, v99
	v_add_f32_e32 v25, v191, v33
	v_mul_f32_e32 v24, v25, v24
	v_cvt_pk_bf16_f32 v251, v23, v24
	s_nop 1
	v_permlane16_swap_b32_e32 v248, v250
	v_permlane16_swap_b32_e32 v249, v251
	global_store_dwordx4 v[238:239], v[248:251], off
	s_waitcnt vmcnt(18)
; __device__ __forceinline__ unsigned cvt_pk_bf16(float lo, float hi) { unsigned r; asm volatile("v_cvt_pk_bf16_f32 %0, %1, %2" : "=v"(r) : "v"(lo), "v"(hi)); return r; }
; __device__ __forceinline__ float bf_lo(unsigned w) { return __uint_as_float(w << 16); }
; __device__ __forceinline__ float bf_hi(unsigned w) { return __uint_as_float(w & 0xffff0000u); }
; #define LAS __attribute__((address_space(3)))
; __device__ __forceinline__ void sgu_unit(LAS unsigned char* lds, bf16* U, const bf16* VS, const float* SGS, const float* lnw, const float* lnb, const v4u* WF, const float* bsl, int unit, int tid) {
;     ...
;         for (int mt = 0; mt < 8; ++mt) {
;             const int t = 16 * mt + fr;
;             f32x4 acc[4];
; #pragma unroll
;             for (int nt = 0; nt < 4; ++nt) acc[nt] = (f32x4){0.f, 0.f, 0.f, 0.f};
; #pragma unroll
;             for (int ks = 0; ks <= (mt >> 1); ++ks) {
;                 const int sb = 32 * ks + 8 * fq; const bf16x8_t wf = __builtin_bit_cast(bf16x8_t, wfr[q++]);
; #pragma unroll
;                 for (int nt = 0; nt < 4; ++nt) { const bf16x8_t vf = *(const LAS bf16x8_t*)(vt + ((fr >> 3) + 8 * (fr & 7) + 2 * nt) * SGU_VP + sb * 2);
;                     acc[nt] = __builtin_amdgcn_mfma_f32_16x16x32_bf16(vf, wf, acc[nt], 0, 0, 0); }
;             }
;             const float bb = bbv[mt];
; #pragma unroll
;             for (int nt = 0; nt < 4; ++nt) { const v2u u2 = uu[mt][nt]; v2u w; w.x = cvt_pk_bf16(bf_lo(u2.x) * (acc[nt][0] + bb), bf_hi(u2.x) * (acc[nt][1] + bb)); w.y = cvt_pk_bf16(bf_lo(u2.y) * (acc[nt][2] + bb), bf_hi(u2.y) * (acc[nt][3] + bb));
;                 *(v2u*)(U + (size_t)(r0 + t) * 1024 + colbase + 16 * nt + 4 * fq) = w; }
;         }
;     }
;     __syncthreads();
	v_lshlrev_b32_e32 v22, 16, v96
	v_add_f32_e32 v23, v191, v34
	v_mul_f32_e32 v22, v23, v22
	v_and_b32_e32 v23, 0xffff0000, v96
	v_add_f32_e32 v24, v191, v35
	v_mul_f32_e32 v23, v24, v23
	v_cvt_pk_bf16_f32 v252, v22, v23
	v_lshlrev_b32_e32 v23, 16, v97
	v_add_f32_e32 v24, v191, v36
	v_mul_f32_e32 v23, v24, v23
	v_and_b32_e32 v24, 0xffff0000, v97
	v_add_f32_e32 v25, v191, v37
	v_mul_f32_e32 v24, v25, v24
	v_cvt_pk_bf16_f32 v253, v23, v24
	s_waitcnt vmcnt(17)
	v_lshlrev_b32_e32 v22, 16, v94
	v_add_f32_e32 v18, v191, v18
	v_mul_f32_e32 v18, v18, v22
	v_and_b32_e32 v22, 0xffff0000, v94
	v_add_f32_e32 v19, v191, v19
	v_mul_f32_e32 v19, v19, v22
	v_cvt_pk_bf16_f32 v254, v18, v19
	v_lshlrev_b32_e32 v18, 16, v95
	v_add_f32_e32 v19, v191, v20
	v_mul_f32_e32 v18, v19, v18
	v_and_b32_e32 v19, 0xffff0000, v95
	v_add_f32_e32 v20, v191, v21
	v_mul_f32_e32 v19, v20, v19
	v_cvt_pk_bf16_f32 v255, v18, v19
	ds_read_b128 v[18:21], v182 offset:1024
	ds_read_b128 v[22:25], v182 offset:1088
	ds_read_b128 v[26:29], v182 offset:1568
	ds_read_b128 v[30:33], v182 offset:1632
	ds_read_b128 v[34:37], v182 offset:2112
	ds_read_b128 v[38:41], v182 offset:2176
	ds_read_b128 v[42:45], v182 offset:2656
	ds_read_b128 v[46:49], v182 offset:2720
	s_waitcnt lgkmcnt(7)
	v_mfma_f32_16x16x32_bf16 v[18:21], v[18:21], v[14:17], 0
	s_waitcnt lgkmcnt(5)
	v_mfma_f32_16x16x32_bf16 v[26:29], v[26:29], v[14:17], 0
	s_waitcnt lgkmcnt(3)
	v_mfma_f32_16x16x32_bf16 v[34:37], v[34:37], v[14:17], 0
	s_waitcnt lgkmcnt(1)
	v_mfma_f32_16x16x32_bf16 v[14:17], v[42:45], v[14:17], 0
	v_mfma_f32_16x16x32_bf16 v[18:21], v[22:25], v[10:13], v[18:21]
	v_mfma_f32_16x16x32_bf16 v[22:25], v[30:33], v[10:13], v[26:29]
	v_mfma_f32_16x16x32_bf16 v[26:29], v[38:41], v[10:13], v[34:37]
	s_waitcnt lgkmcnt(0)
	v_mfma_f32_16x16x32_bf16 v[10:13], v[46:49], v[10:13], v[14:17]
	s_nop 2
	ds_read_b128 v[14:17], v182 offset:1152
	ds_read_b128 v[30:33], v182 offset:1216
	s_waitcnt lgkmcnt(1)
	v_mfma_f32_16x16x32_bf16 v[14:17], v[14:17], v[6:9], v[18:21]
	s_nop 2
	ds_read_b128 v[18:21], v182 offset:1696
	ds_read_b128 v[34:37], v182 offset:1760
	s_waitcnt lgkmcnt(1)
	v_mfma_f32_16x16x32_bf16 v[18:21], v[18:21], v[6:9], v[22:25]
	s_nop 2
	ds_read_b128 v[22:25], v182 offset:2240
	ds_read_b128 v[38:41], v182 offset:2304
	s_waitcnt lgkmcnt(1)
	v_mfma_f32_16x16x32_bf16 v[22:25], v[22:25], v[6:9], v[26:29]
	s_nop 2
	ds_read_b128 v[26:29], v182 offset:2784
	ds_read_b128 v[42:45], v182 offset:2848
	s_nop 1
	v_permlane16_swap_b32_e32 v252, v254
	v_permlane16_swap_b32_e32 v253, v255
	global_store_dwordx4 v[238:239], v[252:255], off offset:64
	s_waitcnt lgkmcnt(1)
	v_mfma_f32_16x16x32_bf16 v[6:9], v[26:29], v[6:9], v[10:13]
	v_mfma_f32_16x16x32_bf16 v[10:13], v[30:33], v[2:5], v[14:17]
	v_mfma_f32_16x16x32_bf16 v[14:17], v[34:37], v[2:5], v[18:21]
	v_mfma_f32_16x16x32_bf16 v[18:21], v[38:41], v[2:5], v[22:25]
	s_waitcnt lgkmcnt(0)
	v_mfma_f32_16x16x32_bf16 v[2:5], v[42:45], v[2:5], v[6:9]
	s_waitcnt vmcnt(17)
	s_nop 1
	v_lshlrev_b32_e32 v6, 16, v92
	v_add_f32_e32 v7, v157, v10
	v_mul_f32_e32 v6, v7, v6
	v_and_b32_e32 v7, 0xffff0000, v92
	v_add_f32_e32 v8, v157, v11
	v_mul_f32_e32 v7, v8, v7
	v_cvt_pk_bf16_f32 v248, v6, v7
	v_lshlrev_b32_e32 v7, 16, v93
	v_add_f32_e32 v8, v157, v12
	v_mul_f32_e32 v7, v8, v7
	v_and_b32_e32 v8, 0xffff0000, v93
	v_add_f32_e32 v9, v157, v13
	v_mul_f32_e32 v8, v9, v8
	v_cvt_pk_bf16_f32 v249, v7, v8
	v_lshl_add_u64 v[238:239], v[82:83], 0, v[236:237]
	s_waitcnt vmcnt(16)
	v_lshlrev_b32_e32 v6, 16, v88
	v_add_f32_e32 v7, v157, v14
	v_mul_f32_e32 v6, v7, v6
	v_and_b32_e32 v7, 0xffff0000, v88
	v_add_f32_e32 v8, v157, v15
	v_mul_f32_e32 v7, v8, v7
	v_cvt_pk_bf16_f32 v250, v6, v7
	v_lshlrev_b32_e32 v7, 16, v89
	v_add_f32_e32 v8, v157, v16
	v_mul_f32_e32 v7, v8, v7
	v_and_b32_e32 v8, 0xffff0000, v89
	v_add_f32_e32 v9, v157, v17
	v_mul_f32_e32 v8, v9, v8
	v_cvt_pk_bf16_f32 v251, v7, v8
	s_nop 1
	v_permlane16_swap_b32_e32 v248, v250
	v_permlane16_swap_b32_e32 v249, v251
	global_store_dwordx4 v[238:239], v[248:251], off
	s_waitcnt vmcnt(16)
	v_lshlrev_b32_e32 v6, 16, v86
	v_add_f32_e32 v7, v157, v18
	v_mul_f32_e32 v6, v7, v6
	v_and_b32_e32 v7, 0xffff0000, v86
	v_add_f32_e32 v8, v157, v19
	v_mul_f32_e32 v7, v8, v7
	v_cvt_pk_bf16_f32 v252, v6, v7
	v_lshlrev_b32_e32 v7, 16, v87
	v_add_f32_e32 v8, v157, v20
	v_mul_f32_e32 v7, v8, v7
	v_and_b32_e32 v8, 0xffff0000, v87
	v_add_f32_e32 v9, v157, v21
	v_mul_f32_e32 v8, v9, v8
	v_cvt_pk_bf16_f32 v253, v7, v8
	s_waitcnt vmcnt(15)
	v_lshlrev_b32_e32 v6, 16, v84
	v_add_f32_e32 v2, v157, v2
	v_mul_f32_e32 v2, v2, v6
	v_and_b32_e32 v6, 0xffff0000, v84
	v_add_f32_e32 v3, v157, v3
	v_mul_f32_e32 v3, v3, v6
	v_cvt_pk_bf16_f32 v254, v2, v3
	v_lshlrev_b32_e32 v3, 16, v85
	v_add_f32_e32 v4, v157, v4
	v_mul_f32_e32 v3, v4, v3
	v_and_b32_e32 v4, 0xffff0000, v85
	v_add_f32_e32 v5, v157, v5
	v_mul_f32_e32 v4, v5, v4
	v_cvt_pk_bf16_f32 v255, v3, v4
	s_nop 1
	v_permlane16_swap_b32_e32 v252, v254
	v_permlane16_swap_b32_e32 v253, v255
	global_store_dwordx4 v[238:239], v[252:255], off offset:64
	s_barrier
